# K-loops: second-level DMA addresses via SALU base add + saddr form (40 more VALU address adds removed from load segments)
# speedup vs baseline: 1.0207x; 1.0060x over previous
.LBB0_124:
	s_ashr_i32 s79, s78, 31
	s_lshl_b64 s[10:11], s[78:79], 19
	s_add_u32 s80, s54, s10
	v_cmp_lt_i64_e32 vcc, s[72:73], v[178:179]
	s_addc_u32 s81, s55, s11
	s_and_b64 s[10:11], vcc, exec
	s_cselect_b32 s1, s81, s87
	s_cselect_b32 s10, s80, s86
	s_ashr_i32 s77, s76, 31
	s_lshl_b64 s[36:37], s[76:77], 19
	s_add_u32 s72, s66, s36
	s_addc_u32 s73, s59, s37
	s_and_b64 s[36:37], vcc, exec
	s_cselect_b32 s11, s73, s83
	s_cselect_b32 s25, s72, s82
	s_add_u32 s86, s86, 0x40080
	s_addc_u32 s87, s87, 0
	s_add_u32 s33, s82, 0x100
	s_addc_u32 s36, s83, 0
	s_mov_b32 s37, -2
	s_add_u32 s27, s86, 0xfffc0080
	s_addc_u32 s56, s87, -1
	s_add_i32 s57, 0, 0x10000
	v_add_u32_e32 v76, s57, v217
	ds_read_b128 v[64:67], v76
	ds_read_b128 v[68:71], v76 offset:1024
	ds_read_b128 v[72:75], v76 offset:2048
	ds_read_b128 v[76:79], v76 offset:3072
	s_cmp_eq_u32 s37, 12
	s_cselect_b32 vcc_hi, s1, s56
	s_cselect_b32 vcc_lo, s10, s27
	s_cselect_b32 s83, s11, s36
	s_cselect_b32 s82, s25, s33
	s_add_i32 m0, s75, 0xc000
	ds_read_b128 v[80:83], v220
	ds_read_b128 v[84:87], v220 offset:1024
	ds_read_b128 v[88:91], v220 offset:2048
	ds_read_b128 v[92:95], v220 offset:3072
	ds_read_b128 v[188:191], v220 offset:4096
	ds_read_b128 v[192:195], v220 offset:5120
	ds_read_b128 v[196:199], v220 offset:6144
	ds_read_b128 v[200:203], v220 offset:7168
	global_load_lds_dwordx4 v164, s[86:87]
	s_add_i32 m0, s75, 0xe000
	s_nop 0
	global_load_lds_dwordx4 v166, s[86:87]
	s_waitcnt lgkmcnt(8)
	s_barrier
	s_waitcnt lgkmcnt(0)
	v_mfma_f32_16x16x32_bf16 v[146:149], v[64:67], v[80:83], 0
	v_mfma_f32_16x16x32_bf16 v[116:119], v[72:75], v[80:83], 0
	v_mfma_f32_16x16x32_bf16 v[158:161], v[64:67], v[88:91], 0
	v_mfma_f32_16x16x32_bf16 v[124:127], v[72:75], v[88:91], 0
	v_mfma_f32_16x16x32_bf16 v[154:157], v[64:67], v[188:191], 0
	v_mfma_f32_16x16x32_bf16 v[112:115], v[72:75], v[188:191], 0
	v_mfma_f32_16x16x32_bf16 v[150:153], v[64:67], v[196:199], 0
	v_mfma_f32_16x16x32_bf16 v[120:123], v[72:75], v[196:199], 0
	v_mfma_f32_16x16x32_bf16 v[146:149], v[68:71], v[84:87], v[146:149]
	v_mfma_f32_16x16x32_bf16 v[116:119], v[76:79], v[84:87], v[116:119]
	v_mfma_f32_16x16x32_bf16 v[158:161], v[68:71], v[92:95], v[158:161]
	v_mfma_f32_16x16x32_bf16 v[124:127], v[76:79], v[92:95], v[124:127]
	v_mfma_f32_16x16x32_bf16 v[154:157], v[68:71], v[192:195], v[154:157]
	v_mfma_f32_16x16x32_bf16 v[112:115], v[76:79], v[192:195], v[112:115]
	v_mfma_f32_16x16x32_bf16 v[150:153], v[68:71], v[200:203], v[150:153]
	v_mfma_f32_16x16x32_bf16 v[120:123], v[76:79], v[200:203], v[120:123]
	s_barrier
	s_add_i32 s27, 0, 0x14000
	v_add_u32_e32 v168, s27, v217
	s_add_i32 s56, s57, s74
	ds_read_b128 v[204:207], v168
	ds_read_b128 v[222:225], v168 offset:1024
	ds_read_b128 v[228:231], v168 offset:2048
	ds_read_b128 v[232:235], v168 offset:3072
	s_mov_b32 m0, s56
	global_load_lds_dwordx4 v144, s[82:83]
	s_add_i32 m0, s56, 0x2000
	s_nop 0
	global_load_lds_dwordx4 v162, s[82:83]
	s_barrier
	s_waitcnt lgkmcnt(0)
	v_mfma_f32_16x16x32_bf16 v[140:143], v[204:207], v[80:83], 0
	v_mfma_f32_16x16x32_bf16 v[80:83], v[228:231], v[80:83], 0
	v_mfma_f32_16x16x32_bf16 v[140:143], v[222:225], v[84:87], v[140:143]
	v_mfma_f32_16x16x32_bf16 v[80:83], v[232:235], v[84:87], v[80:83]
	v_mfma_f32_16x16x32_bf16 v[84:87], v[204:207], v[88:91], 0
	v_mfma_f32_16x16x32_bf16 v[88:91], v[228:231], v[88:91], 0
	v_mfma_f32_16x16x32_bf16 v[100:103], v[228:231], v[188:191], 0
	v_mfma_f32_16x16x32_bf16 v[104:107], v[204:207], v[196:199], 0
	v_mfma_f32_16x16x32_bf16 v[96:99], v[228:231], v[196:199], 0
	v_mfma_f32_16x16x32_bf16 v[84:87], v[222:225], v[92:95], v[84:87]
	v_mfma_f32_16x16x32_bf16 v[88:91], v[232:235], v[92:95], v[88:91]
	v_mfma_f32_16x16x32_bf16 v[92:95], v[204:207], v[188:191], 0
	v_mfma_f32_16x16x32_bf16 v[100:103], v[232:235], v[192:195], v[100:103]
	v_mfma_f32_16x16x32_bf16 v[128:131], v[222:225], v[200:203], v[104:107]
	v_mfma_f32_16x16x32_bf16 v[96:99], v[232:235], v[200:203], v[96:99]
	v_mfma_f32_16x16x32_bf16 v[92:95], v[222:225], v[192:195], v[92:95]
	s_barrier
	s_mov_b32 m0, s75
	ds_read_b128 v[104:107], v220 offset:16384
	ds_read_b128 v[108:111], v220 offset:17408
	ds_read_b128 v[132:135], v220 offset:18432
	ds_read_b128 v[136:139], v220 offset:19456
	ds_read_b128 v[188:191], v220 offset:20480
	ds_read_b128 v[192:195], v220 offset:21504
	ds_read_b128 v[196:199], v220 offset:22528
	ds_read_b128 v[200:203], v220 offset:23552
	global_load_lds_dwordx4 v144, vcc
	s_mov_b32 m0, s85
	s_nop 0
	global_load_lds_dwordx4 v162, vcc
	s_barrier
	s_waitcnt lgkmcnt(0)
	v_mfma_f32_16x16x32_bf16 v[48:51], v[64:67], v[104:107], 0
	v_mfma_f32_16x16x32_bf16 v[20:23], v[72:75], v[104:107], 0
	v_mfma_f32_16x16x32_bf16 v[60:63], v[64:67], v[132:135], 0
	v_mfma_f32_16x16x32_bf16 v[28:31], v[72:75], v[132:135], 0
	v_mfma_f32_16x16x32_bf16 v[56:59], v[64:67], v[188:191], 0
	v_mfma_f32_16x16x32_bf16 v[16:19], v[72:75], v[188:191], 0
	v_mfma_f32_16x16x32_bf16 v[52:55], v[64:67], v[196:199], 0
	v_mfma_f32_16x16x32_bf16 v[24:27], v[72:75], v[196:199], 0
	v_mfma_f32_16x16x32_bf16 v[48:51], v[68:71], v[108:111], v[48:51]
	v_mfma_f32_16x16x32_bf16 v[20:23], v[76:79], v[108:111], v[20:23]
	v_mfma_f32_16x16x32_bf16 v[60:63], v[68:71], v[136:139], v[60:63]
	v_mfma_f32_16x16x32_bf16 v[28:31], v[76:79], v[136:139], v[28:31]
	v_mfma_f32_16x16x32_bf16 v[56:59], v[68:71], v[192:195], v[56:59]
	v_mfma_f32_16x16x32_bf16 v[16:19], v[76:79], v[192:195], v[16:19]
	v_mfma_f32_16x16x32_bf16 v[52:55], v[68:71], v[200:203], v[52:55]
	v_mfma_f32_16x16x32_bf16 v[24:27], v[76:79], v[200:203], v[24:27]
	s_barrier
	s_add_u32 s56, s82, 0x40000
	s_addc_u32 s57, s83, 0
	s_add_i32 s27, s27, s74
	s_mov_b32 m0, s27
	s_nop 0
	global_load_lds_dwordx4 v144, s[56:57]
	s_add_i32 m0, s27, 0x2000
	s_nop 0
	global_load_lds_dwordx4 v162, s[56:57]
	s_waitcnt vmcnt(6)
	s_barrier
	v_mfma_f32_16x16x32_bf16 v[44:47], v[204:207], v[104:107], 0
	v_mfma_f32_16x16x32_bf16 v[12:15], v[228:231], v[104:107], 0
	v_mfma_f32_16x16x32_bf16 v[40:43], v[204:207], v[132:135], 0
	v_mfma_f32_16x16x32_bf16 v[8:11], v[228:231], v[132:135], 0
	v_mfma_f32_16x16x32_bf16 v[36:39], v[204:207], v[188:191], 0
	v_mfma_f32_16x16x32_bf16 v[4:7], v[228:231], v[188:191], 0
	v_mfma_f32_16x16x32_bf16 v[32:35], v[204:207], v[196:199], 0
	v_mfma_f32_16x16x32_bf16 v[0:3], v[228:231], v[196:199], 0
	v_mfma_f32_16x16x32_bf16 v[44:47], v[222:225], v[108:111], v[44:47]
	v_mfma_f32_16x16x32_bf16 v[12:15], v[232:235], v[108:111], v[12:15]
	v_mfma_f32_16x16x32_bf16 v[40:43], v[222:225], v[136:139], v[40:43]
	v_mfma_f32_16x16x32_bf16 v[8:11], v[232:235], v[136:139], v[8:11]
	v_mfma_f32_16x16x32_bf16 v[36:39], v[222:225], v[192:195], v[36:39]
	v_mfma_f32_16x16x32_bf16 v[4:7], v[232:235], v[192:195], v[4:7]
	v_mfma_f32_16x16x32_bf16 v[32:35], v[222:225], v[200:203], v[32:35]
	v_mfma_f32_16x16x32_bf16 v[0:3], v[232:235], v[200:203], v[0:3]
	s_barrier
	s_add_i32 s27, 0, 0x18000
	v_add_u32_e32 v76, s27, v217
	ds_read_b128 v[64:67], v76
	ds_read_b128 v[68:71], v76 offset:1024
	ds_read_b128 v[72:75], v76 offset:2048
	ds_read_b128 v[76:79], v76 offset:3072
	s_add_u32 s56, vcc_lo, 0x40000
	s_addc_u32 s57, vcc_hi, 0
	s_mov_b32 m0, s98
	ds_read_b128 v[104:107], v220 offset:32768
	ds_read_b128 v[108:111], v220 offset:33792
	ds_read_b128 v[132:135], v220 offset:34816
	ds_read_b128 v[188:191], v220 offset:35840
	ds_read_b128 v[192:195], v220 offset:36864
	ds_read_b128 v[196:199], v220 offset:37888
	ds_read_b128 v[200:203], v220 offset:38912
	ds_read_b128 v[204:207], v220 offset:39936
	global_load_lds_dwordx4 v144, s[56:57]
	s_mov_b32 m0, s29
	s_nop 0
	global_load_lds_dwordx4 v162, s[56:57]
	s_waitcnt lgkmcnt(8)
	s_barrier
	s_waitcnt lgkmcnt(0)
	v_mfma_f32_16x16x32_bf16 v[136:139], v[64:67], v[104:107], v[146:149]
	v_mfma_f32_16x16x32_bf16 v[146:149], v[68:71], v[108:111], v[136:139]
	v_mfma_f32_16x16x32_bf16 v[136:139], v[64:67], v[132:135], v[158:161]
	v_mfma_f32_16x16x32_bf16 v[158:161], v[68:71], v[188:191], v[136:139]
	v_mfma_f32_16x16x32_bf16 v[136:139], v[64:67], v[192:195], v[154:157]
	v_mfma_f32_16x16x32_bf16 v[116:119], v[72:75], v[104:107], v[116:119]
	v_mfma_f32_16x16x32_bf16 v[124:127], v[72:75], v[132:135], v[124:127]
	v_mfma_f32_16x16x32_bf16 v[154:157], v[68:71], v[196:199], v[136:139]
	v_mfma_f32_16x16x32_bf16 v[112:115], v[72:75], v[192:195], v[112:115]
	v_mfma_f32_16x16x32_bf16 v[136:139], v[64:67], v[200:203], v[150:153]
	v_mfma_f32_16x16x32_bf16 v[120:123], v[72:75], v[200:203], v[120:123]
	v_mfma_f32_16x16x32_bf16 v[116:119], v[76:79], v[108:111], v[116:119]
	v_mfma_f32_16x16x32_bf16 v[124:127], v[76:79], v[188:191], v[124:127]
	v_mfma_f32_16x16x32_bf16 v[112:115], v[76:79], v[196:199], v[112:115]
	v_mfma_f32_16x16x32_bf16 v[150:153], v[68:71], v[204:207], v[136:139]
	v_mfma_f32_16x16x32_bf16 v[120:123], v[76:79], v[204:207], v[120:123]
	s_barrier
	s_add_i32 s58, 0, 0x1c000
	v_add_u32_e32 v136, s58, v217
	s_add_i32 s27, s27, s74
	ds_read_b128 v[222:225], v136
	ds_read_b128 v[228:231], v136 offset:1024
	ds_read_b128 v[232:235], v136 offset:2048
	ds_read_b128 v[236:239], v136 offset:3072
	s_add_u32 s56, s82, s18
	s_addc_u32 s57, s83, s19
	s_mov_b32 m0, s27
	s_nop 0
	global_load_lds_dwordx4 v144, s[56:57]
	s_add_u32 s56, s82, s18
	s_addc_u32 s57, s83, s19
	s_add_i32 m0, s27, 0x2000
	s_nop 0
	global_load_lds_dwordx4 v162, s[56:57]
	s_barrier
	s_waitcnt lgkmcnt(0)
	v_mfma_f32_16x16x32_bf16 v[136:139], v[222:225], v[104:107], v[140:143]
	v_mfma_f32_16x16x32_bf16 v[80:83], v[232:235], v[104:107], v[80:83]
	v_mfma_f32_16x16x32_bf16 v[140:143], v[228:231], v[108:111], v[136:139]
	v_mfma_f32_16x16x32_bf16 v[108:111], v[236:239], v[108:111], v[80:83]
	v_mfma_f32_16x16x32_bf16 v[80:83], v[222:225], v[132:135], v[84:87]
	v_mfma_f32_16x16x32_bf16 v[136:139], v[228:231], v[188:191], v[80:83]
	v_mfma_f32_16x16x32_bf16 v[80:83], v[232:235], v[132:135], v[88:91]
	v_mfma_f32_16x16x32_bf16 v[104:107], v[236:239], v[188:191], v[80:83]
	v_mfma_f32_16x16x32_bf16 v[80:83], v[222:225], v[192:195], v[92:95]
	v_mfma_f32_16x16x32_bf16 v[132:135], v[228:231], v[196:199], v[80:83]
	v_mfma_f32_16x16x32_bf16 v[80:83], v[232:235], v[192:195], v[100:103]
	v_mfma_f32_16x16x32_bf16 v[100:103], v[236:239], v[196:199], v[80:83]
	v_mfma_f32_16x16x32_bf16 v[80:83], v[222:225], v[200:203], v[128:131]
	v_mfma_f32_16x16x32_bf16 v[128:131], v[228:231], v[204:207], v[80:83]
	v_mfma_f32_16x16x32_bf16 v[80:83], v[232:235], v[200:203], v[96:99]
	v_mfma_f32_16x16x32_bf16 v[96:99], v[236:239], v[204:207], v[80:83]
	s_barrier
	s_mov_b32 m0, s31
	s_add_u32 s56, vcc_lo, s18
	s_addc_u32 s57, vcc_hi, s19
	s_nop 2
	ds_read_b128 v[80:83], v220 offset:49152
	ds_read_b128 v[84:87], v220 offset:50176
	ds_read_b128 v[88:91], v220 offset:51200
	ds_read_b128 v[92:95], v220 offset:52224
	ds_read_b128 v[188:191], v220 offset:53248
	ds_read_b128 v[192:195], v220 offset:54272
	ds_read_b128 v[196:199], v220 offset:55296
	ds_read_b128 v[200:203], v220 offset:56320
	global_load_lds_dwordx4 v144, s[56:57]
	s_add_u32 s56, vcc_lo, s18
	s_addc_u32 s57, vcc_hi, s19
	s_mov_b32 m0, s34
	s_nop 0
	global_load_lds_dwordx4 v162, s[56:57]
	s_barrier
	s_waitcnt lgkmcnt(0)
	v_mfma_f32_16x16x32_bf16 v[48:51], v[64:67], v[80:83], v[48:51]
	v_mfma_f32_16x16x32_bf16 v[20:23], v[72:75], v[80:83], v[20:23]
	v_mfma_f32_16x16x32_bf16 v[60:63], v[64:67], v[88:91], v[60:63]
	v_mfma_f32_16x16x32_bf16 v[28:31], v[72:75], v[88:91], v[28:31]
	v_mfma_f32_16x16x32_bf16 v[56:59], v[64:67], v[188:191], v[56:59]
	v_mfma_f32_16x16x32_bf16 v[16:19], v[72:75], v[188:191], v[16:19]
	v_mfma_f32_16x16x32_bf16 v[52:55], v[64:67], v[196:199], v[52:55]
	v_mfma_f32_16x16x32_bf16 v[24:27], v[72:75], v[196:199], v[24:27]
	v_mfma_f32_16x16x32_bf16 v[48:51], v[68:71], v[84:87], v[48:51]
	v_mfma_f32_16x16x32_bf16 v[20:23], v[76:79], v[84:87], v[20:23]
	v_mfma_f32_16x16x32_bf16 v[60:63], v[68:71], v[92:95], v[60:63]
	v_mfma_f32_16x16x32_bf16 v[28:31], v[76:79], v[92:95], v[28:31]
	v_mfma_f32_16x16x32_bf16 v[56:59], v[68:71], v[192:195], v[56:59]
	v_mfma_f32_16x16x32_bf16 v[16:19], v[76:79], v[192:195], v[16:19]
	v_mfma_f32_16x16x32_bf16 v[52:55], v[68:71], v[200:203], v[52:55]
	v_mfma_f32_16x16x32_bf16 v[24:27], v[76:79], v[200:203], v[24:27]
	s_barrier
	s_add_u32 s56, s82, 0x40080
	s_addc_u32 s57, s83, 0
	s_add_i32 s27, s58, s74
	s_mov_b32 m0, s27
	s_nop 0
	global_load_lds_dwordx4 v144, s[56:57]
	s_add_i32 m0, s27, 0x2000
	s_nop 0
	global_load_lds_dwordx4 v162, s[56:57]
	s_waitcnt vmcnt(6)
	s_barrier
	v_mfma_f32_16x16x32_bf16 v[44:47], v[222:225], v[80:83], v[44:47]
	v_mfma_f32_16x16x32_bf16 v[12:15], v[232:235], v[80:83], v[12:15]
	v_mfma_f32_16x16x32_bf16 v[40:43], v[222:225], v[88:91], v[40:43]
	v_mfma_f32_16x16x32_bf16 v[8:11], v[232:235], v[88:91], v[8:11]
	v_mfma_f32_16x16x32_bf16 v[36:39], v[222:225], v[188:191], v[36:39]
	v_mfma_f32_16x16x32_bf16 v[4:7], v[232:235], v[188:191], v[4:7]
	v_mfma_f32_16x16x32_bf16 v[32:35], v[222:225], v[196:199], v[32:35]
	v_mfma_f32_16x16x32_bf16 v[0:3], v[232:235], v[196:199], v[0:3]
	v_mfma_f32_16x16x32_bf16 v[44:47], v[228:231], v[84:87], v[44:47]
	v_mfma_f32_16x16x32_bf16 v[12:15], v[236:239], v[84:87], v[12:15]
	v_mfma_f32_16x16x32_bf16 v[40:43], v[228:231], v[92:95], v[40:43]
	v_mfma_f32_16x16x32_bf16 v[8:11], v[236:239], v[92:95], v[8:11]
	v_mfma_f32_16x16x32_bf16 v[36:39], v[228:231], v[192:195], v[36:39]
	v_mfma_f32_16x16x32_bf16 v[4:7], v[236:239], v[192:195], v[4:7]
	v_mfma_f32_16x16x32_bf16 v[32:35], v[228:231], v[200:203], v[32:35]
	v_mfma_f32_16x16x32_bf16 v[0:3], v[236:239], v[200:203], v[0:3]
	s_barrier
	s_add_i32 s37, s37, 2
	s_add_u32 s86, s86, 0x100
	s_addc_u32 s87, s87, 0
	s_add_u32 s33, s33, 0x100
	s_addc_u32 s36, s36, 0
	s_cmp_gt_u32 s37, 13
.LBB0_125:
	s_add_u32 s27, s86, 0xfffc0080
	s_addc_u32 s56, s87, -1
	s_add_i32 s57, 0, 0x10000
	v_add_u32_e32 v76, s57, v217
	ds_read_b128 v[64:67], v76
	ds_read_b128 v[68:71], v76 offset:1024
	ds_read_b128 v[72:75], v76 offset:2048
	ds_read_b128 v[76:79], v76 offset:3072
	s_cmp_eq_u32 s37, 12
	s_cselect_b32 vcc_hi, s1, s56
	s_cselect_b32 vcc_lo, s10, s27
	s_cselect_b32 s83, s11, s36
	s_cselect_b32 s82, s25, s33
	s_add_i32 m0, s75, 0xc000
	ds_read_b128 v[80:83], v220
	ds_read_b128 v[84:87], v220 offset:1024
	ds_read_b128 v[88:91], v220 offset:2048
	ds_read_b128 v[92:95], v220 offset:3072
	ds_read_b128 v[188:191], v220 offset:4096
	ds_read_b128 v[192:195], v220 offset:5120
	ds_read_b128 v[196:199], v220 offset:6144
	ds_read_b128 v[200:203], v220 offset:7168
	global_load_lds_dwordx4 v164, s[86:87]
	s_add_i32 m0, s75, 0xe000
	s_nop 0
	global_load_lds_dwordx4 v166, s[86:87]
	s_waitcnt lgkmcnt(8)
	s_barrier
	s_waitcnt lgkmcnt(0)
	v_mfma_f32_16x16x32_bf16 v[146:149], v[64:67], v[80:83], v[146:149]
	v_mfma_f32_16x16x32_bf16 v[116:119], v[72:75], v[80:83], v[116:119]
	v_mfma_f32_16x16x32_bf16 v[158:161], v[64:67], v[88:91], v[158:161]
	v_mfma_f32_16x16x32_bf16 v[124:127], v[72:75], v[88:91], v[124:127]
	v_mfma_f32_16x16x32_bf16 v[154:157], v[64:67], v[188:191], v[154:157]
	v_mfma_f32_16x16x32_bf16 v[112:115], v[72:75], v[188:191], v[112:115]
	v_mfma_f32_16x16x32_bf16 v[150:153], v[64:67], v[196:199], v[150:153]
	v_mfma_f32_16x16x32_bf16 v[120:123], v[72:75], v[196:199], v[120:123]
	v_mfma_f32_16x16x32_bf16 v[146:149], v[68:71], v[84:87], v[146:149]
	v_mfma_f32_16x16x32_bf16 v[116:119], v[76:79], v[84:87], v[116:119]
	v_mfma_f32_16x16x32_bf16 v[158:161], v[68:71], v[92:95], v[158:161]
	v_mfma_f32_16x16x32_bf16 v[124:127], v[76:79], v[92:95], v[124:127]
	v_mfma_f32_16x16x32_bf16 v[154:157], v[68:71], v[192:195], v[154:157]
	v_mfma_f32_16x16x32_bf16 v[112:115], v[76:79], v[192:195], v[112:115]
	v_mfma_f32_16x16x32_bf16 v[150:153], v[68:71], v[200:203], v[150:153]
	v_mfma_f32_16x16x32_bf16 v[120:123], v[76:79], v[200:203], v[120:123]
	s_barrier
	s_add_i32 s27, 0, 0x14000
	v_add_u32_e32 v168, s27, v217
	s_add_i32 s56, s57, s74
	ds_read_b128 v[204:207], v168
	ds_read_b128 v[222:225], v168 offset:1024
	ds_read_b128 v[228:231], v168 offset:2048
	ds_read_b128 v[232:235], v168 offset:3072
	s_mov_b32 m0, s56
	global_load_lds_dwordx4 v144, s[82:83]
	s_add_i32 m0, s56, 0x2000
	s_nop 0
	global_load_lds_dwordx4 v162, s[82:83]
	s_barrier
	s_waitcnt lgkmcnt(0)
	v_mfma_f32_16x16x32_bf16 v[140:143], v[204:207], v[80:83], v[140:143]
	v_mfma_f32_16x16x32_bf16 v[80:83], v[228:231], v[80:83], v[108:111]
	v_mfma_f32_16x16x32_bf16 v[140:143], v[222:225], v[84:87], v[140:143]
	v_mfma_f32_16x16x32_bf16 v[80:83], v[232:235], v[84:87], v[80:83]
	v_mfma_f32_16x16x32_bf16 v[84:87], v[204:207], v[88:91], v[136:139]
	v_mfma_f32_16x16x32_bf16 v[88:91], v[228:231], v[88:91], v[104:107]
	v_mfma_f32_16x16x32_bf16 v[100:103], v[228:231], v[188:191], v[100:103]
	v_mfma_f32_16x16x32_bf16 v[104:107], v[204:207], v[196:199], v[128:131]
	v_mfma_f32_16x16x32_bf16 v[96:99], v[228:231], v[196:199], v[96:99]
	v_mfma_f32_16x16x32_bf16 v[84:87], v[222:225], v[92:95], v[84:87]
	v_mfma_f32_16x16x32_bf16 v[88:91], v[232:235], v[92:95], v[88:91]
	v_mfma_f32_16x16x32_bf16 v[92:95], v[204:207], v[188:191], v[132:135]
	v_mfma_f32_16x16x32_bf16 v[100:103], v[232:235], v[192:195], v[100:103]
	v_mfma_f32_16x16x32_bf16 v[128:131], v[222:225], v[200:203], v[104:107]
	v_mfma_f32_16x16x32_bf16 v[96:99], v[232:235], v[200:203], v[96:99]
	v_mfma_f32_16x16x32_bf16 v[92:95], v[222:225], v[192:195], v[92:95]
	s_barrier
	s_mov_b32 m0, s75
	ds_read_b128 v[104:107], v220 offset:16384
	ds_read_b128 v[108:111], v220 offset:17408
	ds_read_b128 v[132:135], v220 offset:18432
	ds_read_b128 v[136:139], v220 offset:19456
	ds_read_b128 v[188:191], v220 offset:20480
	ds_read_b128 v[192:195], v220 offset:21504
	ds_read_b128 v[196:199], v220 offset:22528
	ds_read_b128 v[200:203], v220 offset:23552
	global_load_lds_dwordx4 v144, vcc
	s_mov_b32 m0, s85
	s_nop 0
	global_load_lds_dwordx4 v162, vcc
	s_barrier
	s_waitcnt lgkmcnt(0)
	v_mfma_f32_16x16x32_bf16 v[48:51], v[64:67], v[104:107], v[48:51]
	v_mfma_f32_16x16x32_bf16 v[20:23], v[72:75], v[104:107], v[20:23]
	v_mfma_f32_16x16x32_bf16 v[60:63], v[64:67], v[132:135], v[60:63]
	v_mfma_f32_16x16x32_bf16 v[28:31], v[72:75], v[132:135], v[28:31]
	v_mfma_f32_16x16x32_bf16 v[56:59], v[64:67], v[188:191], v[56:59]
	v_mfma_f32_16x16x32_bf16 v[16:19], v[72:75], v[188:191], v[16:19]
	v_mfma_f32_16x16x32_bf16 v[52:55], v[64:67], v[196:199], v[52:55]
	v_mfma_f32_16x16x32_bf16 v[24:27], v[72:75], v[196:199], v[24:27]
	v_mfma_f32_16x16x32_bf16 v[48:51], v[68:71], v[108:111], v[48:51]
	v_mfma_f32_16x16x32_bf16 v[20:23], v[76:79], v[108:111], v[20:23]
	v_mfma_f32_16x16x32_bf16 v[60:63], v[68:71], v[136:139], v[60:63]
	v_mfma_f32_16x16x32_bf16 v[28:31], v[76:79], v[136:139], v[28:31]
	v_mfma_f32_16x16x32_bf16 v[56:59], v[68:71], v[192:195], v[56:59]
	v_mfma_f32_16x16x32_bf16 v[16:19], v[76:79], v[192:195], v[16:19]
	v_mfma_f32_16x16x32_bf16 v[52:55], v[68:71], v[200:203], v[52:55]
	v_mfma_f32_16x16x32_bf16 v[24:27], v[76:79], v[200:203], v[24:27]
	s_barrier
	s_add_u32 s56, s82, 0x40000
	s_addc_u32 s57, s83, 0
	s_add_i32 s27, s27, s74
	s_mov_b32 m0, s27
	s_nop 0
	global_load_lds_dwordx4 v144, s[56:57]
	s_add_i32 m0, s27, 0x2000
	s_nop 0
	global_load_lds_dwordx4 v162, s[56:57]
	s_waitcnt vmcnt(6)
	s_barrier
	v_mfma_f32_16x16x32_bf16 v[44:47], v[204:207], v[104:107], v[44:47]
	v_mfma_f32_16x16x32_bf16 v[12:15], v[228:231], v[104:107], v[12:15]
	v_mfma_f32_16x16x32_bf16 v[40:43], v[204:207], v[132:135], v[40:43]
	v_mfma_f32_16x16x32_bf16 v[8:11], v[228:231], v[132:135], v[8:11]
	v_mfma_f32_16x16x32_bf16 v[36:39], v[204:207], v[188:191], v[36:39]
	v_mfma_f32_16x16x32_bf16 v[4:7], v[228:231], v[188:191], v[4:7]
	v_mfma_f32_16x16x32_bf16 v[32:35], v[204:207], v[196:199], v[32:35]
	v_mfma_f32_16x16x32_bf16 v[0:3], v[228:231], v[196:199], v[0:3]
	v_mfma_f32_16x16x32_bf16 v[44:47], v[222:225], v[108:111], v[44:47]
	v_mfma_f32_16x16x32_bf16 v[12:15], v[232:235], v[108:111], v[12:15]
	v_mfma_f32_16x16x32_bf16 v[40:43], v[222:225], v[136:139], v[40:43]
	v_mfma_f32_16x16x32_bf16 v[8:11], v[232:235], v[136:139], v[8:11]
	v_mfma_f32_16x16x32_bf16 v[36:39], v[222:225], v[192:195], v[36:39]
	v_mfma_f32_16x16x32_bf16 v[4:7], v[232:235], v[192:195], v[4:7]
	v_mfma_f32_16x16x32_bf16 v[32:35], v[222:225], v[200:203], v[32:35]
	v_mfma_f32_16x16x32_bf16 v[0:3], v[232:235], v[200:203], v[0:3]
	s_barrier
	s_add_i32 s27, 0, 0x18000
	v_add_u32_e32 v76, s27, v217
	ds_read_b128 v[64:67], v76
	ds_read_b128 v[68:71], v76 offset:1024
	ds_read_b128 v[72:75], v76 offset:2048
	ds_read_b128 v[76:79], v76 offset:3072
	s_add_u32 s56, vcc_lo, 0x40000
	s_addc_u32 s57, vcc_hi, 0
	s_mov_b32 m0, s98
	ds_read_b128 v[104:107], v220 offset:32768
	ds_read_b128 v[108:111], v220 offset:33792
	ds_read_b128 v[132:135], v220 offset:34816
	ds_read_b128 v[188:191], v220 offset:35840
	ds_read_b128 v[192:195], v220 offset:36864
	ds_read_b128 v[196:199], v220 offset:37888
	ds_read_b128 v[200:203], v220 offset:38912
	ds_read_b128 v[204:207], v220 offset:39936
	global_load_lds_dwordx4 v144, s[56:57]
	s_mov_b32 m0, s29
	s_nop 0
	global_load_lds_dwordx4 v162, s[56:57]
	s_waitcnt lgkmcnt(8)
	s_barrier
	s_waitcnt lgkmcnt(0)
	v_mfma_f32_16x16x32_bf16 v[136:139], v[64:67], v[104:107], v[146:149]
	v_mfma_f32_16x16x32_bf16 v[146:149], v[68:71], v[108:111], v[136:139]
	v_mfma_f32_16x16x32_bf16 v[136:139], v[64:67], v[132:135], v[158:161]
	v_mfma_f32_16x16x32_bf16 v[158:161], v[68:71], v[188:191], v[136:139]
	v_mfma_f32_16x16x32_bf16 v[136:139], v[64:67], v[192:195], v[154:157]
	v_mfma_f32_16x16x32_bf16 v[116:119], v[72:75], v[104:107], v[116:119]
	v_mfma_f32_16x16x32_bf16 v[124:127], v[72:75], v[132:135], v[124:127]
	v_mfma_f32_16x16x32_bf16 v[154:157], v[68:71], v[196:199], v[136:139]
	v_mfma_f32_16x16x32_bf16 v[112:115], v[72:75], v[192:195], v[112:115]
	v_mfma_f32_16x16x32_bf16 v[136:139], v[64:67], v[200:203], v[150:153]
	v_mfma_f32_16x16x32_bf16 v[120:123], v[72:75], v[200:203], v[120:123]
	v_mfma_f32_16x16x32_bf16 v[116:119], v[76:79], v[108:111], v[116:119]
	v_mfma_f32_16x16x32_bf16 v[124:127], v[76:79], v[188:191], v[124:127]
	v_mfma_f32_16x16x32_bf16 v[112:115], v[76:79], v[196:199], v[112:115]
	v_mfma_f32_16x16x32_bf16 v[150:153], v[68:71], v[204:207], v[136:139]
	v_mfma_f32_16x16x32_bf16 v[120:123], v[76:79], v[204:207], v[120:123]
	s_barrier
	s_add_i32 s58, 0, 0x1c000
	v_add_u32_e32 v136, s58, v217
	s_add_i32 s27, s27, s74
	ds_read_b128 v[222:225], v136
	ds_read_b128 v[228:231], v136 offset:1024
	ds_read_b128 v[232:235], v136 offset:2048
	ds_read_b128 v[236:239], v136 offset:3072
	s_add_u32 s56, s82, s18
	s_addc_u32 s57, s83, s19
	s_mov_b32 m0, s27
	s_nop 0
	global_load_lds_dwordx4 v144, s[56:57]
	s_add_u32 s56, s82, s18
	s_addc_u32 s57, s83, s19
	s_add_i32 m0, s27, 0x2000
	s_nop 0
	global_load_lds_dwordx4 v162, s[56:57]
	s_barrier
	s_waitcnt lgkmcnt(0)
	v_mfma_f32_16x16x32_bf16 v[136:139], v[222:225], v[104:107], v[140:143]
	v_mfma_f32_16x16x32_bf16 v[80:83], v[232:235], v[104:107], v[80:83]
	v_mfma_f32_16x16x32_bf16 v[140:143], v[228:231], v[108:111], v[136:139]
	v_mfma_f32_16x16x32_bf16 v[108:111], v[236:239], v[108:111], v[80:83]
	v_mfma_f32_16x16x32_bf16 v[80:83], v[222:225], v[132:135], v[84:87]
	v_mfma_f32_16x16x32_bf16 v[136:139], v[228:231], v[188:191], v[80:83]
	v_mfma_f32_16x16x32_bf16 v[80:83], v[232:235], v[132:135], v[88:91]
	v_mfma_f32_16x16x32_bf16 v[104:107], v[236:239], v[188:191], v[80:83]
	v_mfma_f32_16x16x32_bf16 v[80:83], v[222:225], v[192:195], v[92:95]
	v_mfma_f32_16x16x32_bf16 v[132:135], v[228:231], v[196:199], v[80:83]
	v_mfma_f32_16x16x32_bf16 v[80:83], v[232:235], v[192:195], v[100:103]
	v_mfma_f32_16x16x32_bf16 v[100:103], v[236:239], v[196:199], v[80:83]
	v_mfma_f32_16x16x32_bf16 v[80:83], v[222:225], v[200:203], v[128:131]
	v_mfma_f32_16x16x32_bf16 v[128:131], v[228:231], v[204:207], v[80:83]
	v_mfma_f32_16x16x32_bf16 v[80:83], v[232:235], v[200:203], v[96:99]
	v_mfma_f32_16x16x32_bf16 v[96:99], v[236:239], v[204:207], v[80:83]
	s_barrier
	s_mov_b32 m0, s31
	s_add_u32 s56, vcc_lo, s18
	s_addc_u32 s57, vcc_hi, s19
	s_nop 2
	ds_read_b128 v[80:83], v220 offset:49152
	ds_read_b128 v[84:87], v220 offset:50176
	ds_read_b128 v[88:91], v220 offset:51200
	ds_read_b128 v[92:95], v220 offset:52224
	ds_read_b128 v[188:191], v220 offset:53248
	ds_read_b128 v[192:195], v220 offset:54272
	ds_read_b128 v[196:199], v220 offset:55296
	ds_read_b128 v[200:203], v220 offset:56320
	global_load_lds_dwordx4 v144, s[56:57]
	s_add_u32 s56, vcc_lo, s18
	s_addc_u32 s57, vcc_hi, s19
	s_mov_b32 m0, s34
	s_nop 0
	global_load_lds_dwordx4 v162, s[56:57]
	s_barrier
	s_waitcnt lgkmcnt(0)
	v_mfma_f32_16x16x32_bf16 v[48:51], v[64:67], v[80:83], v[48:51]
	v_mfma_f32_16x16x32_bf16 v[20:23], v[72:75], v[80:83], v[20:23]
	v_mfma_f32_16x16x32_bf16 v[60:63], v[64:67], v[88:91], v[60:63]
	v_mfma_f32_16x16x32_bf16 v[28:31], v[72:75], v[88:91], v[28:31]
	v_mfma_f32_16x16x32_bf16 v[56:59], v[64:67], v[188:191], v[56:59]
	v_mfma_f32_16x16x32_bf16 v[16:19], v[72:75], v[188:191], v[16:19]
	v_mfma_f32_16x16x32_bf16 v[52:55], v[64:67], v[196:199], v[52:55]
	v_mfma_f32_16x16x32_bf16 v[24:27], v[72:75], v[196:199], v[24:27]
	v_mfma_f32_16x16x32_bf16 v[48:51], v[68:71], v[84:87], v[48:51]
	v_mfma_f32_16x16x32_bf16 v[20:23], v[76:79], v[84:87], v[20:23]
	v_mfma_f32_16x16x32_bf16 v[60:63], v[68:71], v[92:95], v[60:63]
	v_mfma_f32_16x16x32_bf16 v[28:31], v[76:79], v[92:95], v[28:31]
	v_mfma_f32_16x16x32_bf16 v[56:59], v[68:71], v[192:195], v[56:59]
	v_mfma_f32_16x16x32_bf16 v[16:19], v[76:79], v[192:195], v[16:19]
	v_mfma_f32_16x16x32_bf16 v[52:55], v[68:71], v[200:203], v[52:55]
	v_mfma_f32_16x16x32_bf16 v[24:27], v[76:79], v[200:203], v[24:27]
	s_barrier
	s_add_u32 s56, s82, 0x40080
	s_addc_u32 s57, s83, 0
	s_add_i32 s27, s58, s74
	s_mov_b32 m0, s27
	s_nop 0
	global_load_lds_dwordx4 v144, s[56:57]
	s_add_i32 m0, s27, 0x2000
	s_nop 0
	global_load_lds_dwordx4 v162, s[56:57]
	s_waitcnt vmcnt(6)
	s_barrier
	v_mfma_f32_16x16x32_bf16 v[44:47], v[222:225], v[80:83], v[44:47]
	v_mfma_f32_16x16x32_bf16 v[12:15], v[232:235], v[80:83], v[12:15]
	v_mfma_f32_16x16x32_bf16 v[40:43], v[222:225], v[88:91], v[40:43]
	v_mfma_f32_16x16x32_bf16 v[8:11], v[232:235], v[88:91], v[8:11]
	v_mfma_f32_16x16x32_bf16 v[36:39], v[222:225], v[188:191], v[36:39]
	v_mfma_f32_16x16x32_bf16 v[4:7], v[232:235], v[188:191], v[4:7]
	v_mfma_f32_16x16x32_bf16 v[32:35], v[222:225], v[196:199], v[32:35]
	v_mfma_f32_16x16x32_bf16 v[0:3], v[232:235], v[196:199], v[0:3]
	v_mfma_f32_16x16x32_bf16 v[44:47], v[228:231], v[84:87], v[44:47]
	v_mfma_f32_16x16x32_bf16 v[12:15], v[236:239], v[84:87], v[12:15]
	v_mfma_f32_16x16x32_bf16 v[40:43], v[228:231], v[92:95], v[40:43]
	v_mfma_f32_16x16x32_bf16 v[8:11], v[236:239], v[92:95], v[8:11]
	v_mfma_f32_16x16x32_bf16 v[36:39], v[228:231], v[192:195], v[36:39]
	v_mfma_f32_16x16x32_bf16 v[4:7], v[236:239], v[192:195], v[4:7]
	v_mfma_f32_16x16x32_bf16 v[32:35], v[228:231], v[200:203], v[32:35]
	v_mfma_f32_16x16x32_bf16 v[0:3], v[236:239], v[200:203], v[0:3]
	s_barrier
	s_add_i32 s37, s37, 2
	s_add_u32 s86, s86, 0x100
	s_addc_u32 s87, s87, 0
	s_add_u32 s33, s33, 0x100
	s_addc_u32 s36, s36, 0
	s_cmp_gt_u32 s37, 13
	s_cbranch_scc0 .LBB0_125
	s_lshl_b32 s1, s84, 8
	v_readlane_b32 s10, v254, 61
	s_add_i32 s1, s1, s10
	v_or_b32_e32 v198, s1, v216
	s_add_i32 s10, s1, 0x80
	v_or_b32_e32 v168, s10, v216
	v_lshl_or_b32 v188, s0, 7, v219
	v_lshlrev_b32_e32 v190, 2, v188
	v_lshlrev_b32_e32 v189, 1, v188
	s_ashr_i32 s11, s1, 5
	s_movk_i32 s10, 0xb00
	s_movk_i32 s20, 0x1600
	s_mov_b32 s101, 0xbfb8aa3b
	s_cmp_eq_u32 s84, s100
	s_cbranch_scc1 .Ldepi_w
	v_ashrrev_i32_e32 v199, 31, v198
	v_ashrrev_i32_e32 v169, 31, v168
	v_lshl_add_u64 v[170:171], v[198:199], 3, s[48:49]
	v_lshl_add_u64 v[172:173], v[168:169], 3, s[48:49]
	global_load_dwordx2 v[176:177], v[170:171], off
	global_load_dwordx2 v[202:203], v[170:171], off offset:128
	global_load_dwordx2 v[206:207], v[170:171], off offset:256
	global_load_dwordx2 v[222:223], v[170:171], off offset:384
	global_load_dwordx2 v[200:201], v[172:173], off
	global_load_dwordx2 v[196:197], v[172:173], off offset:128
	global_load_dwordx2 v[194:195], v[172:173], off offset:256
	global_load_dwordx2 v[192:193], v[172:173], off offset:384

.LBB0_325:
	s_ashr_i32 s93, s92, 31
	s_lshl_b64 s[30:31], s[92:93], 19
	s_add_u32 s94, s54, s30
	v_cmp_lt_i64_e32 vcc, s[50:51], v[186:187]
	s_addc_u32 s95, s55, s31
	s_and_b64 s[30:31], vcc, exec
	s_cselect_b32 s1, s95, s53
	s_cselect_b32 s11, s94, s52
	s_ashr_i32 s9, s8, 31
	s_lshl_b64 s[30:31], s[8:9], 19
	s_add_u32 s28, s80, s30
	s_addc_u32 s29, s78, s31
	s_and_b64 s[30:31], vcc, exec
	s_cselect_b32 s25, s29, s73
	s_cselect_b32 s30, s28, s72
	s_add_u32 s52, s52, 0x40080
	s_addc_u32 s53, s53, 0
	s_add_u32 s31, s72, 0x100
	s_addc_u32 s33, s73, 0
	s_mov_b32 s34, -2
	s_add_u32 s27, s52, 0xfffc0080
	s_addc_u32 s35, s53, -1
	s_add_i32 s36, 0, 0x10000
	v_add_u32_e32 v140, s36, v216
	ds_read_b128 v[128:131], v140
	ds_read_b128 v[132:135], v140 offset:1024
	ds_read_b128 v[136:139], v140 offset:2048
	ds_read_b128 v[140:143], v140 offset:3072
	s_cmp_eq_u32 s34, 12
	s_cselect_b32 s75, s1, s35
	s_cselect_b32 s74, s11, s27
	s_cselect_b32 s73, s25, s33
	s_cselect_b32 s72, s30, s31
	s_add_i32 m0, s83, 0xc000
	ds_read_b128 v[156:159], v217
	ds_read_b128 v[160:163], v217 offset:1024
	ds_read_b128 v[164:167], v217 offset:2048
	ds_read_b128 v[188:191], v217 offset:3072
	ds_read_b128 v[192:195], v217 offset:4096
	ds_read_b128 v[196:199], v217 offset:5120
	ds_read_b128 v[200:203], v217 offset:6144
	ds_read_b128 v[204:207], v217 offset:7168
	global_load_lds_dwordx4 v152, s[52:53]
	s_add_i32 m0, s83, 0xe000
	s_nop 0
	global_load_lds_dwordx4 v154, s[52:53]
	s_waitcnt lgkmcnt(8)
	s_barrier
	s_waitcnt lgkmcnt(0)
	v_mfma_f32_16x16x32_bf16 v[124:127], v[128:131], v[156:159], 0
	v_mfma_f32_16x16x32_bf16 v[120:123], v[136:139], v[156:159], 0
	v_mfma_f32_16x16x32_bf16 v[108:111], v[128:131], v[164:167], 0
	v_mfma_f32_16x16x32_bf16 v[104:107], v[136:139], v[164:167], 0
	v_mfma_f32_16x16x32_bf16 v[92:95], v[128:131], v[192:195], 0
	v_mfma_f32_16x16x32_bf16 v[88:91], v[136:139], v[192:195], 0
	v_mfma_f32_16x16x32_bf16 v[76:79], v[128:131], v[200:203], 0
	v_mfma_f32_16x16x32_bf16 v[72:75], v[136:139], v[200:203], 0
	v_mfma_f32_16x16x32_bf16 v[124:127], v[132:135], v[160:163], v[124:127]
	v_mfma_f32_16x16x32_bf16 v[120:123], v[140:143], v[160:163], v[120:123]
	v_mfma_f32_16x16x32_bf16 v[108:111], v[132:135], v[188:191], v[108:111]
	v_mfma_f32_16x16x32_bf16 v[104:107], v[140:143], v[188:191], v[104:107]
	v_mfma_f32_16x16x32_bf16 v[92:95], v[132:135], v[196:199], v[92:95]
	v_mfma_f32_16x16x32_bf16 v[88:91], v[140:143], v[196:199], v[88:91]
	v_mfma_f32_16x16x32_bf16 v[76:79], v[132:135], v[204:207], v[76:79]
	v_mfma_f32_16x16x32_bf16 v[72:75], v[140:143], v[204:207], v[72:75]
	s_barrier
	s_add_i32 s27, 0, 0x14000
	s_add_i32 s35, s36, s81
	v_add_u32_e32 v144, s27, v216
	s_mov_b32 m0, s35
	ds_read_b128 v[220:223], v144
	ds_read_b128 v[228:231], v144 offset:1024
	ds_read_b128 v[232:235], v144 offset:2048
	ds_read_b128 v[236:239], v144 offset:3072
	global_load_lds_dwordx4 v148, s[72:73]
	s_add_i32 m0, s35, 0x2000
	s_nop 0
	global_load_lds_dwordx4 v146, s[72:73]
	s_barrier
	s_waitcnt lgkmcnt(0)
	v_mfma_f32_16x16x32_bf16 v[116:119], v[220:223], v[156:159], 0
	v_mfma_f32_16x16x32_bf16 v[112:115], v[232:235], v[156:159], 0
	v_mfma_f32_16x16x32_bf16 v[100:103], v[220:223], v[164:167], 0
	v_mfma_f32_16x16x32_bf16 v[96:99], v[232:235], v[164:167], 0
	v_mfma_f32_16x16x32_bf16 v[84:87], v[220:223], v[192:195], 0
	v_mfma_f32_16x16x32_bf16 v[80:83], v[232:235], v[192:195], 0
	v_mfma_f32_16x16x32_bf16 v[68:71], v[220:223], v[200:203], 0
	v_mfma_f32_16x16x32_bf16 v[64:67], v[232:235], v[200:203], 0
	v_mfma_f32_16x16x32_bf16 v[116:119], v[228:231], v[160:163], v[116:119]
	v_mfma_f32_16x16x32_bf16 v[112:115], v[236:239], v[160:163], v[112:115]
	v_mfma_f32_16x16x32_bf16 v[100:103], v[228:231], v[188:191], v[100:103]
	v_mfma_f32_16x16x32_bf16 v[96:99], v[236:239], v[188:191], v[96:99]
	v_mfma_f32_16x16x32_bf16 v[84:87], v[228:231], v[196:199], v[84:87]
	v_mfma_f32_16x16x32_bf16 v[80:83], v[236:239], v[196:199], v[80:83]
	v_mfma_f32_16x16x32_bf16 v[68:71], v[228:231], v[204:207], v[68:71]
	v_mfma_f32_16x16x32_bf16 v[64:67], v[236:239], v[204:207], v[64:67]
	s_barrier
	s_mov_b32 m0, s83
	ds_read_b128 v[156:159], v217 offset:16384
	ds_read_b128 v[160:163], v217 offset:17408
	ds_read_b128 v[164:167], v217 offset:18432
	ds_read_b128 v[188:191], v217 offset:19456
	ds_read_b128 v[192:195], v217 offset:20480
	ds_read_b128 v[196:199], v217 offset:21504
	ds_read_b128 v[200:203], v217 offset:22528
	ds_read_b128 v[204:207], v217 offset:23552
	global_load_lds_dwordx4 v148, s[74:75]
	s_mov_b32 m0, s84
	s_nop 0
	global_load_lds_dwordx4 v146, s[74:75]
	s_barrier
	s_waitcnt lgkmcnt(0)
	v_mfma_f32_16x16x32_bf16 v[60:63], v[128:131], v[156:159], 0
	v_mfma_f32_16x16x32_bf16 v[56:59], v[136:139], v[156:159], 0
	v_mfma_f32_16x16x32_bf16 v[44:47], v[128:131], v[164:167], 0
	v_mfma_f32_16x16x32_bf16 v[40:43], v[136:139], v[164:167], 0
	v_mfma_f32_16x16x32_bf16 v[28:31], v[128:131], v[192:195], 0
	v_mfma_f32_16x16x32_bf16 v[24:27], v[136:139], v[192:195], 0
	v_mfma_f32_16x16x32_bf16 v[12:15], v[128:131], v[200:203], 0
	v_mfma_f32_16x16x32_bf16 v[8:11], v[136:139], v[200:203], 0
	v_mfma_f32_16x16x32_bf16 v[60:63], v[132:135], v[160:163], v[60:63]
	v_mfma_f32_16x16x32_bf16 v[56:59], v[140:143], v[160:163], v[56:59]
	v_mfma_f32_16x16x32_bf16 v[44:47], v[132:135], v[188:191], v[44:47]
	v_mfma_f32_16x16x32_bf16 v[40:43], v[140:143], v[188:191], v[40:43]
	v_mfma_f32_16x16x32_bf16 v[28:31], v[132:135], v[196:199], v[28:31]
	v_mfma_f32_16x16x32_bf16 v[24:27], v[140:143], v[196:199], v[24:27]
	v_mfma_f32_16x16x32_bf16 v[12:15], v[132:135], v[204:207], v[12:15]
	v_mfma_f32_16x16x32_bf16 v[8:11], v[140:143], v[204:207], v[8:11]
	s_barrier
	s_add_u32 s36, s72, 0x40000
	s_addc_u32 s37, s73, 0
	s_add_i32 s27, s27, s81
	s_mov_b32 m0, s27
	s_nop 0
	global_load_lds_dwordx4 v148, s[36:37]
	s_add_i32 m0, s27, 0x2000
	s_nop 0
	global_load_lds_dwordx4 v146, s[36:37]
	s_waitcnt vmcnt(6)
	s_barrier
	v_mfma_f32_16x16x32_bf16 v[52:55], v[220:223], v[156:159], 0
	v_mfma_f32_16x16x32_bf16 v[48:51], v[232:235], v[156:159], 0
	v_mfma_f32_16x16x32_bf16 v[36:39], v[220:223], v[164:167], 0
	v_mfma_f32_16x16x32_bf16 v[32:35], v[232:235], v[164:167], 0
	v_mfma_f32_16x16x32_bf16 v[20:23], v[220:223], v[192:195], 0
	v_mfma_f32_16x16x32_bf16 v[16:19], v[232:235], v[192:195], 0
	v_mfma_f32_16x16x32_bf16 v[4:7], v[220:223], v[200:203], 0
	v_mfma_f32_16x16x32_bf16 v[0:3], v[232:235], v[200:203], 0
	v_mfma_f32_16x16x32_bf16 v[52:55], v[228:231], v[160:163], v[52:55]
	v_mfma_f32_16x16x32_bf16 v[48:51], v[236:239], v[160:163], v[48:51]
	v_mfma_f32_16x16x32_bf16 v[36:39], v[228:231], v[188:191], v[36:39]
	v_mfma_f32_16x16x32_bf16 v[32:35], v[236:239], v[188:191], v[32:35]
	v_mfma_f32_16x16x32_bf16 v[20:23], v[228:231], v[196:199], v[20:23]
	v_mfma_f32_16x16x32_bf16 v[16:19], v[236:239], v[196:199], v[16:19]
	v_mfma_f32_16x16x32_bf16 v[4:7], v[228:231], v[204:207], v[4:7]
	v_mfma_f32_16x16x32_bf16 v[0:3], v[236:239], v[204:207], v[0:3]
	s_barrier
	s_add_i32 s27, 0, 0x18000
	v_add_u32_e32 v140, s27, v216
	ds_read_b128 v[128:131], v140
	ds_read_b128 v[132:135], v140 offset:1024
	ds_read_b128 v[136:139], v140 offset:2048
	ds_read_b128 v[140:143], v140 offset:3072
	s_add_u32 s36, s74, 0x40000
	s_addc_u32 s37, s75, 0
	s_mov_b32 m0, s85
	ds_read_b128 v[156:159], v217 offset:32768
	ds_read_b128 v[160:163], v217 offset:33792
	ds_read_b128 v[164:167], v217 offset:34816
	ds_read_b128 v[188:191], v217 offset:35840
	ds_read_b128 v[192:195], v217 offset:36864
	ds_read_b128 v[196:199], v217 offset:37888
	ds_read_b128 v[200:203], v217 offset:38912
	ds_read_b128 v[204:207], v217 offset:39936
	global_load_lds_dwordx4 v148, s[36:37]
	s_mov_b32 m0, s86
	s_nop 0
	global_load_lds_dwordx4 v146, s[36:37]
	s_waitcnt lgkmcnt(8)
	s_barrier
	s_waitcnt lgkmcnt(0)
	v_mfma_f32_16x16x32_bf16 v[124:127], v[128:131], v[156:159], v[124:127]
	v_mfma_f32_16x16x32_bf16 v[120:123], v[136:139], v[156:159], v[120:123]
	v_mfma_f32_16x16x32_bf16 v[108:111], v[128:131], v[164:167], v[108:111]
	v_mfma_f32_16x16x32_bf16 v[104:107], v[136:139], v[164:167], v[104:107]
	v_mfma_f32_16x16x32_bf16 v[92:95], v[128:131], v[192:195], v[92:95]
	v_mfma_f32_16x16x32_bf16 v[88:91], v[136:139], v[192:195], v[88:91]
	v_mfma_f32_16x16x32_bf16 v[76:79], v[128:131], v[200:203], v[76:79]
	v_mfma_f32_16x16x32_bf16 v[72:75], v[136:139], v[200:203], v[72:75]
	v_mfma_f32_16x16x32_bf16 v[124:127], v[132:135], v[160:163], v[124:127]
	v_mfma_f32_16x16x32_bf16 v[120:123], v[140:143], v[160:163], v[120:123]
	v_mfma_f32_16x16x32_bf16 v[108:111], v[132:135], v[188:191], v[108:111]
	v_mfma_f32_16x16x32_bf16 v[104:107], v[140:143], v[188:191], v[104:107]
	v_mfma_f32_16x16x32_bf16 v[92:95], v[132:135], v[196:199], v[92:95]
	v_mfma_f32_16x16x32_bf16 v[88:91], v[140:143], v[196:199], v[88:91]
	v_mfma_f32_16x16x32_bf16 v[76:79], v[132:135], v[204:207], v[76:79]
	v_mfma_f32_16x16x32_bf16 v[72:75], v[140:143], v[204:207], v[72:75]
	s_barrier
	s_add_i32 s35, 0, 0x1c000
	s_add_i32 s27, s27, s81
	v_add_u32_e32 v144, s35, v216
	s_add_u32 s36, s72, s18
	s_addc_u32 s37, s73, s19
	s_mov_b32 m0, s27
	ds_read_b128 v[220:223], v144
	ds_read_b128 v[228:231], v144 offset:1024
	ds_read_b128 v[232:235], v144 offset:2048
	ds_read_b128 v[236:239], v144 offset:3072
	global_load_lds_dwordx4 v148, s[36:37]
	s_add_u32 s36, s72, s18
	s_addc_u32 s37, s73, s19
	s_add_i32 m0, s27, 0x2000
	s_nop 0
	global_load_lds_dwordx4 v146, s[36:37]
	s_barrier
	s_waitcnt lgkmcnt(0)
	v_mfma_f32_16x16x32_bf16 v[116:119], v[220:223], v[156:159], v[116:119]
	v_mfma_f32_16x16x32_bf16 v[112:115], v[232:235], v[156:159], v[112:115]
	v_mfma_f32_16x16x32_bf16 v[100:103], v[220:223], v[164:167], v[100:103]
	v_mfma_f32_16x16x32_bf16 v[96:99], v[232:235], v[164:167], v[96:99]
	v_mfma_f32_16x16x32_bf16 v[84:87], v[220:223], v[192:195], v[84:87]
	v_mfma_f32_16x16x32_bf16 v[80:83], v[232:235], v[192:195], v[80:83]
	v_mfma_f32_16x16x32_bf16 v[68:71], v[220:223], v[200:203], v[68:71]
	v_mfma_f32_16x16x32_bf16 v[64:67], v[232:235], v[200:203], v[64:67]
	v_mfma_f32_16x16x32_bf16 v[116:119], v[228:231], v[160:163], v[116:119]
	v_mfma_f32_16x16x32_bf16 v[112:115], v[236:239], v[160:163], v[112:115]
	v_mfma_f32_16x16x32_bf16 v[100:103], v[228:231], v[188:191], v[100:103]
	v_mfma_f32_16x16x32_bf16 v[96:99], v[236:239], v[188:191], v[96:99]
	v_mfma_f32_16x16x32_bf16 v[84:87], v[228:231], v[196:199], v[84:87]
	v_mfma_f32_16x16x32_bf16 v[80:83], v[236:239], v[196:199], v[80:83]
	v_mfma_f32_16x16x32_bf16 v[68:71], v[228:231], v[204:207], v[68:71]
	v_mfma_f32_16x16x32_bf16 v[64:67], v[236:239], v[204:207], v[64:67]
	s_barrier
	s_mov_b32 m0, s87
	s_add_u32 s36, s74, s18
	s_addc_u32 s37, s75, s19
	ds_read_b128 v[156:159], v217 offset:49152
	ds_read_b128 v[160:163], v217 offset:50176
	ds_read_b128 v[164:167], v217 offset:51200
	ds_read_b128 v[188:191], v217 offset:52224
	ds_read_b128 v[192:195], v217 offset:53248
	ds_read_b128 v[196:199], v217 offset:54272
	ds_read_b128 v[200:203], v217 offset:55296
	ds_read_b128 v[204:207], v217 offset:56320
	global_load_lds_dwordx4 v148, s[36:37]
	s_add_u32 s36, s74, s18
	s_addc_u32 s37, s75, s19
	s_mov_b32 m0, s79
	s_nop 0
	global_load_lds_dwordx4 v146, s[36:37]
	s_barrier
	s_waitcnt lgkmcnt(0)
	v_mfma_f32_16x16x32_bf16 v[60:63], v[128:131], v[156:159], v[60:63]
	v_mfma_f32_16x16x32_bf16 v[56:59], v[136:139], v[156:159], v[56:59]
	v_mfma_f32_16x16x32_bf16 v[44:47], v[128:131], v[164:167], v[44:47]
	v_mfma_f32_16x16x32_bf16 v[40:43], v[136:139], v[164:167], v[40:43]
	v_mfma_f32_16x16x32_bf16 v[28:31], v[128:131], v[192:195], v[28:31]
	v_mfma_f32_16x16x32_bf16 v[24:27], v[136:139], v[192:195], v[24:27]
	v_mfma_f32_16x16x32_bf16 v[12:15], v[128:131], v[200:203], v[12:15]
	v_mfma_f32_16x16x32_bf16 v[8:11], v[136:139], v[200:203], v[8:11]
	v_mfma_f32_16x16x32_bf16 v[60:63], v[132:135], v[160:163], v[60:63]
	v_mfma_f32_16x16x32_bf16 v[56:59], v[140:143], v[160:163], v[56:59]
	v_mfma_f32_16x16x32_bf16 v[44:47], v[132:135], v[188:191], v[44:47]
	v_mfma_f32_16x16x32_bf16 v[40:43], v[140:143], v[188:191], v[40:43]
	v_mfma_f32_16x16x32_bf16 v[28:31], v[132:135], v[196:199], v[28:31]
	v_mfma_f32_16x16x32_bf16 v[24:27], v[140:143], v[196:199], v[24:27]
	v_mfma_f32_16x16x32_bf16 v[12:15], v[132:135], v[204:207], v[12:15]
	v_mfma_f32_16x16x32_bf16 v[8:11], v[140:143], v[204:207], v[8:11]
	s_barrier
	s_add_u32 s36, s72, 0x40080
	s_addc_u32 s37, s73, 0
	s_add_i32 s27, s35, s81
	s_mov_b32 m0, s27
	s_nop 0
	global_load_lds_dwordx4 v148, s[36:37]
	s_add_i32 m0, s27, 0x2000
	s_nop 0
	global_load_lds_dwordx4 v146, s[36:37]
	s_waitcnt vmcnt(6)
	s_barrier
	v_mfma_f32_16x16x32_bf16 v[52:55], v[220:223], v[156:159], v[52:55]
	v_mfma_f32_16x16x32_bf16 v[48:51], v[232:235], v[156:159], v[48:51]
	v_mfma_f32_16x16x32_bf16 v[36:39], v[220:223], v[164:167], v[36:39]
	v_mfma_f32_16x16x32_bf16 v[32:35], v[232:235], v[164:167], v[32:35]
	v_mfma_f32_16x16x32_bf16 v[20:23], v[220:223], v[192:195], v[20:23]
	v_mfma_f32_16x16x32_bf16 v[16:19], v[232:235], v[192:195], v[16:19]
	v_mfma_f32_16x16x32_bf16 v[4:7], v[220:223], v[200:203], v[4:7]
	v_mfma_f32_16x16x32_bf16 v[0:3], v[232:235], v[200:203], v[0:3]
	v_mfma_f32_16x16x32_bf16 v[52:55], v[228:231], v[160:163], v[52:55]
	v_mfma_f32_16x16x32_bf16 v[48:51], v[236:239], v[160:163], v[48:51]
	v_mfma_f32_16x16x32_bf16 v[36:39], v[228:231], v[188:191], v[36:39]
	v_mfma_f32_16x16x32_bf16 v[32:35], v[236:239], v[188:191], v[32:35]
	v_mfma_f32_16x16x32_bf16 v[20:23], v[228:231], v[196:199], v[20:23]
	v_mfma_f32_16x16x32_bf16 v[16:19], v[236:239], v[196:199], v[16:19]
	v_mfma_f32_16x16x32_bf16 v[4:7], v[228:231], v[204:207], v[4:7]
	v_mfma_f32_16x16x32_bf16 v[0:3], v[236:239], v[204:207], v[0:3]
	s_barrier
	s_add_i32 s34, s34, 2
	s_add_u32 s52, s52, 0x100
	s_addc_u32 s53, s53, 0
	s_add_u32 s31, s31, 0x100
	s_addc_u32 s33, s33, 0
	s_cmp_gt_u32 s34, 13
.LBB0_326:
	s_add_u32 s27, s52, 0xfffc0080
	s_addc_u32 s35, s53, -1
	s_add_i32 s36, 0, 0x10000
	v_add_u32_e32 v140, s36, v216
	ds_read_b128 v[128:131], v140
	ds_read_b128 v[132:135], v140 offset:1024
	ds_read_b128 v[136:139], v140 offset:2048
	ds_read_b128 v[140:143], v140 offset:3072
	s_cmp_eq_u32 s34, 12
	s_cselect_b32 s75, s1, s35
	s_cselect_b32 s74, s11, s27
	s_cselect_b32 s73, s25, s33
	s_cselect_b32 s72, s30, s31
	s_add_i32 m0, s83, 0xc000
	ds_read_b128 v[156:159], v217
	ds_read_b128 v[160:163], v217 offset:1024
	ds_read_b128 v[164:167], v217 offset:2048
	ds_read_b128 v[188:191], v217 offset:3072
	ds_read_b128 v[192:195], v217 offset:4096
	ds_read_b128 v[196:199], v217 offset:5120
	ds_read_b128 v[200:203], v217 offset:6144
	ds_read_b128 v[204:207], v217 offset:7168
	global_load_lds_dwordx4 v152, s[52:53]
	s_add_i32 m0, s83, 0xe000
	s_nop 0
	global_load_lds_dwordx4 v154, s[52:53]
	s_waitcnt lgkmcnt(8)
	s_barrier
	s_waitcnt lgkmcnt(0)
	v_mfma_f32_16x16x32_bf16 v[124:127], v[128:131], v[156:159], v[124:127]
	v_mfma_f32_16x16x32_bf16 v[120:123], v[136:139], v[156:159], v[120:123]
	v_mfma_f32_16x16x32_bf16 v[108:111], v[128:131], v[164:167], v[108:111]
	v_mfma_f32_16x16x32_bf16 v[104:107], v[136:139], v[164:167], v[104:107]
	v_mfma_f32_16x16x32_bf16 v[92:95], v[128:131], v[192:195], v[92:95]
	v_mfma_f32_16x16x32_bf16 v[88:91], v[136:139], v[192:195], v[88:91]
	v_mfma_f32_16x16x32_bf16 v[76:79], v[128:131], v[200:203], v[76:79]
	v_mfma_f32_16x16x32_bf16 v[72:75], v[136:139], v[200:203], v[72:75]
	v_mfma_f32_16x16x32_bf16 v[124:127], v[132:135], v[160:163], v[124:127]
	v_mfma_f32_16x16x32_bf16 v[120:123], v[140:143], v[160:163], v[120:123]
	v_mfma_f32_16x16x32_bf16 v[108:111], v[132:135], v[188:191], v[108:111]
	v_mfma_f32_16x16x32_bf16 v[104:107], v[140:143], v[188:191], v[104:107]
	v_mfma_f32_16x16x32_bf16 v[92:95], v[132:135], v[196:199], v[92:95]
	v_mfma_f32_16x16x32_bf16 v[88:91], v[140:143], v[196:199], v[88:91]
	v_mfma_f32_16x16x32_bf16 v[76:79], v[132:135], v[204:207], v[76:79]
	v_mfma_f32_16x16x32_bf16 v[72:75], v[140:143], v[204:207], v[72:75]
	s_barrier
	s_add_i32 s27, 0, 0x14000
	s_add_i32 s35, s36, s81
	v_add_u32_e32 v144, s27, v216
	s_mov_b32 m0, s35
	ds_read_b128 v[220:223], v144
	ds_read_b128 v[228:231], v144 offset:1024
	ds_read_b128 v[232:235], v144 offset:2048
	ds_read_b128 v[236:239], v144 offset:3072
	global_load_lds_dwordx4 v148, s[72:73]
	s_add_i32 m0, s35, 0x2000
	s_nop 0
	global_load_lds_dwordx4 v146, s[72:73]
	s_barrier
	s_waitcnt lgkmcnt(0)
	v_mfma_f32_16x16x32_bf16 v[116:119], v[220:223], v[156:159], v[116:119]
	v_mfma_f32_16x16x32_bf16 v[112:115], v[232:235], v[156:159], v[112:115]
	v_mfma_f32_16x16x32_bf16 v[100:103], v[220:223], v[164:167], v[100:103]
	v_mfma_f32_16x16x32_bf16 v[96:99], v[232:235], v[164:167], v[96:99]
	v_mfma_f32_16x16x32_bf16 v[84:87], v[220:223], v[192:195], v[84:87]
	v_mfma_f32_16x16x32_bf16 v[80:83], v[232:235], v[192:195], v[80:83]
	v_mfma_f32_16x16x32_bf16 v[68:71], v[220:223], v[200:203], v[68:71]
	v_mfma_f32_16x16x32_bf16 v[64:67], v[232:235], v[200:203], v[64:67]
	v_mfma_f32_16x16x32_bf16 v[116:119], v[228:231], v[160:163], v[116:119]
	v_mfma_f32_16x16x32_bf16 v[112:115], v[236:239], v[160:163], v[112:115]
	v_mfma_f32_16x16x32_bf16 v[100:103], v[228:231], v[188:191], v[100:103]
	v_mfma_f32_16x16x32_bf16 v[96:99], v[236:239], v[188:191], v[96:99]
	v_mfma_f32_16x16x32_bf16 v[84:87], v[228:231], v[196:199], v[84:87]
	v_mfma_f32_16x16x32_bf16 v[80:83], v[236:239], v[196:199], v[80:83]
	v_mfma_f32_16x16x32_bf16 v[68:71], v[228:231], v[204:207], v[68:71]
	v_mfma_f32_16x16x32_bf16 v[64:67], v[236:239], v[204:207], v[64:67]
	s_barrier
	s_mov_b32 m0, s83
	ds_read_b128 v[156:159], v217 offset:16384
	ds_read_b128 v[160:163], v217 offset:17408
	ds_read_b128 v[164:167], v217 offset:18432
	ds_read_b128 v[188:191], v217 offset:19456
	ds_read_b128 v[192:195], v217 offset:20480
	ds_read_b128 v[196:199], v217 offset:21504
	ds_read_b128 v[200:203], v217 offset:22528
	ds_read_b128 v[204:207], v217 offset:23552
	global_load_lds_dwordx4 v148, s[74:75]
	s_mov_b32 m0, s84
	s_nop 0
	global_load_lds_dwordx4 v146, s[74:75]
	s_barrier
	s_waitcnt lgkmcnt(0)
	v_mfma_f32_16x16x32_bf16 v[60:63], v[128:131], v[156:159], v[60:63]
	v_mfma_f32_16x16x32_bf16 v[56:59], v[136:139], v[156:159], v[56:59]
	v_mfma_f32_16x16x32_bf16 v[44:47], v[128:131], v[164:167], v[44:47]
	v_mfma_f32_16x16x32_bf16 v[40:43], v[136:139], v[164:167], v[40:43]
	v_mfma_f32_16x16x32_bf16 v[28:31], v[128:131], v[192:195], v[28:31]
	v_mfma_f32_16x16x32_bf16 v[24:27], v[136:139], v[192:195], v[24:27]
	v_mfma_f32_16x16x32_bf16 v[12:15], v[128:131], v[200:203], v[12:15]
	v_mfma_f32_16x16x32_bf16 v[8:11], v[136:139], v[200:203], v[8:11]
	v_mfma_f32_16x16x32_bf16 v[60:63], v[132:135], v[160:163], v[60:63]
	v_mfma_f32_16x16x32_bf16 v[56:59], v[140:143], v[160:163], v[56:59]
	v_mfma_f32_16x16x32_bf16 v[44:47], v[132:135], v[188:191], v[44:47]
	v_mfma_f32_16x16x32_bf16 v[40:43], v[140:143], v[188:191], v[40:43]
	v_mfma_f32_16x16x32_bf16 v[28:31], v[132:135], v[196:199], v[28:31]
	v_mfma_f32_16x16x32_bf16 v[24:27], v[140:143], v[196:199], v[24:27]
	v_mfma_f32_16x16x32_bf16 v[12:15], v[132:135], v[204:207], v[12:15]
	v_mfma_f32_16x16x32_bf16 v[8:11], v[140:143], v[204:207], v[8:11]
	s_barrier
	s_add_u32 s36, s72, 0x40000
	s_addc_u32 s37, s73, 0
	s_add_i32 s27, s27, s81
	s_mov_b32 m0, s27
	s_nop 0
	global_load_lds_dwordx4 v148, s[36:37]
	s_add_i32 m0, s27, 0x2000
	s_nop 0
	global_load_lds_dwordx4 v146, s[36:37]
	s_waitcnt vmcnt(6)
	s_barrier
	v_mfma_f32_16x16x32_bf16 v[52:55], v[220:223], v[156:159], v[52:55]
	v_mfma_f32_16x16x32_bf16 v[48:51], v[232:235], v[156:159], v[48:51]
	v_mfma_f32_16x16x32_bf16 v[36:39], v[220:223], v[164:167], v[36:39]
	v_mfma_f32_16x16x32_bf16 v[32:35], v[232:235], v[164:167], v[32:35]
	v_mfma_f32_16x16x32_bf16 v[20:23], v[220:223], v[192:195], v[20:23]
	v_mfma_f32_16x16x32_bf16 v[16:19], v[232:235], v[192:195], v[16:19]
	v_mfma_f32_16x16x32_bf16 v[4:7], v[220:223], v[200:203], v[4:7]
	v_mfma_f32_16x16x32_bf16 v[0:3], v[232:235], v[200:203], v[0:3]
	v_mfma_f32_16x16x32_bf16 v[52:55], v[228:231], v[160:163], v[52:55]
	v_mfma_f32_16x16x32_bf16 v[48:51], v[236:239], v[160:163], v[48:51]
	v_mfma_f32_16x16x32_bf16 v[36:39], v[228:231], v[188:191], v[36:39]
	v_mfma_f32_16x16x32_bf16 v[32:35], v[236:239], v[188:191], v[32:35]
	v_mfma_f32_16x16x32_bf16 v[20:23], v[228:231], v[196:199], v[20:23]
	v_mfma_f32_16x16x32_bf16 v[16:19], v[236:239], v[196:199], v[16:19]
	v_mfma_f32_16x16x32_bf16 v[4:7], v[228:231], v[204:207], v[4:7]
	v_mfma_f32_16x16x32_bf16 v[0:3], v[236:239], v[204:207], v[0:3]
	s_barrier
	s_add_i32 s27, 0, 0x18000
	v_add_u32_e32 v140, s27, v216
	ds_read_b128 v[128:131], v140
	ds_read_b128 v[132:135], v140 offset:1024
	ds_read_b128 v[136:139], v140 offset:2048
	ds_read_b128 v[140:143], v140 offset:3072
	s_add_u32 s36, s74, 0x40000
	s_addc_u32 s37, s75, 0
	s_mov_b32 m0, s85
	ds_read_b128 v[156:159], v217 offset:32768
	ds_read_b128 v[160:163], v217 offset:33792
	ds_read_b128 v[164:167], v217 offset:34816
	ds_read_b128 v[188:191], v217 offset:35840
	ds_read_b128 v[192:195], v217 offset:36864
	ds_read_b128 v[196:199], v217 offset:37888
	ds_read_b128 v[200:203], v217 offset:38912
	ds_read_b128 v[204:207], v217 offset:39936
	global_load_lds_dwordx4 v148, s[36:37]
	s_mov_b32 m0, s86
	s_nop 0
	global_load_lds_dwordx4 v146, s[36:37]
	s_waitcnt lgkmcnt(8)
	s_barrier
	s_waitcnt lgkmcnt(0)
	v_mfma_f32_16x16x32_bf16 v[124:127], v[128:131], v[156:159], v[124:127]
	v_mfma_f32_16x16x32_bf16 v[120:123], v[136:139], v[156:159], v[120:123]
	v_mfma_f32_16x16x32_bf16 v[108:111], v[128:131], v[164:167], v[108:111]
	v_mfma_f32_16x16x32_bf16 v[104:107], v[136:139], v[164:167], v[104:107]
	v_mfma_f32_16x16x32_bf16 v[92:95], v[128:131], v[192:195], v[92:95]
	v_mfma_f32_16x16x32_bf16 v[88:91], v[136:139], v[192:195], v[88:91]
	v_mfma_f32_16x16x32_bf16 v[76:79], v[128:131], v[200:203], v[76:79]
	v_mfma_f32_16x16x32_bf16 v[72:75], v[136:139], v[200:203], v[72:75]
	v_mfma_f32_16x16x32_bf16 v[124:127], v[132:135], v[160:163], v[124:127]
	v_mfma_f32_16x16x32_bf16 v[120:123], v[140:143], v[160:163], v[120:123]
	v_mfma_f32_16x16x32_bf16 v[108:111], v[132:135], v[188:191], v[108:111]
	v_mfma_f32_16x16x32_bf16 v[104:107], v[140:143], v[188:191], v[104:107]
	v_mfma_f32_16x16x32_bf16 v[92:95], v[132:135], v[196:199], v[92:95]
	v_mfma_f32_16x16x32_bf16 v[88:91], v[140:143], v[196:199], v[88:91]
	v_mfma_f32_16x16x32_bf16 v[76:79], v[132:135], v[204:207], v[76:79]
	v_mfma_f32_16x16x32_bf16 v[72:75], v[140:143], v[204:207], v[72:75]
	s_barrier
	s_add_i32 s35, 0, 0x1c000
	s_add_i32 s27, s27, s81
	v_add_u32_e32 v144, s35, v216
	s_add_u32 s36, s72, s18
	s_addc_u32 s37, s73, s19
	s_mov_b32 m0, s27
	ds_read_b128 v[220:223], v144
	ds_read_b128 v[228:231], v144 offset:1024
	ds_read_b128 v[232:235], v144 offset:2048
	ds_read_b128 v[236:239], v144 offset:3072
	global_load_lds_dwordx4 v148, s[36:37]
	s_add_u32 s36, s72, s18
	s_addc_u32 s37, s73, s19
	s_add_i32 m0, s27, 0x2000
	s_nop 0
	global_load_lds_dwordx4 v146, s[36:37]
	s_barrier
	s_waitcnt lgkmcnt(0)
	v_mfma_f32_16x16x32_bf16 v[116:119], v[220:223], v[156:159], v[116:119]
	v_mfma_f32_16x16x32_bf16 v[112:115], v[232:235], v[156:159], v[112:115]
	v_mfma_f32_16x16x32_bf16 v[100:103], v[220:223], v[164:167], v[100:103]
	v_mfma_f32_16x16x32_bf16 v[96:99], v[232:235], v[164:167], v[96:99]
	v_mfma_f32_16x16x32_bf16 v[84:87], v[220:223], v[192:195], v[84:87]
	v_mfma_f32_16x16x32_bf16 v[80:83], v[232:235], v[192:195], v[80:83]
	v_mfma_f32_16x16x32_bf16 v[68:71], v[220:223], v[200:203], v[68:71]
	v_mfma_f32_16x16x32_bf16 v[64:67], v[232:235], v[200:203], v[64:67]
	v_mfma_f32_16x16x32_bf16 v[116:119], v[228:231], v[160:163], v[116:119]
	v_mfma_f32_16x16x32_bf16 v[112:115], v[236:239], v[160:163], v[112:115]
	v_mfma_f32_16x16x32_bf16 v[100:103], v[228:231], v[188:191], v[100:103]
	v_mfma_f32_16x16x32_bf16 v[96:99], v[236:239], v[188:191], v[96:99]
	v_mfma_f32_16x16x32_bf16 v[84:87], v[228:231], v[196:199], v[84:87]
	v_mfma_f32_16x16x32_bf16 v[80:83], v[236:239], v[196:199], v[80:83]
	v_mfma_f32_16x16x32_bf16 v[68:71], v[228:231], v[204:207], v[68:71]
	v_mfma_f32_16x16x32_bf16 v[64:67], v[236:239], v[204:207], v[64:67]
	s_barrier
	s_mov_b32 m0, s87
	s_add_u32 s36, s74, s18
	s_addc_u32 s37, s75, s19
	ds_read_b128 v[156:159], v217 offset:49152
	ds_read_b128 v[160:163], v217 offset:50176
	ds_read_b128 v[164:167], v217 offset:51200
	ds_read_b128 v[188:191], v217 offset:52224
	ds_read_b128 v[192:195], v217 offset:53248
	ds_read_b128 v[196:199], v217 offset:54272
	ds_read_b128 v[200:203], v217 offset:55296
	ds_read_b128 v[204:207], v217 offset:56320
	global_load_lds_dwordx4 v148, s[36:37]
	s_add_u32 s36, s74, s18
	s_addc_u32 s37, s75, s19
	s_mov_b32 m0, s79
	s_nop 0
	global_load_lds_dwordx4 v146, s[36:37]
	s_barrier
	s_waitcnt lgkmcnt(0)
	v_mfma_f32_16x16x32_bf16 v[60:63], v[128:131], v[156:159], v[60:63]
	v_mfma_f32_16x16x32_bf16 v[56:59], v[136:139], v[156:159], v[56:59]
	v_mfma_f32_16x16x32_bf16 v[44:47], v[128:131], v[164:167], v[44:47]
	v_mfma_f32_16x16x32_bf16 v[40:43], v[136:139], v[164:167], v[40:43]
	v_mfma_f32_16x16x32_bf16 v[28:31], v[128:131], v[192:195], v[28:31]
	v_mfma_f32_16x16x32_bf16 v[24:27], v[136:139], v[192:195], v[24:27]
	v_mfma_f32_16x16x32_bf16 v[12:15], v[128:131], v[200:203], v[12:15]
	v_mfma_f32_16x16x32_bf16 v[8:11], v[136:139], v[200:203], v[8:11]
	v_mfma_f32_16x16x32_bf16 v[60:63], v[132:135], v[160:163], v[60:63]
	v_mfma_f32_16x16x32_bf16 v[56:59], v[140:143], v[160:163], v[56:59]
	v_mfma_f32_16x16x32_bf16 v[44:47], v[132:135], v[188:191], v[44:47]
	v_mfma_f32_16x16x32_bf16 v[40:43], v[140:143], v[188:191], v[40:43]
	v_mfma_f32_16x16x32_bf16 v[28:31], v[132:135], v[196:199], v[28:31]
	v_mfma_f32_16x16x32_bf16 v[24:27], v[140:143], v[196:199], v[24:27]
	v_mfma_f32_16x16x32_bf16 v[12:15], v[132:135], v[204:207], v[12:15]
	v_mfma_f32_16x16x32_bf16 v[8:11], v[140:143], v[204:207], v[8:11]
	s_barrier
	s_add_u32 s36, s72, 0x40080
	s_addc_u32 s37, s73, 0
	s_add_i32 s27, s35, s81
	s_mov_b32 m0, s27
	s_nop 0
	global_load_lds_dwordx4 v148, s[36:37]
	s_add_i32 m0, s27, 0x2000
	s_nop 0
	global_load_lds_dwordx4 v146, s[36:37]
	s_waitcnt vmcnt(6)
	s_barrier
	v_mfma_f32_16x16x32_bf16 v[52:55], v[220:223], v[156:159], v[52:55]
	v_mfma_f32_16x16x32_bf16 v[48:51], v[232:235], v[156:159], v[48:51]
	v_mfma_f32_16x16x32_bf16 v[36:39], v[220:223], v[164:167], v[36:39]
	v_mfma_f32_16x16x32_bf16 v[32:35], v[232:235], v[164:167], v[32:35]
	v_mfma_f32_16x16x32_bf16 v[20:23], v[220:223], v[192:195], v[20:23]
	v_mfma_f32_16x16x32_bf16 v[16:19], v[232:235], v[192:195], v[16:19]
	v_mfma_f32_16x16x32_bf16 v[4:7], v[220:223], v[200:203], v[4:7]
	v_mfma_f32_16x16x32_bf16 v[0:3], v[232:235], v[200:203], v[0:3]
	v_mfma_f32_16x16x32_bf16 v[52:55], v[228:231], v[160:163], v[52:55]
	v_mfma_f32_16x16x32_bf16 v[48:51], v[236:239], v[160:163], v[48:51]
	v_mfma_f32_16x16x32_bf16 v[36:39], v[228:231], v[188:191], v[36:39]
	v_mfma_f32_16x16x32_bf16 v[32:35], v[236:239], v[188:191], v[32:35]
	v_mfma_f32_16x16x32_bf16 v[20:23], v[228:231], v[196:199], v[20:23]
	v_mfma_f32_16x16x32_bf16 v[16:19], v[236:239], v[196:199], v[16:19]
	v_mfma_f32_16x16x32_bf16 v[4:7], v[228:231], v[204:207], v[4:7]
	v_mfma_f32_16x16x32_bf16 v[0:3], v[236:239], v[204:207], v[0:3]
	s_barrier
	s_add_i32 s34, s34, 2
	s_add_u32 s52, s52, 0x100
	s_addc_u32 s53, s53, 0
	s_add_u32 s31, s31, 0x100
	s_addc_u32 s33, s33, 0
	s_cmp_gt_u32 s34, 13
	s_cbranch_scc0 .LBB0_326
	v_lshl_add_u32 v128, s0, 8, v151
	v_readlane_b32 s0, v252, 36
	v_ashrrev_i32_e32 v129, 31, v128
	v_readlane_b32 s1, v252, 37
	v_or_b32_e32 v132, 16, v128
	v_or_b32_e32 v136, 32, v128
	v_lshl_add_u64 v[130:131], v[128:129], 3, s[0:1]
	v_ashrrev_i32_e32 v133, 31, v132
	v_ashrrev_i32_e32 v137, 31, v136
	v_or_b32_e32 v140, 48, v128
	v_lshl_add_u64 v[134:135], v[132:133], 3, s[0:1]
	v_lshl_add_u64 v[138:139], v[136:137], 3, s[0:1]
	v_ashrrev_i32_e32 v141, 31, v140
	global_load_dwordx2 v[202:203], v[130:131], off
	global_load_dwordx2 v[200:201], v[134:135], off
	global_load_dwordx2 v[192:193], v[138:139], off
	global_load_dwordx2 v[166:167], v[130:131], off offset:1024
	v_add_u32_e32 v164, 0x90, v128
	v_add_u32_e32 v158, 0xa0, v128
	v_add_u32_e32 v156, 0xb0, v128
	v_lshl_add_u64 v[142:143], v[140:141], 3, s[0:1]
	v_ashrrev_i32_e32 v165, 31, v164
	v_ashrrev_i32_e32 v159, 31, v158
	v_ashrrev_i32_e32 v157, 31, v156
	v_lshl_add_u64 v[130:131], v[164:165], 3, s[0:1]
	v_lshl_add_u64 v[134:135], v[158:159], 3, s[0:1]
	v_lshl_add_u64 v[138:139], v[156:157], 3, s[0:1]
	global_load_dwordx2 v[196:197], v[142:143], off
	global_load_dwordx2 v[188:189], v[130:131], off
	global_load_dwordx2 v[162:163], v[134:135], off
	global_load_dwordx2 v[160:161], v[138:139], off
	v_add_u32_e32 v168, 0x80, v128
	s_mov_b64 s[0:1], -1
	s_cmp_gt_u32 s10, 1
	v_lshlrev_b32_e32 v144, 1, v150
	v_ashrrev_i32_e32 v169, 31, v168
	v_lshlrev_b64 v[204:205], 10, v[128:129]
	v_lshlrev_b64 v[198:199], 10, v[132:133]
	v_lshlrev_b64 v[194:195], 10, v[136:137]
	v_lshlrev_b64 v[190:191], 10, v[140:141]
	s_waitcnt vmcnt(0)
	v_ffbh_u32_e32 v222, v203
	v_ffbh_u32_e32 v221, v201
	v_ffbh_u32_e32 v220, v193
	v_ffbh_u32_e32 v219, v197
	s_cbranch_scc0 .LBB0_329
	s_cmp_lt_u32 s10, 4
	s_cselect_b64 vcc, -1, 0
	v_readlane_b32 s56, v254, 23
	s_and_b64 s[0:1], vcc, exec
	v_readlane_b32 s70, v254, 37
	v_readlane_b32 s36, v252, 15
	v_readlane_b32 s71, v254, 38
	v_readlane_b32 s37, v252, 16
	s_cselect_b32 s0, s70, s36
	s_mov_b32 s11, 0x4400000
	v_readlane_b32 s30, v254, 62
	s_cselect_b32 s1, s71, s37
	s_cselect_b32 s11, s11, 0x4800000
	v_readlane_b32 s31, v254, 63
	s_add_u32 s0, s0, s30
	s_addc_u32 s1, s1, s31
	global_load_dwordx4 v[136:139], v218, s[0:1] offset:16
	global_load_dwordx4 v[140:143], v218, s[0:1]
	global_load_dwordx4 v[128:131], v218, s[0:1] offset:144
	global_load_dwordx4 v[132:135], v218, s[0:1] offset:128
	v_and_b32_e32 v177, 64, v214
	v_xor_b32_e32 v176, 16, v214
	v_add_u32_e32 v177, 64, v177
	v_cndmask_b32_e32 v223, 1.0, v215, vcc
	v_cmp_lt_i32_e32 vcc, v176, v177
	v_readlane_b32 s9, v254, 52
	s_add_u32 s11, s9, s11
	v_cndmask_b32_e32 v176, v214, v176, vcc
	v_lshlrev_b32_e32 v225, 2, v176
	v_xor_b32_e32 v176, 32, v214
	v_cmp_lt_i32_e32 vcc, v176, v177
	v_readlane_b32 s9, v254, 61
	s_addc_u32 s25, s9, 0
	v_cndmask_b32_e32 v176, v214, v176, vcc
	v_lshlrev_b32_e32 v224, 2, v176
	v_min_u32_e32 v176, 32, v222
	v_lshlrev_b64 v[228:229], v176, v[202:203]
	v_min_u32_e32 v177, 1, v228
	v_or_b32_e32 v177, v229, v177
	v_cvt_f32_u32_e32 v177, v177
	v_sub_u32_e32 v176, 32, v176
	s_lshl_b32 s0, s10, 9
	s_and_b32 s0, s0, 0x200
	v_ldexp_f32 v176, v177, v176
	v_mul_f32_e32 v176, 0x35800000, v176
	v_fmamk_f32 v176, v176, 0x3a800000, v210
	s_add_u32 s0, s11, s0
	v_rsq_f32_e32 v176, v176
	s_addc_u32 s1, s25, 0
	v_lshl_add_u64 v[206:207], s[0:1], 0, v[144:145]
	v_readlane_b32 s48, v252, 27
	v_mov_b32_e32 v228, v176
	v_pk_mul_f32 v[230:231], v[124:125], v[228:229] op_sel_hi:[1,0]
	v_pk_mul_f32 v[232:233], v[126:127], v[228:229] op_sel_hi:[1,0]
	v_pk_mul_f32 v[236:237], v[230:231], v[230:231]
	v_pk_mul_f32 v[234:235], v[232:233], v[232:233]
	v_pk_mul_f32 v[250:251], v[114:115], v[228:229] op_sel_hi:[1,0]
	v_pk_mov_b32 v[238:239], v[236:237], v[234:235] op_sel:[1,0]
	v_mov_b32_e32 v237, v235
	v_pk_add_f32 v[234:235], v[238:239], v[236:237]
	v_pk_mul_f32 v[236:237], v[120:121], v[228:229] op_sel_hi:[1,0]
	v_pk_mul_f32 v[238:239], v[122:123], v[228:229] op_sel_hi:[1,0]
	v_pk_mul_f32 v[242:243], v[236:237], v[236:237]
	v_pk_mul_f32 v[240:241], v[238:239], v[238:239]
	v_pk_add_f32 v[234:235], v[234:235], v[234:235] op_sel_hi:[0,1]
	v_pk_mov_b32 v[244:245], v[242:243], v[240:241] op_sel:[1,0]
	v_mov_b32_e32 v243, v241
	v_pk_add_f32 v[240:241], v[244:245], v[242:243]
	v_pk_mul_f32 v[244:245], v[116:117], v[228:229] op_sel_hi:[1,0]
	v_pk_mul_f32 v[242:243], v[118:119], v[228:229] op_sel_hi:[1,0]
	v_mul_f32_e32 v234, v244, v244
	v_pk_fma_f32 v[246:247], v[244:245], v[244:245], v[234:235] op_sel_hi:[1,1,0]
	v_mul_f32_e32 v234, v242, v242
	v_pk_add_f32 v[240:241], v[240:241], v[240:241] op_sel_hi:[0,1]
	v_pk_fma_f32 v[248:249], v[242:243], v[242:243], v[234:235] op_sel_hi:[1,1,0]
	v_pk_mul_f32 v[176:177], v[112:113], v[228:229] op_sel_hi:[1,0]
	v_mul_f32_e32 v234, v250, v250
	v_mul_f32_e32 v246, v176, v176
	v_mul_f32_e32 v248, v177, v177
	v_mul_f32_e32 v240, v251, v251
	v_pk_add_f32 v[228:229], v[246:247], v[248:249]
	v_pk_add_f32 v[234:235], v[234:235], v[240:241]
	v_lshl_add_u64 v[240:241], v[206:207], 0, v[204:205]
	v_pk_add_f32 v[228:229], v[228:229], v[234:235]
	v_readlane_b32 s57, v254, 24
	v_add_f32_e32 v228, v228, v229
	ds_bpermute_b32 v229, v225, v228
	v_readlane_b32 s58, v254, 25
	v_readlane_b32 s59, v254, 26
	v_readlane_b32 s60, v254, 27
	v_readlane_b32 s61, v254, 28
	s_waitcnt lgkmcnt(0)
	v_add_f32_e32 v228, v228, v229
	ds_bpermute_b32 v229, v224, v228
	v_readlane_b32 s62, v254, 29
	v_readlane_b32 s63, v254, 30
	v_readlane_b32 s64, v254, 31
	v_readlane_b32 s65, v254, 32
	s_waitcnt lgkmcnt(0)
	v_add_f32_e32 v228, v228, v229
	v_fmamk_f32 v228, v228, 0x3c800000, v210
	v_readlane_b32 s66, v254, 33
	v_rsq_f32_e32 v228, v228
	v_readlane_b32 s67, v254, 34
	v_readlane_b32 s68, v254, 35
	v_readlane_b32 s69, v254, 36
	v_mul_f32_e32 v234, v223, v228
	v_pk_mul_f32 v[228:229], v[230:231], v[234:235] op_sel_hi:[1,0]
	v_pk_mul_f32 v[230:231], v[232:233], v[234:235] op_sel_hi:[1,0]
	s_waitcnt vmcnt(2)
	v_pk_mul_f32 v[228:229], v[140:141], v[228:229]
	v_pk_mul_f32 v[230:231], v[142:143], v[230:231]
	v_pk_mul_f32 v[232:233], v[236:237], v[234:235] op_sel_hi:[1,0]
	v_pk_mul_f32 v[236:237], v[238:239], v[234:235] op_sel_hi:[1,0]
	v_cvt_pk_bf16_f32 v228, v228, v229
	v_cvt_pk_bf16_f32 v229, v230, v231
	v_pk_mul_f32 v[232:233], v[136:137], v[232:233]
	v_pk_mul_f32 v[236:237], v[138:139], v[236:237]
	v_cvt_pk_bf16_f32 v230, v232, v233
	v_pk_mul_f32 v[176:177], v[176:177], v[234:235] op_sel_hi:[1,0]
	v_cvt_pk_bf16_f32 v231, v236, v237
	global_store_dwordx4 v[240:241], v[228:231], off
	v_pk_mul_f32 v[232:233], v[250:251], v[234:235] op_sel_hi:[1,0]
	s_waitcnt vmcnt(2)
	v_pk_mul_f32 v[176:177], v[128:129], v[176:177]
	v_pk_mul_f32 v[228:229], v[244:245], v[234:235] op_sel_hi:[1,0]
	v_pk_mul_f32 v[230:231], v[242:243], v[234:235] op_sel_hi:[1,0]
	s_waitcnt vmcnt(1)
	v_pk_mul_f32 v[228:229], v[132:133], v[228:229]
	v_pk_mul_f32 v[230:231], v[134:135], v[230:231]
	v_cvt_pk_bf16_f32 v228, v228, v229
	v_pk_mul_f32 v[232:233], v[130:131], v[232:233]
	v_cvt_pk_bf16_f32 v229, v230, v231
	v_cvt_pk_bf16_f32 v230, v176, v177
	s_nop 1
	v_readlane_b32 s38, v252, 17
	v_cvt_pk_bf16_f32 v231, v232, v233
	s_nop 1
	global_store_dwordx4 v[240:241], v[228:231], off offset:64
	v_readlane_b32 s39, v252, 18
	v_readlane_b32 s40, v252, 19
	v_min_u32_e32 v228, 32, v221
	v_lshlrev_b64 v[176:177], v228, v[200:201]
	v_min_u32_e32 v176, 1, v176
	v_or_b32_e32 v176, v177, v176
	v_cvt_f32_u32_e32 v176, v176
	v_sub_u32_e32 v177, 32, v228
	v_readlane_b32 s41, v252, 20
	v_readlane_b32 s42, v252, 21
	v_ldexp_f32 v176, v176, v177
	v_mul_f32_e32 v176, 0x35800000, v176
	v_fmamk_f32 v176, v176, 0x3a800000, v210
	v_readlane_b32 s43, v252, 22
	v_rsq_f32_e32 v176, v176
	v_readlane_b32 s44, v252, 23
	v_readlane_b32 s45, v252, 24
	v_readlane_b32 s46, v252, 25
	v_pk_mul_f32 v[228:229], v[108:109], v[176:177] op_sel_hi:[1,0]
	v_pk_mul_f32 v[230:231], v[110:111], v[176:177] op_sel_hi:[1,0]
	v_pk_mul_f32 v[234:235], v[228:229], v[228:229]
	v_pk_mul_f32 v[232:233], v[230:231], v[230:231]
	v_pk_mul_f32 v[248:249], v[98:99], v[176:177] op_sel_hi:[1,0]
	v_pk_mov_b32 v[236:237], v[234:235], v[232:233] op_sel:[1,0]
	v_mov_b32_e32 v235, v233
	v_pk_add_f32 v[232:233], v[236:237], v[234:235]
	v_pk_mul_f32 v[234:235], v[104:105], v[176:177] op_sel_hi:[1,0]
	v_pk_mul_f32 v[236:237], v[106:107], v[176:177] op_sel_hi:[1,0]
	v_pk_mul_f32 v[240:241], v[234:235], v[234:235]
	v_pk_mul_f32 v[238:239], v[236:237], v[236:237]
	v_pk_add_f32 v[232:233], v[232:233], v[232:233] op_sel_hi:[0,1]
	v_pk_mov_b32 v[242:243], v[240:241], v[238:239] op_sel:[1,0]
	v_mov_b32_e32 v241, v239
	v_pk_add_f32 v[238:239], v[242:243], v[240:241]
	v_pk_mul_f32 v[242:243], v[100:101], v[176:177] op_sel_hi:[1,0]
	v_pk_mul_f32 v[240:241], v[102:103], v[176:177] op_sel_hi:[1,0]
	v_mul_f32_e32 v232, v242, v242
	v_pk_fma_f32 v[244:245], v[242:243], v[242:243], v[232:233] op_sel_hi:[1,1,0]
	v_mul_f32_e32 v232, v240, v240
	v_pk_add_f32 v[238:239], v[238:239], v[238:239] op_sel_hi:[0,1]
	v_pk_fma_f32 v[246:247], v[240:241], v[240:241], v[232:233] op_sel_hi:[1,1,0]
	v_pk_mul_f32 v[176:177], v[96:97], v[176:177] op_sel_hi:[1,0]
	v_mul_f32_e32 v232, v248, v248
	v_mul_f32_e32 v244, v176, v176
	v_mul_f32_e32 v246, v177, v177
	v_mul_f32_e32 v238, v249, v249
	v_pk_add_f32 v[244:245], v[244:245], v[246:247]
	v_pk_add_f32 v[232:233], v[232:233], v[238:239]
	v_lshl_add_u64 v[238:239], v[206:207], 0, v[198:199]
	v_pk_add_f32 v[232:233], v[244:245], v[232:233]
	v_readlane_b32 s47, v252, 26
	v_add_f32_e32 v232, v232, v233
	ds_bpermute_b32 v233, v225, v232
	v_readlane_b32 s49, v252, 28
	v_readlane_b32 s50, v252, 29
	v_readlane_b32 s51, v252, 30
	v_readlane_b32 s48, v252, 40
	s_waitcnt lgkmcnt(0)
	v_add_f32_e32 v232, v232, v233
	ds_bpermute_b32 v233, v224, v232
	s_mov_b64 s[0:1], 0
	s_waitcnt lgkmcnt(0)
	v_add_f32_e32 v232, v232, v233
	v_fmamk_f32 v232, v232, 0x3c800000, v210
	s_nop 0
	v_rsq_f32_e32 v232, v232
	s_nop 0
	v_mul_f32_e32 v232, v223, v232
	v_pk_mul_f32 v[228:229], v[228:229], v[232:233] op_sel_hi:[1,0]
	v_pk_mul_f32 v[230:231], v[230:231], v[232:233] op_sel_hi:[1,0]
	v_pk_mul_f32 v[228:229], v[140:141], v[228:229]
	v_pk_mul_f32 v[230:231], v[142:143], v[230:231]
	v_pk_mul_f32 v[234:235], v[234:235], v[232:233] op_sel_hi:[1,0]
	v_pk_mul_f32 v[236:237], v[236:237], v[232:233] op_sel_hi:[1,0]
	v_cvt_pk_bf16_f32 v228, v228, v229
	v_cvt_pk_bf16_f32 v229, v230, v231
	v_pk_mul_f32 v[234:235], v[136:137], v[234:235]
	v_pk_mul_f32 v[236:237], v[138:139], v[236:237]
	v_cvt_pk_bf16_f32 v230, v234, v235
	v_pk_mul_f32 v[176:177], v[176:177], v[232:233] op_sel_hi:[1,0]
	v_cvt_pk_bf16_f32 v231, v236, v237
	global_store_dwordx4 v[238:239], v[228:231], off
	v_pk_mul_f32 v[176:177], v[128:129], v[176:177]
	s_nop 0
	v_pk_mul_f32 v[228:229], v[242:243], v[232:233] op_sel_hi:[1,0]
	v_pk_mul_f32 v[230:231], v[240:241], v[232:233] op_sel_hi:[1,0]
	v_pk_mul_f32 v[228:229], v[132:133], v[228:229]
	v_pk_mul_f32 v[230:231], v[134:135], v[230:231]
	v_pk_mul_f32 v[232:233], v[248:249], v[232:233] op_sel_hi:[1,0]
	v_cvt_pk_bf16_f32 v228, v228, v229
	v_cvt_pk_bf16_f32 v229, v230, v231
	v_cvt_pk_bf16_f32 v230, v176, v177
	s_nop 0
	v_pk_mul_f32 v[232:233], v[130:131], v[232:233]
	s_nop 0
	v_cvt_pk_bf16_f32 v231, v232, v233
	global_store_dwordx4 v[238:239], v[228:231], off offset:64
	s_nop 1
	v_min_u32_e32 v228, 32, v220
	v_lshlrev_b64 v[176:177], v228, v[192:193]
	v_min_u32_e32 v176, 1, v176
	v_or_b32_e32 v176, v177, v176
	v_cvt_f32_u32_e32 v176, v176
	v_sub_u32_e32 v177, 32, v228
	v_ldexp_f32 v176, v176, v177
	v_mul_f32_e32 v176, 0x35800000, v176
	v_fmamk_f32 v176, v176, 0x3a800000, v210
	s_nop 0
	v_rsq_f32_e32 v176, v176
	s_nop 0
	v_pk_mul_f32 v[228:229], v[92:93], v[176:177] op_sel_hi:[1,0]
	v_pk_mul_f32 v[230:231], v[94:95], v[176:177] op_sel_hi:[1,0]
	v_pk_mul_f32 v[234:235], v[228:229], v[228:229]
	v_pk_mul_f32 v[232:233], v[230:231], v[230:231]
	v_pk_mul_f32 v[248:249], v[82:83], v[176:177] op_sel_hi:[1,0]
	v_pk_mov_b32 v[236:237], v[234:235], v[232:233] op_sel:[1,0]
	v_mov_b32_e32 v235, v233
	v_pk_add_f32 v[232:233], v[236:237], v[234:235]
	v_pk_mul_f32 v[234:235], v[88:89], v[176:177] op_sel_hi:[1,0]
	v_pk_mul_f32 v[236:237], v[90:91], v[176:177] op_sel_hi:[1,0]
	v_pk_mul_f32 v[240:241], v[234:235], v[234:235]
	v_pk_mul_f32 v[238:239], v[236:237], v[236:237]
	v_pk_add_f32 v[232:233], v[232:233], v[232:233] op_sel_hi:[0,1]
	v_pk_mov_b32 v[242:243], v[240:241], v[238:239] op_sel:[1,0]
	v_mov_b32_e32 v241, v239
	v_pk_add_f32 v[238:239], v[242:243], v[240:241]
	v_pk_mul_f32 v[242:243], v[84:85], v[176:177] op_sel_hi:[1,0]
	v_pk_mul_f32 v[240:241], v[86:87], v[176:177] op_sel_hi:[1,0]
	v_mul_f32_e32 v232, v242, v242
	v_pk_fma_f32 v[244:245], v[242:243], v[242:243], v[232:233] op_sel_hi:[1,1,0]
	v_mul_f32_e32 v232, v240, v240
	v_pk_add_f32 v[238:239], v[238:239], v[238:239] op_sel_hi:[0,1]
	v_pk_fma_f32 v[246:247], v[240:241], v[240:241], v[232:233] op_sel_hi:[1,1,0]
	v_pk_mul_f32 v[176:177], v[80:81], v[176:177] op_sel_hi:[1,0]
	v_mul_f32_e32 v232, v248, v248
	v_mul_f32_e32 v244, v176, v176
	v_mul_f32_e32 v246, v177, v177
	v_mul_f32_e32 v238, v249, v249
	v_pk_add_f32 v[244:245], v[244:245], v[246:247]
	v_pk_add_f32 v[232:233], v[232:233], v[238:239]
	v_lshl_add_u64 v[238:239], v[206:207], 0, v[194:195]
	v_pk_add_f32 v[232:233], v[244:245], v[232:233]
	s_nop 0
	v_add_f32_e32 v232, v232, v233
	ds_bpermute_b32 v233, v225, v232
	s_waitcnt lgkmcnt(0)
	v_add_f32_e32 v232, v232, v233
	ds_bpermute_b32 v233, v224, v232
	s_waitcnt lgkmcnt(0)
	v_add_f32_e32 v232, v232, v233
	v_fmamk_f32 v232, v232, 0x3c800000, v210
	s_nop 0
	v_rsq_f32_e32 v232, v232
	s_nop 0
	v_mul_f32_e32 v232, v223, v232
	v_pk_mul_f32 v[228:229], v[228:229], v[232:233] op_sel_hi:[1,0]
	v_pk_mul_f32 v[230:231], v[230:231], v[232:233] op_sel_hi:[1,0]
	v_pk_mul_f32 v[228:229], v[140:141], v[228:229]
	v_pk_mul_f32 v[230:231], v[142:143], v[230:231]
	v_pk_mul_f32 v[234:235], v[234:235], v[232:233] op_sel_hi:[1,0]
	v_pk_mul_f32 v[236:237], v[236:237], v[232:233] op_sel_hi:[1,0]
	v_cvt_pk_bf16_f32 v228, v228, v229
	v_cvt_pk_bf16_f32 v229, v230, v231
	v_pk_mul_f32 v[234:235], v[136:137], v[234:235]
	v_pk_mul_f32 v[236:237], v[138:139], v[236:237]
	v_cvt_pk_bf16_f32 v230, v234, v235
	v_pk_mul_f32 v[176:177], v[176:177], v[232:233] op_sel_hi:[1,0]
	v_cvt_pk_bf16_f32 v231, v236, v237
	global_store_dwordx4 v[238:239], v[228:231], off
	v_pk_mul_f32 v[176:177], v[128:129], v[176:177]
	s_nop 0
	v_pk_mul_f32 v[228:229], v[242:243], v[232:233] op_sel_hi:[1,0]
	v_pk_mul_f32 v[230:231], v[240:241], v[232:233] op_sel_hi:[1,0]
	v_pk_mul_f32 v[228:229], v[132:133], v[228:229]
	v_pk_mul_f32 v[230:231], v[134:135], v[230:231]
	v_pk_mul_f32 v[232:233], v[248:249], v[232:233] op_sel_hi:[1,0]
	v_cvt_pk_bf16_f32 v228, v228, v229
	v_cvt_pk_bf16_f32 v229, v230, v231
	v_cvt_pk_bf16_f32 v230, v176, v177
	s_nop 0
	v_pk_mul_f32 v[232:233], v[130:131], v[232:233]
	s_nop 0
	v_cvt_pk_bf16_f32 v231, v232, v233
	global_store_dwordx4 v[238:239], v[228:231], off offset:64
	s_nop 1
	v_min_u32_e32 v228, 32, v219
	v_lshlrev_b64 v[176:177], v228, v[196:197]
	v_min_u32_e32 v176, 1, v176
	v_or_b32_e32 v176, v177, v176
	v_cvt_f32_u32_e32 v176, v176
	v_sub_u32_e32 v177, 32, v228
	v_ldexp_f32 v176, v176, v177
	v_mul_f32_e32 v176, 0x35800000, v176
	v_fmamk_f32 v176, v176, 0x3a800000, v210
	s_nop 0
	v_rsq_f32_e32 v176, v176
	s_nop 0
	v_pk_mul_f32 v[228:229], v[76:77], v[176:177] op_sel_hi:[1,0]
	v_pk_mul_f32 v[230:231], v[78:79], v[176:177] op_sel_hi:[1,0]
	v_pk_mul_f32 v[234:235], v[228:229], v[228:229]
	v_pk_mul_f32 v[232:233], v[230:231], v[230:231]
	v_pk_mul_f32 v[248:249], v[66:67], v[176:177] op_sel_hi:[1,0]
	v_pk_mov_b32 v[236:237], v[234:235], v[232:233] op_sel:[1,0]
	v_mov_b32_e32 v235, v233
	v_pk_add_f32 v[232:233], v[236:237], v[234:235]
	v_pk_mul_f32 v[234:235], v[72:73], v[176:177] op_sel_hi:[1,0]
	v_pk_mul_f32 v[236:237], v[74:75], v[176:177] op_sel_hi:[1,0]
	v_pk_mul_f32 v[240:241], v[234:235], v[234:235]
	v_pk_mul_f32 v[238:239], v[236:237], v[236:237]
	v_pk_add_f32 v[232:233], v[232:233], v[232:233] op_sel_hi:[0,1]
	v_pk_mov_b32 v[242:243], v[240:241], v[238:239] op_sel:[1,0]
	v_mov_b32_e32 v241, v239
	v_pk_add_f32 v[238:239], v[242:243], v[240:241]
	v_pk_mul_f32 v[242:243], v[68:69], v[176:177] op_sel_hi:[1,0]
	v_pk_mul_f32 v[240:241], v[70:71], v[176:177] op_sel_hi:[1,0]
	v_mul_f32_e32 v232, v242, v242
	v_pk_fma_f32 v[244:245], v[242:243], v[242:243], v[232:233] op_sel_hi:[1,1,0]
	v_mul_f32_e32 v232, v240, v240
	v_pk_add_f32 v[238:239], v[238:239], v[238:239] op_sel_hi:[0,1]
	v_pk_fma_f32 v[246:247], v[240:241], v[240:241], v[232:233] op_sel_hi:[1,1,0]
	v_pk_mul_f32 v[176:177], v[64:65], v[176:177] op_sel_hi:[1,0]
	v_mul_f32_e32 v232, v248, v248
	v_mul_f32_e32 v244, v176, v176
	v_mul_f32_e32 v246, v177, v177
	v_mul_f32_e32 v238, v249, v249
	v_pk_add_f32 v[244:245], v[244:245], v[246:247]
	v_pk_add_f32 v[232:233], v[232:233], v[238:239]
	v_lshl_add_u64 v[238:239], v[206:207], 0, v[190:191]
	v_pk_add_f32 v[232:233], v[244:245], v[232:233]
	s_nop 0
	v_add_f32_e32 v232, v232, v233
	ds_bpermute_b32 v233, v225, v232
	s_waitcnt lgkmcnt(0)
	v_add_f32_e32 v232, v232, v233
	ds_bpermute_b32 v233, v224, v232
	s_waitcnt lgkmcnt(0)
	v_add_f32_e32 v232, v232, v233
	v_fmamk_f32 v232, v232, 0x3c800000, v210
	s_nop 0
	v_rsq_f32_e32 v232, v232
	s_nop 0
	v_mul_f32_e32 v232, v223, v232
	v_pk_mul_f32 v[228:229], v[228:229], v[232:233] op_sel_hi:[1,0]
	v_pk_mul_f32 v[230:231], v[230:231], v[232:233] op_sel_hi:[1,0]
	v_pk_mul_f32 v[228:229], v[140:141], v[228:229]
	v_pk_mul_f32 v[230:231], v[142:143], v[230:231]
	v_pk_mul_f32 v[234:235], v[234:235], v[232:233] op_sel_hi:[1,0]
	v_pk_mul_f32 v[236:237], v[236:237], v[232:233] op_sel_hi:[1,0]
	v_pk_mul_f32 v[234:235], v[136:137], v[234:235]
	v_pk_mul_f32 v[236:237], v[138:139], v[236:237]
	v_cvt_pk_bf16_f32 v228, v228, v229
	v_cvt_pk_bf16_f32 v229, v230, v231
	v_cvt_pk_bf16_f32 v230, v234, v235
	v_pk_mul_f32 v[176:177], v[176:177], v[232:233] op_sel_hi:[1,0]
	v_cvt_pk_bf16_f32 v231, v236, v237
	global_store_dwordx4 v[238:239], v[228:231], off
	v_pk_mul_f32 v[176:177], v[128:129], v[176:177]
	s_nop 0
	v_pk_mul_f32 v[228:229], v[242:243], v[232:233] op_sel_hi:[1,0]
	v_pk_mul_f32 v[230:231], v[240:241], v[232:233] op_sel_hi:[1,0]
	v_pk_mul_f32 v[228:229], v[132:133], v[228:229]
	v_pk_mul_f32 v[230:231], v[134:135], v[230:231]
	v_pk_mul_f32 v[232:233], v[248:249], v[232:233] op_sel_hi:[1,0]
	v_cvt_pk_bf16_f32 v228, v228, v229
	v_cvt_pk_bf16_f32 v229, v230, v231
	v_cvt_pk_bf16_f32 v230, v176, v177
	v_ffbh_u32_e32 v176, v167
	v_pk_mul_f32 v[232:233], v[130:131], v[232:233]
	s_nop 0
	v_cvt_pk_bf16_f32 v231, v232, v233
	global_store_dwordx4 v[238:239], v[228:231], off offset:64
	s_nop 1
	v_min_u32_e32 v228, 32, v176
	v_lshlrev_b64 v[176:177], v228, v[166:167]
	v_min_u32_e32 v176, 1, v176
	v_or_b32_e32 v176, v177, v176
	v_cvt_f32_u32_e32 v176, v176
	v_sub_u32_e32 v177, 32, v228
	v_ldexp_f32 v176, v176, v177
	v_mul_f32_e32 v176, 0x35800000, v176
	v_fmamk_f32 v176, v176, 0x3a800000, v210
	s_nop 0
	v_rsq_f32_e32 v176, v176
	s_nop 0
	v_pk_mul_f32 v[228:229], v[60:61], v[176:177] op_sel_hi:[1,0]
	v_pk_mul_f32 v[230:231], v[62:63], v[176:177] op_sel_hi:[1,0]
	v_pk_mul_f32 v[234:235], v[228:229], v[228:229]
	v_pk_mul_f32 v[232:233], v[230:231], v[230:231]
	v_pk_mul_f32 v[248:249], v[50:51], v[176:177] op_sel_hi:[1,0]
	v_pk_mov_b32 v[236:237], v[234:235], v[232:233] op_sel:[1,0]
	v_mov_b32_e32 v235, v233
	v_pk_add_f32 v[232:233], v[236:237], v[234:235]
	v_pk_mul_f32 v[234:235], v[56:57], v[176:177] op_sel_hi:[1,0]
	v_pk_mul_f32 v[236:237], v[58:59], v[176:177] op_sel_hi:[1,0]
	v_pk_mul_f32 v[240:241], v[234:235], v[234:235]
	v_pk_mul_f32 v[238:239], v[236:237], v[236:237]
	v_pk_add_f32 v[232:233], v[232:233], v[232:233] op_sel_hi:[0,1]
	v_pk_mov_b32 v[242:243], v[240:241], v[238:239] op_sel:[1,0]
	v_mov_b32_e32 v241, v239
	v_pk_add_f32 v[238:239], v[242:243], v[240:241]
	v_pk_mul_f32 v[242:243], v[52:53], v[176:177] op_sel_hi:[1,0]
	v_pk_mul_f32 v[240:241], v[54:55], v[176:177] op_sel_hi:[1,0]
	v_mul_f32_e32 v232, v242, v242
	v_pk_fma_f32 v[244:245], v[242:243], v[242:243], v[232:233] op_sel_hi:[1,1,0]
	v_mul_f32_e32 v232, v240, v240
	v_pk_add_f32 v[238:239], v[238:239], v[238:239] op_sel_hi:[0,1]
	v_pk_fma_f32 v[246:247], v[240:241], v[240:241], v[232:233] op_sel_hi:[1,1,0]
	v_pk_mul_f32 v[176:177], v[48:49], v[176:177] op_sel_hi:[1,0]
	v_mul_f32_e32 v232, v248, v248
	v_mul_f32_e32 v244, v176, v176
	v_mul_f32_e32 v246, v177, v177
	v_mul_f32_e32 v238, v249, v249
	v_pk_add_f32 v[244:245], v[244:245], v[246:247]
	v_pk_add_f32 v[232:233], v[232:233], v[238:239]
	v_lshlrev_b64 v[238:239], 10, v[168:169]
	v_pk_add_f32 v[232:233], v[244:245], v[232:233]
	v_lshl_add_u64 v[238:239], v[206:207], 0, v[238:239]
	v_add_f32_e32 v232, v232, v233
	ds_bpermute_b32 v233, v225, v232
	s_waitcnt lgkmcnt(0)
	v_add_f32_e32 v232, v232, v233
	ds_bpermute_b32 v233, v224, v232
	s_waitcnt lgkmcnt(0)
	v_add_f32_e32 v232, v232, v233
	v_fmamk_f32 v232, v232, 0x3c800000, v210
	s_nop 0
	v_rsq_f32_e32 v232, v232
	s_nop 0
	v_mul_f32_e32 v232, v223, v232
	v_pk_mul_f32 v[228:229], v[228:229], v[232:233] op_sel_hi:[1,0]
	v_pk_mul_f32 v[230:231], v[230:231], v[232:233] op_sel_hi:[1,0]
	v_pk_mul_f32 v[228:229], v[140:141], v[228:229]
	v_pk_mul_f32 v[230:231], v[142:143], v[230:231]
	v_pk_mul_f32 v[234:235], v[234:235], v[232:233] op_sel_hi:[1,0]
	v_pk_mul_f32 v[236:237], v[236:237], v[232:233] op_sel_hi:[1,0]
	v_pk_mul_f32 v[234:235], v[136:137], v[234:235]
	v_pk_mul_f32 v[236:237], v[138:139], v[236:237]
	v_cvt_pk_bf16_f32 v228, v228, v229
	v_cvt_pk_bf16_f32 v229, v230, v231
	v_cvt_pk_bf16_f32 v230, v234, v235
	v_pk_mul_f32 v[176:177], v[176:177], v[232:233] op_sel_hi:[1,0]
	v_cvt_pk_bf16_f32 v231, v236, v237
	global_store_dwordx4 v[238:239], v[228:231], off
	v_pk_mul_f32 v[176:177], v[128:129], v[176:177]
	s_nop 0
	v_pk_mul_f32 v[228:229], v[242:243], v[232:233] op_sel_hi:[1,0]
	v_pk_mul_f32 v[230:231], v[240:241], v[232:233] op_sel_hi:[1,0]
	v_pk_mul_f32 v[228:229], v[132:133], v[228:229]
	v_pk_mul_f32 v[230:231], v[134:135], v[230:231]
	v_pk_mul_f32 v[232:233], v[248:249], v[232:233] op_sel_hi:[1,0]
	v_cvt_pk_bf16_f32 v228, v228, v229
	v_cvt_pk_bf16_f32 v229, v230, v231
	v_cvt_pk_bf16_f32 v230, v176, v177
	v_ffbh_u32_e32 v176, v189
	v_pk_mul_f32 v[232:233], v[130:131], v[232:233]
	s_nop 0
	v_cvt_pk_bf16_f32 v231, v232, v233
	global_store_dwordx4 v[238:239], v[228:231], off offset:64
	s_nop 1
	v_min_u32_e32 v228, 32, v176
	v_lshlrev_b64 v[176:177], v228, v[188:189]
	v_min_u32_e32 v176, 1, v176
	v_or_b32_e32 v176, v177, v176
	v_cvt_f32_u32_e32 v176, v176
	v_sub_u32_e32 v177, 32, v228
	v_ldexp_f32 v176, v176, v177
	v_mul_f32_e32 v176, 0x35800000, v176
	v_fmamk_f32 v176, v176, 0x3a800000, v210
	s_nop 0
	v_rsq_f32_e32 v176, v176
	s_nop 0
	v_pk_mul_f32 v[228:229], v[44:45], v[176:177] op_sel_hi:[1,0]
	v_pk_mul_f32 v[230:231], v[46:47], v[176:177] op_sel_hi:[1,0]
	v_pk_mul_f32 v[234:235], v[228:229], v[228:229]
	v_pk_mul_f32 v[232:233], v[230:231], v[230:231]
	v_pk_mul_f32 v[248:249], v[34:35], v[176:177] op_sel_hi:[1,0]
	v_pk_mov_b32 v[236:237], v[234:235], v[232:233] op_sel:[1,0]
	v_mov_b32_e32 v235, v233
	v_pk_add_f32 v[232:233], v[236:237], v[234:235]
	v_pk_mul_f32 v[234:235], v[40:41], v[176:177] op_sel_hi:[1,0]
	v_pk_mul_f32 v[236:237], v[42:43], v[176:177] op_sel_hi:[1,0]
	v_pk_mul_f32 v[240:241], v[234:235], v[234:235]
	v_pk_mul_f32 v[238:239], v[236:237], v[236:237]
	v_pk_add_f32 v[232:233], v[232:233], v[232:233] op_sel_hi:[0,1]
	v_pk_mov_b32 v[242:243], v[240:241], v[238:239] op_sel:[1,0]
	v_mov_b32_e32 v241, v239
	v_pk_add_f32 v[238:239], v[242:243], v[240:241]
	v_pk_mul_f32 v[242:243], v[36:37], v[176:177] op_sel_hi:[1,0]
	v_pk_mul_f32 v[240:241], v[38:39], v[176:177] op_sel_hi:[1,0]
	v_mul_f32_e32 v232, v242, v242
	v_pk_fma_f32 v[244:245], v[242:243], v[242:243], v[232:233] op_sel_hi:[1,1,0]
	v_mul_f32_e32 v232, v240, v240
	v_pk_add_f32 v[238:239], v[238:239], v[238:239] op_sel_hi:[0,1]
	v_pk_fma_f32 v[246:247], v[240:241], v[240:241], v[232:233] op_sel_hi:[1,1,0]
	v_pk_mul_f32 v[176:177], v[32:33], v[176:177] op_sel_hi:[1,0]
	v_mul_f32_e32 v232, v248, v248
	v_mul_f32_e32 v244, v176, v176
	v_mul_f32_e32 v246, v177, v177
	v_mul_f32_e32 v238, v249, v249
	v_pk_add_f32 v[244:245], v[244:245], v[246:247]
	v_pk_add_f32 v[232:233], v[232:233], v[238:239]
	v_lshlrev_b64 v[238:239], 10, v[164:165]
	v_pk_add_f32 v[232:233], v[244:245], v[232:233]
	v_lshl_add_u64 v[238:239], v[206:207], 0, v[238:239]
	v_add_f32_e32 v232, v232, v233
	ds_bpermute_b32 v233, v225, v232
	s_waitcnt lgkmcnt(0)
	v_add_f32_e32 v232, v232, v233
	ds_bpermute_b32 v233, v224, v232
	s_waitcnt lgkmcnt(0)
	v_add_f32_e32 v232, v232, v233
	v_fmamk_f32 v232, v232, 0x3c800000, v210
	s_nop 0
	v_rsq_f32_e32 v232, v232
	s_nop 0
	v_mul_f32_e32 v232, v223, v232
	v_pk_mul_f32 v[228:229], v[228:229], v[232:233] op_sel_hi:[1,0]
	v_pk_mul_f32 v[230:231], v[230:231], v[232:233] op_sel_hi:[1,0]
	v_pk_mul_f32 v[228:229], v[140:141], v[228:229]
	v_pk_mul_f32 v[230:231], v[142:143], v[230:231]
	v_pk_mul_f32 v[234:235], v[234:235], v[232:233] op_sel_hi:[1,0]
	v_pk_mul_f32 v[236:237], v[236:237], v[232:233] op_sel_hi:[1,0]
	v_pk_mul_f32 v[234:235], v[136:137], v[234:235]
	v_pk_mul_f32 v[236:237], v[138:139], v[236:237]
	v_cvt_pk_bf16_f32 v228, v228, v229
	v_cvt_pk_bf16_f32 v229, v230, v231
	v_cvt_pk_bf16_f32 v230, v234, v235
	v_pk_mul_f32 v[176:177], v[176:177], v[232:233] op_sel_hi:[1,0]
	v_cvt_pk_bf16_f32 v231, v236, v237
	global_store_dwordx4 v[238:239], v[228:231], off
	v_pk_mul_f32 v[176:177], v[128:129], v[176:177]
	s_nop 0
	v_pk_mul_f32 v[228:229], v[242:243], v[232:233] op_sel_hi:[1,0]
	v_pk_mul_f32 v[230:231], v[240:241], v[232:233] op_sel_hi:[1,0]
	v_pk_mul_f32 v[228:229], v[132:133], v[228:229]
	v_pk_mul_f32 v[230:231], v[134:135], v[230:231]
	v_pk_mul_f32 v[232:233], v[248:249], v[232:233] op_sel_hi:[1,0]
	v_cvt_pk_bf16_f32 v228, v228, v229
	v_cvt_pk_bf16_f32 v229, v230, v231
	v_cvt_pk_bf16_f32 v230, v176, v177
	v_ffbh_u32_e32 v176, v163
	v_pk_mul_f32 v[232:233], v[130:131], v[232:233]
	s_nop 0
	v_cvt_pk_bf16_f32 v231, v232, v233
	global_store_dwordx4 v[238:239], v[228:231], off offset:64
	s_nop 1
	v_min_u32_e32 v228, 32, v176
	v_lshlrev_b64 v[176:177], v228, v[162:163]
	v_min_u32_e32 v176, 1, v176
	v_or_b32_e32 v176, v177, v176
	v_cvt_f32_u32_e32 v176, v176
	v_sub_u32_e32 v177, 32, v228
	v_ldexp_f32 v176, v176, v177
	v_mul_f32_e32 v176, 0x35800000, v176
	v_fmamk_f32 v176, v176, 0x3a800000, v210
	s_nop 0
	v_rsq_f32_e32 v176, v176
	s_nop 0
	v_pk_mul_f32 v[228:229], v[28:29], v[176:177] op_sel_hi:[1,0]
	v_pk_mul_f32 v[230:231], v[30:31], v[176:177] op_sel_hi:[1,0]
	v_pk_mul_f32 v[234:235], v[228:229], v[228:229]
	v_pk_mul_f32 v[232:233], v[230:231], v[230:231]
	v_pk_mul_f32 v[248:249], v[18:19], v[176:177] op_sel_hi:[1,0]
	v_pk_mov_b32 v[236:237], v[234:235], v[232:233] op_sel:[1,0]
	v_mov_b32_e32 v235, v233
	v_pk_add_f32 v[232:233], v[236:237], v[234:235]
	v_pk_mul_f32 v[234:235], v[24:25], v[176:177] op_sel_hi:[1,0]
	v_pk_mul_f32 v[236:237], v[26:27], v[176:177] op_sel_hi:[1,0]
	v_pk_mul_f32 v[240:241], v[234:235], v[234:235]
	v_pk_mul_f32 v[238:239], v[236:237], v[236:237]
	v_pk_add_f32 v[232:233], v[232:233], v[232:233] op_sel_hi:[0,1]
	v_pk_mov_b32 v[242:243], v[240:241], v[238:239] op_sel:[1,0]
	v_mov_b32_e32 v241, v239
	v_pk_add_f32 v[238:239], v[242:243], v[240:241]
	v_pk_mul_f32 v[242:243], v[20:21], v[176:177] op_sel_hi:[1,0]
	v_pk_mul_f32 v[240:241], v[22:23], v[176:177] op_sel_hi:[1,0]
	v_mul_f32_e32 v232, v242, v242
	v_pk_fma_f32 v[244:245], v[242:243], v[242:243], v[232:233] op_sel_hi:[1,1,0]
	v_mul_f32_e32 v232, v240, v240
	v_pk_add_f32 v[238:239], v[238:239], v[238:239] op_sel_hi:[0,1]
	v_pk_fma_f32 v[246:247], v[240:241], v[240:241], v[232:233] op_sel_hi:[1,1,0]
	v_pk_mul_f32 v[176:177], v[16:17], v[176:177] op_sel_hi:[1,0]
	v_mul_f32_e32 v232, v248, v248
	v_mul_f32_e32 v244, v176, v176
	v_mul_f32_e32 v246, v177, v177
	v_mul_f32_e32 v238, v249, v249
	v_pk_add_f32 v[244:245], v[244:245], v[246:247]
	v_pk_add_f32 v[232:233], v[232:233], v[238:239]
	v_lshlrev_b64 v[238:239], 10, v[158:159]
	v_pk_add_f32 v[232:233], v[244:245], v[232:233]
	v_lshl_add_u64 v[238:239], v[206:207], 0, v[238:239]
	v_add_f32_e32 v232, v232, v233
	ds_bpermute_b32 v233, v225, v232
	s_waitcnt lgkmcnt(0)
	v_add_f32_e32 v232, v232, v233
	ds_bpermute_b32 v233, v224, v232
	s_waitcnt lgkmcnt(0)
	v_add_f32_e32 v232, v232, v233
	v_fmamk_f32 v232, v232, 0x3c800000, v210
	s_nop 0
	v_rsq_f32_e32 v232, v232
	s_nop 0
	v_mul_f32_e32 v232, v223, v232
	v_pk_mul_f32 v[228:229], v[228:229], v[232:233] op_sel_hi:[1,0]
	v_pk_mul_f32 v[230:231], v[230:231], v[232:233] op_sel_hi:[1,0]
	v_pk_mul_f32 v[228:229], v[140:141], v[228:229]
	v_pk_mul_f32 v[230:231], v[142:143], v[230:231]
	v_pk_mul_f32 v[234:235], v[234:235], v[232:233] op_sel_hi:[1,0]
	v_pk_mul_f32 v[236:237], v[236:237], v[232:233] op_sel_hi:[1,0]
	v_pk_mul_f32 v[234:235], v[136:137], v[234:235]
	v_pk_mul_f32 v[236:237], v[138:139], v[236:237]
	v_cvt_pk_bf16_f32 v228, v228, v229
	v_cvt_pk_bf16_f32 v229, v230, v231
	v_cvt_pk_bf16_f32 v230, v234, v235
	v_pk_mul_f32 v[176:177], v[176:177], v[232:233] op_sel_hi:[1,0]
	v_cvt_pk_bf16_f32 v231, v236, v237
	global_store_dwordx4 v[238:239], v[228:231], off
	v_pk_mul_f32 v[176:177], v[128:129], v[176:177]
	s_nop 0
	v_pk_mul_f32 v[228:229], v[242:243], v[232:233] op_sel_hi:[1,0]
	v_pk_mul_f32 v[230:231], v[240:241], v[232:233] op_sel_hi:[1,0]
	v_pk_mul_f32 v[228:229], v[132:133], v[228:229]
	v_pk_mul_f32 v[230:231], v[134:135], v[230:231]
	v_pk_mul_f32 v[232:233], v[248:249], v[232:233] op_sel_hi:[1,0]
	v_cvt_pk_bf16_f32 v228, v228, v229
	v_cvt_pk_bf16_f32 v229, v230, v231
	v_cvt_pk_bf16_f32 v230, v176, v177
	v_ffbh_u32_e32 v176, v161
	v_pk_mul_f32 v[232:233], v[130:131], v[232:233]
	s_nop 0
	v_cvt_pk_bf16_f32 v231, v232, v233
	global_store_dwordx4 v[238:239], v[228:231], off offset:64
	s_nop 1
	v_min_u32_e32 v228, 32, v176
	v_lshlrev_b64 v[176:177], v228, v[160:161]
	v_min_u32_e32 v176, 1, v176
	v_or_b32_e32 v176, v177, v176
	v_cvt_f32_u32_e32 v176, v176
	v_sub_u32_e32 v177, 32, v228
	v_ldexp_f32 v176, v176, v177
	v_mul_f32_e32 v176, 0x35800000, v176
	v_fmamk_f32 v176, v176, 0x3a800000, v210
	s_nop 0
	v_rsq_f32_e32 v176, v176
	s_nop 0
	v_pk_mul_f32 v[228:229], v[12:13], v[176:177] op_sel_hi:[1,0]
	v_pk_mul_f32 v[230:231], v[14:15], v[176:177] op_sel_hi:[1,0]
	v_pk_mul_f32 v[234:235], v[228:229], v[228:229]
	v_pk_mul_f32 v[232:233], v[230:231], v[230:231]
	v_pk_mul_f32 v[248:249], v[2:3], v[176:177] op_sel_hi:[1,0]
	v_pk_mov_b32 v[236:237], v[234:235], v[232:233] op_sel:[1,0]
	v_mov_b32_e32 v235, v233
	v_pk_add_f32 v[232:233], v[236:237], v[234:235]
	v_pk_mul_f32 v[234:235], v[8:9], v[176:177] op_sel_hi:[1,0]
	v_pk_mul_f32 v[236:237], v[10:11], v[176:177] op_sel_hi:[1,0]
	v_pk_mul_f32 v[240:241], v[234:235], v[234:235]
	v_pk_mul_f32 v[238:239], v[236:237], v[236:237]
	v_pk_add_f32 v[232:233], v[232:233], v[232:233] op_sel_hi:[0,1]
	v_pk_mov_b32 v[242:243], v[240:241], v[238:239] op_sel:[1,0]
	v_mov_b32_e32 v241, v239
	v_pk_add_f32 v[238:239], v[242:243], v[240:241]
	v_pk_mul_f32 v[242:243], v[4:5], v[176:177] op_sel_hi:[1,0]
	v_pk_mul_f32 v[240:241], v[6:7], v[176:177] op_sel_hi:[1,0]
	v_mul_f32_e32 v232, v242, v242
	v_pk_fma_f32 v[244:245], v[242:243], v[242:243], v[232:233] op_sel_hi:[1,1,0]
	v_mul_f32_e32 v232, v240, v240
	v_pk_add_f32 v[238:239], v[238:239], v[238:239] op_sel_hi:[0,1]
	v_pk_fma_f32 v[246:247], v[240:241], v[240:241], v[232:233] op_sel_hi:[1,1,0]
	v_pk_mul_f32 v[176:177], v[0:1], v[176:177] op_sel_hi:[1,0]
	v_mul_f32_e32 v232, v248, v248
	v_mul_f32_e32 v244, v176, v176
	v_mul_f32_e32 v246, v177, v177
	v_mul_f32_e32 v238, v249, v249
	v_pk_add_f32 v[244:245], v[244:245], v[246:247]
	v_pk_add_f32 v[232:233], v[232:233], v[238:239]
	s_nop 0
	v_pk_add_f32 v[232:233], v[244:245], v[232:233]
	s_nop 0
	v_add_f32_e32 v232, v232, v233
	ds_bpermute_b32 v225, v225, v232
	s_waitcnt lgkmcnt(0)
	v_add_f32_e32 v225, v232, v225
	ds_bpermute_b32 v224, v224, v225
	v_lshlrev_b64 v[232:233], 10, v[156:157]
	v_lshl_add_u64 v[206:207], v[206:207], 0, v[232:233]
	s_waitcnt lgkmcnt(0)
	v_add_f32_e32 v224, v225, v224
	v_fmamk_f32 v224, v224, 0x3c800000, v210
	s_nop 0
	v_rsq_f32_e32 v224, v224
	s_nop 0
	v_mul_f32_e32 v224, v223, v224
	v_pk_mul_f32 v[228:229], v[228:229], v[224:225] op_sel_hi:[1,0]
	v_pk_mul_f32 v[230:231], v[230:231], v[224:225] op_sel_hi:[1,0]
	v_pk_mul_f32 v[140:141], v[140:141], v[228:229]
	v_pk_mul_f32 v[142:143], v[142:143], v[230:231]
	v_pk_mul_f32 v[228:229], v[234:235], v[224:225] op_sel_hi:[1,0]
	v_pk_mul_f32 v[230:231], v[236:237], v[224:225] op_sel_hi:[1,0]
	s_nop 0
	v_pk_mul_f32 v[230:231], v[138:139], v[230:231]
	v_pk_mul_f32 v[138:139], v[136:137], v[228:229]
	v_cvt_pk_bf16_f32 v136, v140, v141
	v_cvt_pk_bf16_f32 v137, v142, v143
	s_nop 0
	v_cvt_pk_bf16_f32 v138, v138, v139
	v_cvt_pk_bf16_f32 v139, v230, v231
	global_store_dwordx4 v[206:207], v[136:139], off
	s_nop 1
	v_pk_mul_f32 v[136:137], v[242:243], v[224:225] op_sel_hi:[1,0]
	v_pk_mul_f32 v[138:139], v[240:241], v[224:225] op_sel_hi:[1,0]
	v_pk_mul_f32 v[132:133], v[132:133], v[136:137]
	v_pk_mul_f32 v[134:135], v[134:135], v[138:139]
	v_pk_mul_f32 v[136:137], v[176:177], v[224:225] op_sel_hi:[1,0]
	v_pk_mul_f32 v[138:139], v[248:249], v[224:225] op_sel_hi:[1,0]
	s_nop 0
	v_pk_mul_f32 v[138:139], v[130:131], v[138:139]
	v_pk_mul_f32 v[130:131], v[128:129], v[136:137]
	v_cvt_pk_bf16_f32 v128, v132, v133
	v_cvt_pk_bf16_f32 v129, v134, v135
	s_nop 0
	v_cvt_pk_bf16_f32 v130, v130, v131
	v_cvt_pk_bf16_f32 v131, v138, v139
	s_nop 1

.LBB0_350:
	s_lshl_b32 s25, s84, 1
	s_add_i32 s25, s85, s25
	s_and_b32 s85, s25, 3
	s_lshl_b32 s25, s85, 19
	s_add_u32 s92, s74, s25
	v_cmp_lt_i64_e32 vcc, s[52:53], v[180:181]
	s_addc_u32 s93, s75, 0
	s_and_b64 s[30:31], vcc, exec
	s_cselect_b32 s25, s93, s1
	s_cselect_b32 s30, s92, s0
	s_ashr_i32 s47, s46, 31
	s_lshl_b64 s[34:35], s[46:47], 19
	s_add_u32 s94, s54, s34
	s_addc_u32 s95, s55, s35
	s_and_b64 s[34:35], vcc, exec
	s_cselect_b32 s31, s95, s51
	s_cselect_b32 s33, s94, s50
	s_add_u32 s0, s0, 0x40080
	s_addc_u32 s1, s1, 0
	s_add_u32 s34, s50, 0x100
	s_addc_u32 s35, s51, 0
	s_mov_b32 s36, -2
	s_add_u32 s27, s0, 0xfffc0080
	s_addc_u32 s37, s1, -1
	s_add_i32 s47, 0, 0x10000
	v_add_u32_e32 v140, s47, v192
	ds_read_b128 v[128:131], v140
	ds_read_b128 v[132:135], v140 offset:1024
	ds_read_b128 v[136:139], v140 offset:2048
	ds_read_b128 v[140:143], v140 offset:3072
	s_cmp_eq_u32 s36, 12
	s_cselect_b32 s53, s25, s37
	s_cselect_b32 s52, s30, s27
	s_cselect_b32 s51, s31, s35
	s_cselect_b32 s50, s33, s34
	s_add_i32 m0, s77, 0xc000
	ds_read_b128 v[162:165], v194
	ds_read_b128 v[166:169], v194 offset:1024
	ds_read_b128 v[196:199], v194 offset:2048
	ds_read_b128 v[200:203], v194 offset:3072
	ds_read_b128 v[204:207], v194 offset:4096
	ds_read_b128 v[216:219], v194 offset:5120
	ds_read_b128 v[220:223], v194 offset:6144
	ds_read_b128 v[228:231], v194 offset:7168
	global_load_lds_dwordx4 v156, s[0:1]
	s_add_i32 m0, s77, 0xe000
	s_nop 0
	global_load_lds_dwordx4 v158, s[0:1]
	s_waitcnt lgkmcnt(8)
	s_barrier
	s_waitcnt lgkmcnt(0)
	v_mfma_f32_16x16x32_bf16 v[124:127], v[128:131], v[162:165], 0
	v_mfma_f32_16x16x32_bf16 v[120:123], v[136:139], v[162:165], 0
	v_mfma_f32_16x16x32_bf16 v[116:119], v[128:131], v[196:199], 0
	v_mfma_f32_16x16x32_bf16 v[112:115], v[136:139], v[196:199], 0
	v_mfma_f32_16x16x32_bf16 v[108:111], v[128:131], v[204:207], 0
	v_mfma_f32_16x16x32_bf16 v[104:107], v[136:139], v[204:207], 0
	v_mfma_f32_16x16x32_bf16 v[100:103], v[128:131], v[220:223], 0
	v_mfma_f32_16x16x32_bf16 v[96:99], v[136:139], v[220:223], 0
	v_mfma_f32_16x16x32_bf16 v[124:127], v[132:135], v[166:169], v[124:127]
	v_mfma_f32_16x16x32_bf16 v[120:123], v[140:143], v[166:169], v[120:123]
	v_mfma_f32_16x16x32_bf16 v[116:119], v[132:135], v[200:203], v[116:119]
	v_mfma_f32_16x16x32_bf16 v[112:115], v[140:143], v[200:203], v[112:115]
	v_mfma_f32_16x16x32_bf16 v[108:111], v[132:135], v[216:219], v[108:111]
	v_mfma_f32_16x16x32_bf16 v[104:107], v[140:143], v[216:219], v[104:107]
	v_mfma_f32_16x16x32_bf16 v[100:103], v[132:135], v[228:231], v[100:103]
	v_mfma_f32_16x16x32_bf16 v[96:99], v[140:143], v[228:231], v[96:99]
	s_barrier
	s_add_i32 s27, 0, 0x14000
	s_add_i32 s37, s47, s76
	v_add_u32_e32 v161, s27, v192
	s_mov_b32 m0, s37
	ds_read_b128 v[232:235], v161
	ds_read_b128 v[236:239], v161 offset:1024
	ds_read_b128 v[240:243], v161 offset:2048
	ds_read_b128 v[244:247], v161 offset:3072
	global_load_lds_dwordx4 v148, s[50:51]
	s_add_i32 m0, s37, 0x2000
	s_nop 0
	global_load_lds_dwordx4 v152, s[50:51]
	s_barrier
	s_waitcnt lgkmcnt(0)
	v_mfma_f32_16x16x32_bf16 v[92:95], v[232:235], v[162:165], 0
	v_mfma_f32_16x16x32_bf16 v[88:91], v[240:243], v[162:165], 0
	v_mfma_f32_16x16x32_bf16 v[84:87], v[232:235], v[196:199], 0
	v_mfma_f32_16x16x32_bf16 v[80:83], v[240:243], v[196:199], 0
	v_mfma_f32_16x16x32_bf16 v[76:79], v[232:235], v[204:207], 0
	v_mfma_f32_16x16x32_bf16 v[72:75], v[240:243], v[204:207], 0
	v_mfma_f32_16x16x32_bf16 v[68:71], v[232:235], v[220:223], 0
	v_mfma_f32_16x16x32_bf16 v[64:67], v[240:243], v[220:223], 0
	v_mfma_f32_16x16x32_bf16 v[92:95], v[236:239], v[166:169], v[92:95]
	v_mfma_f32_16x16x32_bf16 v[88:91], v[244:247], v[166:169], v[88:91]
	v_mfma_f32_16x16x32_bf16 v[84:87], v[236:239], v[200:203], v[84:87]
	v_mfma_f32_16x16x32_bf16 v[80:83], v[244:247], v[200:203], v[80:83]
	v_mfma_f32_16x16x32_bf16 v[76:79], v[236:239], v[216:219], v[76:79]
	v_mfma_f32_16x16x32_bf16 v[72:75], v[244:247], v[216:219], v[72:75]
	v_mfma_f32_16x16x32_bf16 v[68:71], v[236:239], v[228:231], v[68:71]
	v_mfma_f32_16x16x32_bf16 v[64:67], v[244:247], v[228:231], v[64:67]
	s_barrier
	s_mov_b32 m0, s77
	v_lshl_add_u64 v[224:225], s[52:53], 0, v[146:147]
	ds_read_b128 v[162:165], v194 offset:16384
	ds_read_b128 v[166:169], v194 offset:17408
	ds_read_b128 v[196:199], v194 offset:18432
	ds_read_b128 v[200:203], v194 offset:19456
	ds_read_b128 v[204:207], v194 offset:20480
	ds_read_b128 v[216:219], v194 offset:21504
	ds_read_b128 v[220:223], v194 offset:22528
	ds_read_b128 v[228:231], v194 offset:23552
	global_load_lds_dwordx4 v[224:225], off
	v_lshl_add_u64 v[248:249], s[52:53], 0, v[150:151]
	s_mov_b32 m0, s78
	s_nop 0
	global_load_lds_dwordx4 v[248:249], off
	s_barrier
	s_waitcnt lgkmcnt(0)
	v_mfma_f32_16x16x32_bf16 v[60:63], v[128:131], v[162:165], 0
	v_mfma_f32_16x16x32_bf16 v[56:59], v[136:139], v[162:165], 0
	v_mfma_f32_16x16x32_bf16 v[52:55], v[128:131], v[196:199], 0
	v_mfma_f32_16x16x32_bf16 v[48:51], v[136:139], v[196:199], 0
	v_mfma_f32_16x16x32_bf16 v[44:47], v[128:131], v[204:207], 0
	v_mfma_f32_16x16x32_bf16 v[40:43], v[136:139], v[204:207], 0
	v_mfma_f32_16x16x32_bf16 v[36:39], v[128:131], v[220:223], 0
	v_mfma_f32_16x16x32_bf16 v[32:35], v[136:139], v[220:223], 0
	v_mfma_f32_16x16x32_bf16 v[60:63], v[132:135], v[166:169], v[60:63]
	v_mfma_f32_16x16x32_bf16 v[56:59], v[140:143], v[166:169], v[56:59]
	v_mfma_f32_16x16x32_bf16 v[52:55], v[132:135], v[200:203], v[52:55]
	v_mfma_f32_16x16x32_bf16 v[48:51], v[140:143], v[200:203], v[48:51]
	v_mfma_f32_16x16x32_bf16 v[44:47], v[132:135], v[216:219], v[44:47]
	v_mfma_f32_16x16x32_bf16 v[40:43], v[140:143], v[216:219], v[40:43]
	v_mfma_f32_16x16x32_bf16 v[36:39], v[132:135], v[228:231], v[36:39]
	v_mfma_f32_16x16x32_bf16 v[32:35], v[140:143], v[228:231], v[32:35]
	s_barrier
	s_add_u32 s56, s50, 0x40000
	s_addc_u32 s57, s51, 0
	s_add_i32 s27, s27, s76
	s_mov_b32 m0, s27
	s_nop 0
	global_load_lds_dwordx4 v148, s[56:57]
	s_add_i32 m0, s27, 0x2000
	s_nop 0
	global_load_lds_dwordx4 v152, s[56:57]
	s_waitcnt vmcnt(6)
	s_barrier
	v_mfma_f32_16x16x32_bf16 v[28:31], v[232:235], v[162:165], 0
	v_mfma_f32_16x16x32_bf16 v[24:27], v[240:243], v[162:165], 0
	v_mfma_f32_16x16x32_bf16 v[20:23], v[232:235], v[196:199], 0
	v_mfma_f32_16x16x32_bf16 v[16:19], v[240:243], v[196:199], 0
	v_mfma_f32_16x16x32_bf16 v[12:15], v[232:235], v[204:207], 0
	v_mfma_f32_16x16x32_bf16 v[8:11], v[240:243], v[204:207], 0
	v_mfma_f32_16x16x32_bf16 v[4:7], v[232:235], v[220:223], 0
	v_mfma_f32_16x16x32_bf16 v[0:3], v[240:243], v[220:223], 0
	v_mfma_f32_16x16x32_bf16 v[28:31], v[236:239], v[166:169], v[28:31]
	v_mfma_f32_16x16x32_bf16 v[24:27], v[244:247], v[166:169], v[24:27]
	v_mfma_f32_16x16x32_bf16 v[20:23], v[236:239], v[200:203], v[20:23]
	v_mfma_f32_16x16x32_bf16 v[16:19], v[244:247], v[200:203], v[16:19]
	v_mfma_f32_16x16x32_bf16 v[12:15], v[236:239], v[216:219], v[12:15]
	v_mfma_f32_16x16x32_bf16 v[8:11], v[244:247], v[216:219], v[8:11]
	v_mfma_f32_16x16x32_bf16 v[4:7], v[236:239], v[228:231], v[4:7]
	v_mfma_f32_16x16x32_bf16 v[0:3], v[244:247], v[228:231], v[0:3]
	s_barrier
	s_add_i32 s27, 0, 0x18000
	v_add_u32_e32 v140, s27, v192
	ds_read_b128 v[128:131], v140
	ds_read_b128 v[132:135], v140 offset:1024
	ds_read_b128 v[136:139], v140 offset:2048
	ds_read_b128 v[140:143], v140 offset:3072
	s_add_u32 s52, s52, 0x40000
	s_addc_u32 s53, s53, 0
	s_mov_b32 m0, s81
	ds_read_b128 v[162:165], v194 offset:32768
	ds_read_b128 v[166:169], v194 offset:33792
	ds_read_b128 v[196:199], v194 offset:34816
	ds_read_b128 v[200:203], v194 offset:35840
	ds_read_b128 v[204:207], v194 offset:36864
	ds_read_b128 v[216:219], v194 offset:37888
	ds_read_b128 v[220:223], v194 offset:38912
	ds_read_b128 v[228:231], v194 offset:39936
	global_load_lds_dwordx4 v146, s[52:53]
	s_mov_b32 m0, s82
	s_nop 0
	global_load_lds_dwordx4 v150, s[52:53]
	s_waitcnt lgkmcnt(8)
	s_barrier
	s_waitcnt lgkmcnt(0)
	v_mfma_f32_16x16x32_bf16 v[124:127], v[128:131], v[162:165], v[124:127]
	v_mfma_f32_16x16x32_bf16 v[120:123], v[136:139], v[162:165], v[120:123]
	v_mfma_f32_16x16x32_bf16 v[116:119], v[128:131], v[196:199], v[116:119]
	v_mfma_f32_16x16x32_bf16 v[112:115], v[136:139], v[196:199], v[112:115]
	v_mfma_f32_16x16x32_bf16 v[108:111], v[128:131], v[204:207], v[108:111]
	v_mfma_f32_16x16x32_bf16 v[104:107], v[136:139], v[204:207], v[104:107]
	v_mfma_f32_16x16x32_bf16 v[100:103], v[128:131], v[220:223], v[100:103]
	v_mfma_f32_16x16x32_bf16 v[96:99], v[136:139], v[220:223], v[96:99]
	v_mfma_f32_16x16x32_bf16 v[124:127], v[132:135], v[166:169], v[124:127]
	v_mfma_f32_16x16x32_bf16 v[120:123], v[140:143], v[166:169], v[120:123]
	v_mfma_f32_16x16x32_bf16 v[116:119], v[132:135], v[200:203], v[116:119]
	v_mfma_f32_16x16x32_bf16 v[112:115], v[140:143], v[200:203], v[112:115]
	v_mfma_f32_16x16x32_bf16 v[108:111], v[132:135], v[216:219], v[108:111]
	v_mfma_f32_16x16x32_bf16 v[104:107], v[140:143], v[216:219], v[104:107]
	v_mfma_f32_16x16x32_bf16 v[100:103], v[132:135], v[228:231], v[100:103]
	v_mfma_f32_16x16x32_bf16 v[96:99], v[140:143], v[228:231], v[96:99]
	s_barrier
	s_add_i32 s37, 0, 0x1c000
	s_add_i32 s27, s27, s76
	v_add_u32_e32 v161, s37, v192
	s_add_u32 s56, s50, s18
	s_addc_u32 s57, s51, s19
	s_mov_b32 m0, s27
	ds_read_b128 v[232:235], v161
	ds_read_b128 v[236:239], v161 offset:1024
	ds_read_b128 v[240:243], v161 offset:2048
	ds_read_b128 v[244:247], v161 offset:3072
	global_load_lds_dwordx4 v148, s[56:57]
	s_add_u32 s56, s50, s18
	s_addc_u32 s57, s51, s19
	s_add_i32 m0, s27, 0x2000
	s_nop 0
	global_load_lds_dwordx4 v152, s[56:57]
	s_barrier
	s_waitcnt lgkmcnt(0)
	v_mfma_f32_16x16x32_bf16 v[92:95], v[232:235], v[162:165], v[92:95]
	v_mfma_f32_16x16x32_bf16 v[88:91], v[240:243], v[162:165], v[88:91]
	v_mfma_f32_16x16x32_bf16 v[84:87], v[232:235], v[196:199], v[84:87]
	v_mfma_f32_16x16x32_bf16 v[80:83], v[240:243], v[196:199], v[80:83]
	v_mfma_f32_16x16x32_bf16 v[76:79], v[232:235], v[204:207], v[76:79]
	v_mfma_f32_16x16x32_bf16 v[72:75], v[240:243], v[204:207], v[72:75]
	v_mfma_f32_16x16x32_bf16 v[68:71], v[232:235], v[220:223], v[68:71]
	v_mfma_f32_16x16x32_bf16 v[64:67], v[240:243], v[220:223], v[64:67]
	v_mfma_f32_16x16x32_bf16 v[92:95], v[236:239], v[166:169], v[92:95]
	v_mfma_f32_16x16x32_bf16 v[88:91], v[244:247], v[166:169], v[88:91]
	v_mfma_f32_16x16x32_bf16 v[84:87], v[236:239], v[200:203], v[84:87]
	v_mfma_f32_16x16x32_bf16 v[80:83], v[244:247], v[200:203], v[80:83]
	v_mfma_f32_16x16x32_bf16 v[76:79], v[236:239], v[216:219], v[76:79]
	v_mfma_f32_16x16x32_bf16 v[72:75], v[244:247], v[216:219], v[72:75]
	v_mfma_f32_16x16x32_bf16 v[68:71], v[236:239], v[228:231], v[68:71]
	v_mfma_f32_16x16x32_bf16 v[64:67], v[244:247], v[228:231], v[64:67]
	s_barrier
	s_mov_b32 m0, s80
	v_lshl_add_u64 v[176:177], v[224:225], 0, s[18:19]
	ds_read_b128 v[162:165], v194 offset:49152
	ds_read_b128 v[166:169], v194 offset:50176
	ds_read_b128 v[196:199], v194 offset:51200
	ds_read_b128 v[200:203], v194 offset:52224
	ds_read_b128 v[204:207], v194 offset:53248
	ds_read_b128 v[216:219], v194 offset:54272
	ds_read_b128 v[220:223], v194 offset:55296
	ds_read_b128 v[228:231], v194 offset:56320
	global_load_lds_dwordx4 v[176:177], off
	v_lshl_add_u64 v[176:177], v[248:249], 0, s[18:19]
	s_mov_b32 m0, s83
	s_nop 0
	global_load_lds_dwordx4 v[176:177], off
	s_barrier
	s_waitcnt lgkmcnt(0)
	v_mfma_f32_16x16x32_bf16 v[60:63], v[128:131], v[162:165], v[60:63]
	v_mfma_f32_16x16x32_bf16 v[56:59], v[136:139], v[162:165], v[56:59]
	v_mfma_f32_16x16x32_bf16 v[52:55], v[128:131], v[196:199], v[52:55]
	v_mfma_f32_16x16x32_bf16 v[48:51], v[136:139], v[196:199], v[48:51]
	v_mfma_f32_16x16x32_bf16 v[44:47], v[128:131], v[204:207], v[44:47]
	v_mfma_f32_16x16x32_bf16 v[40:43], v[136:139], v[204:207], v[40:43]
	v_mfma_f32_16x16x32_bf16 v[36:39], v[128:131], v[220:223], v[36:39]
	v_mfma_f32_16x16x32_bf16 v[32:35], v[136:139], v[220:223], v[32:35]
	v_mfma_f32_16x16x32_bf16 v[60:63], v[132:135], v[166:169], v[60:63]
	v_mfma_f32_16x16x32_bf16 v[56:59], v[140:143], v[166:169], v[56:59]
	v_mfma_f32_16x16x32_bf16 v[52:55], v[132:135], v[200:203], v[52:55]
	v_mfma_f32_16x16x32_bf16 v[48:51], v[140:143], v[200:203], v[48:51]
	v_mfma_f32_16x16x32_bf16 v[44:47], v[132:135], v[216:219], v[44:47]
	v_mfma_f32_16x16x32_bf16 v[40:43], v[140:143], v[216:219], v[40:43]
	v_mfma_f32_16x16x32_bf16 v[36:39], v[132:135], v[228:231], v[36:39]
	v_mfma_f32_16x16x32_bf16 v[32:35], v[140:143], v[228:231], v[32:35]
	s_barrier
	s_add_u32 s50, s50, 0x40080
	s_addc_u32 s51, s51, 0
	s_add_i32 s27, s37, s76
	s_mov_b32 m0, s27
	s_nop 0
	global_load_lds_dwordx4 v148, s[50:51]
	s_add_i32 m0, s27, 0x2000
	s_nop 0
	global_load_lds_dwordx4 v152, s[50:51]
	s_waitcnt vmcnt(6)
	s_barrier
	v_mfma_f32_16x16x32_bf16 v[28:31], v[232:235], v[162:165], v[28:31]
	v_mfma_f32_16x16x32_bf16 v[24:27], v[240:243], v[162:165], v[24:27]
	v_mfma_f32_16x16x32_bf16 v[20:23], v[232:235], v[196:199], v[20:23]
	v_mfma_f32_16x16x32_bf16 v[16:19], v[240:243], v[196:199], v[16:19]
	v_mfma_f32_16x16x32_bf16 v[12:15], v[232:235], v[204:207], v[12:15]
	v_mfma_f32_16x16x32_bf16 v[8:11], v[240:243], v[204:207], v[8:11]
	v_mfma_f32_16x16x32_bf16 v[4:7], v[232:235], v[220:223], v[4:7]
	v_mfma_f32_16x16x32_bf16 v[0:3], v[240:243], v[220:223], v[0:3]
	v_mfma_f32_16x16x32_bf16 v[28:31], v[236:239], v[166:169], v[28:31]
	v_mfma_f32_16x16x32_bf16 v[24:27], v[244:247], v[166:169], v[24:27]
	v_mfma_f32_16x16x32_bf16 v[20:23], v[236:239], v[200:203], v[20:23]
	v_mfma_f32_16x16x32_bf16 v[16:19], v[244:247], v[200:203], v[16:19]
	v_mfma_f32_16x16x32_bf16 v[12:15], v[236:239], v[216:219], v[12:15]
	v_mfma_f32_16x16x32_bf16 v[8:11], v[244:247], v[216:219], v[8:11]
	v_mfma_f32_16x16x32_bf16 v[4:7], v[236:239], v[228:231], v[4:7]
	v_mfma_f32_16x16x32_bf16 v[0:3], v[244:247], v[228:231], v[0:3]
	s_barrier
	s_add_i32 s36, s36, 2
	s_add_u32 s0, s0, 0x100
	s_addc_u32 s1, s1, 0
	s_add_u32 s34, s34, 0x100
	s_addc_u32 s35, s35, 0
	s_cmp_gt_u32 s36, 13
.LBB0_351:
	s_add_u32 s27, s0, 0xfffc0080
	s_addc_u32 s37, s1, -1
	s_add_i32 s47, 0, 0x10000
	v_add_u32_e32 v140, s47, v192
	ds_read_b128 v[128:131], v140
	ds_read_b128 v[132:135], v140 offset:1024
	ds_read_b128 v[136:139], v140 offset:2048
	ds_read_b128 v[140:143], v140 offset:3072
	s_cmp_eq_u32 s36, 12
	s_cselect_b32 s53, s25, s37
	s_cselect_b32 s52, s30, s27
	s_cselect_b32 s51, s31, s35
	s_cselect_b32 s50, s33, s34
	s_add_i32 m0, s77, 0xc000
	ds_read_b128 v[162:165], v194
	ds_read_b128 v[166:169], v194 offset:1024
	ds_read_b128 v[196:199], v194 offset:2048
	ds_read_b128 v[200:203], v194 offset:3072
	ds_read_b128 v[204:207], v194 offset:4096
	ds_read_b128 v[216:219], v194 offset:5120
	ds_read_b128 v[220:223], v194 offset:6144
	ds_read_b128 v[228:231], v194 offset:7168
	global_load_lds_dwordx4 v156, s[0:1]
	s_add_i32 m0, s77, 0xe000
	s_nop 0
	global_load_lds_dwordx4 v158, s[0:1]
	s_waitcnt lgkmcnt(8)
	s_barrier
	s_waitcnt lgkmcnt(0)
	v_mfma_f32_16x16x32_bf16 v[124:127], v[128:131], v[162:165], v[124:127]
	v_mfma_f32_16x16x32_bf16 v[120:123], v[136:139], v[162:165], v[120:123]
	v_mfma_f32_16x16x32_bf16 v[116:119], v[128:131], v[196:199], v[116:119]
	v_mfma_f32_16x16x32_bf16 v[112:115], v[136:139], v[196:199], v[112:115]
	v_mfma_f32_16x16x32_bf16 v[108:111], v[128:131], v[204:207], v[108:111]
	v_mfma_f32_16x16x32_bf16 v[104:107], v[136:139], v[204:207], v[104:107]
	v_mfma_f32_16x16x32_bf16 v[100:103], v[128:131], v[220:223], v[100:103]
	v_mfma_f32_16x16x32_bf16 v[96:99], v[136:139], v[220:223], v[96:99]
	v_mfma_f32_16x16x32_bf16 v[124:127], v[132:135], v[166:169], v[124:127]
	v_mfma_f32_16x16x32_bf16 v[120:123], v[140:143], v[166:169], v[120:123]
	v_mfma_f32_16x16x32_bf16 v[116:119], v[132:135], v[200:203], v[116:119]
	v_mfma_f32_16x16x32_bf16 v[112:115], v[140:143], v[200:203], v[112:115]
	v_mfma_f32_16x16x32_bf16 v[108:111], v[132:135], v[216:219], v[108:111]
	v_mfma_f32_16x16x32_bf16 v[104:107], v[140:143], v[216:219], v[104:107]
	v_mfma_f32_16x16x32_bf16 v[100:103], v[132:135], v[228:231], v[100:103]
	v_mfma_f32_16x16x32_bf16 v[96:99], v[140:143], v[228:231], v[96:99]
	s_barrier
	s_add_i32 s27, 0, 0x14000
	s_add_i32 s37, s47, s76
	v_add_u32_e32 v161, s27, v192
	s_mov_b32 m0, s37
	ds_read_b128 v[232:235], v161
	ds_read_b128 v[236:239], v161 offset:1024
	ds_read_b128 v[240:243], v161 offset:2048
	ds_read_b128 v[244:247], v161 offset:3072
	global_load_lds_dwordx4 v148, s[50:51]
	s_add_i32 m0, s37, 0x2000
	s_nop 0
	global_load_lds_dwordx4 v152, s[50:51]
	s_barrier
	s_waitcnt lgkmcnt(0)
	v_mfma_f32_16x16x32_bf16 v[92:95], v[232:235], v[162:165], v[92:95]
	v_mfma_f32_16x16x32_bf16 v[88:91], v[240:243], v[162:165], v[88:91]
	v_mfma_f32_16x16x32_bf16 v[84:87], v[232:235], v[196:199], v[84:87]
	v_mfma_f32_16x16x32_bf16 v[80:83], v[240:243], v[196:199], v[80:83]
	v_mfma_f32_16x16x32_bf16 v[76:79], v[232:235], v[204:207], v[76:79]
	v_mfma_f32_16x16x32_bf16 v[72:75], v[240:243], v[204:207], v[72:75]
	v_mfma_f32_16x16x32_bf16 v[68:71], v[232:235], v[220:223], v[68:71]
	v_mfma_f32_16x16x32_bf16 v[64:67], v[240:243], v[220:223], v[64:67]
	v_mfma_f32_16x16x32_bf16 v[92:95], v[236:239], v[166:169], v[92:95]
	v_mfma_f32_16x16x32_bf16 v[88:91], v[244:247], v[166:169], v[88:91]
	v_mfma_f32_16x16x32_bf16 v[84:87], v[236:239], v[200:203], v[84:87]
	v_mfma_f32_16x16x32_bf16 v[80:83], v[244:247], v[200:203], v[80:83]
	v_mfma_f32_16x16x32_bf16 v[76:79], v[236:239], v[216:219], v[76:79]
	v_mfma_f32_16x16x32_bf16 v[72:75], v[244:247], v[216:219], v[72:75]
	v_mfma_f32_16x16x32_bf16 v[68:71], v[236:239], v[228:231], v[68:71]
	v_mfma_f32_16x16x32_bf16 v[64:67], v[244:247], v[228:231], v[64:67]
	s_barrier
	s_mov_b32 m0, s77
	v_lshl_add_u64 v[224:225], s[52:53], 0, v[146:147]
	ds_read_b128 v[162:165], v194 offset:16384
	ds_read_b128 v[166:169], v194 offset:17408
	ds_read_b128 v[196:199], v194 offset:18432
	ds_read_b128 v[200:203], v194 offset:19456
	ds_read_b128 v[204:207], v194 offset:20480
	ds_read_b128 v[216:219], v194 offset:21504
	ds_read_b128 v[220:223], v194 offset:22528
	ds_read_b128 v[228:231], v194 offset:23552
	global_load_lds_dwordx4 v[224:225], off
	v_lshl_add_u64 v[248:249], s[52:53], 0, v[150:151]
	s_mov_b32 m0, s78
	s_nop 0
	global_load_lds_dwordx4 v[248:249], off
	s_barrier
	s_waitcnt lgkmcnt(0)
	v_mfma_f32_16x16x32_bf16 v[60:63], v[128:131], v[162:165], v[60:63]
	v_mfma_f32_16x16x32_bf16 v[56:59], v[136:139], v[162:165], v[56:59]
	v_mfma_f32_16x16x32_bf16 v[52:55], v[128:131], v[196:199], v[52:55]
	v_mfma_f32_16x16x32_bf16 v[48:51], v[136:139], v[196:199], v[48:51]
	v_mfma_f32_16x16x32_bf16 v[44:47], v[128:131], v[204:207], v[44:47]
	v_mfma_f32_16x16x32_bf16 v[40:43], v[136:139], v[204:207], v[40:43]
	v_mfma_f32_16x16x32_bf16 v[36:39], v[128:131], v[220:223], v[36:39]
	v_mfma_f32_16x16x32_bf16 v[32:35], v[136:139], v[220:223], v[32:35]
	v_mfma_f32_16x16x32_bf16 v[60:63], v[132:135], v[166:169], v[60:63]
	v_mfma_f32_16x16x32_bf16 v[56:59], v[140:143], v[166:169], v[56:59]
	v_mfma_f32_16x16x32_bf16 v[52:55], v[132:135], v[200:203], v[52:55]
	v_mfma_f32_16x16x32_bf16 v[48:51], v[140:143], v[200:203], v[48:51]
	v_mfma_f32_16x16x32_bf16 v[44:47], v[132:135], v[216:219], v[44:47]
	v_mfma_f32_16x16x32_bf16 v[40:43], v[140:143], v[216:219], v[40:43]
	v_mfma_f32_16x16x32_bf16 v[36:39], v[132:135], v[228:231], v[36:39]
	v_mfma_f32_16x16x32_bf16 v[32:35], v[140:143], v[228:231], v[32:35]
	s_barrier
	s_add_u32 s56, s50, 0x40000
	s_addc_u32 s57, s51, 0
	s_add_i32 s27, s27, s76
	s_mov_b32 m0, s27
	s_nop 0
	global_load_lds_dwordx4 v148, s[56:57]
	s_add_i32 m0, s27, 0x2000
	s_nop 0
	global_load_lds_dwordx4 v152, s[56:57]
	s_waitcnt vmcnt(6)
	s_barrier
	v_mfma_f32_16x16x32_bf16 v[28:31], v[232:235], v[162:165], v[28:31]
	v_mfma_f32_16x16x32_bf16 v[24:27], v[240:243], v[162:165], v[24:27]
	v_mfma_f32_16x16x32_bf16 v[20:23], v[232:235], v[196:199], v[20:23]
	v_mfma_f32_16x16x32_bf16 v[16:19], v[240:243], v[196:199], v[16:19]
	v_mfma_f32_16x16x32_bf16 v[12:15], v[232:235], v[204:207], v[12:15]
	v_mfma_f32_16x16x32_bf16 v[8:11], v[240:243], v[204:207], v[8:11]
	v_mfma_f32_16x16x32_bf16 v[4:7], v[232:235], v[220:223], v[4:7]
	v_mfma_f32_16x16x32_bf16 v[0:3], v[240:243], v[220:223], v[0:3]
	v_mfma_f32_16x16x32_bf16 v[28:31], v[236:239], v[166:169], v[28:31]
	v_mfma_f32_16x16x32_bf16 v[24:27], v[244:247], v[166:169], v[24:27]
	v_mfma_f32_16x16x32_bf16 v[20:23], v[236:239], v[200:203], v[20:23]
	v_mfma_f32_16x16x32_bf16 v[16:19], v[244:247], v[200:203], v[16:19]
	v_mfma_f32_16x16x32_bf16 v[12:15], v[236:239], v[216:219], v[12:15]
	v_mfma_f32_16x16x32_bf16 v[8:11], v[244:247], v[216:219], v[8:11]
	v_mfma_f32_16x16x32_bf16 v[4:7], v[236:239], v[228:231], v[4:7]
	v_mfma_f32_16x16x32_bf16 v[0:3], v[244:247], v[228:231], v[0:3]
	s_barrier
	s_add_i32 s27, 0, 0x18000
	v_add_u32_e32 v140, s27, v192
	ds_read_b128 v[128:131], v140
	ds_read_b128 v[132:135], v140 offset:1024
	ds_read_b128 v[136:139], v140 offset:2048
	ds_read_b128 v[140:143], v140 offset:3072
	s_add_u32 s52, s52, 0x40000
	s_addc_u32 s53, s53, 0
	s_mov_b32 m0, s81
	ds_read_b128 v[162:165], v194 offset:32768
	ds_read_b128 v[166:169], v194 offset:33792
	ds_read_b128 v[196:199], v194 offset:34816
	ds_read_b128 v[200:203], v194 offset:35840
	ds_read_b128 v[204:207], v194 offset:36864
	ds_read_b128 v[216:219], v194 offset:37888
	ds_read_b128 v[220:223], v194 offset:38912
	ds_read_b128 v[228:231], v194 offset:39936
	global_load_lds_dwordx4 v146, s[52:53]
	s_mov_b32 m0, s82
	s_nop 0
	global_load_lds_dwordx4 v150, s[52:53]
	s_waitcnt lgkmcnt(8)
	s_barrier
	s_waitcnt lgkmcnt(0)
	v_mfma_f32_16x16x32_bf16 v[124:127], v[128:131], v[162:165], v[124:127]
	v_mfma_f32_16x16x32_bf16 v[120:123], v[136:139], v[162:165], v[120:123]
	v_mfma_f32_16x16x32_bf16 v[116:119], v[128:131], v[196:199], v[116:119]
	v_mfma_f32_16x16x32_bf16 v[112:115], v[136:139], v[196:199], v[112:115]
	v_mfma_f32_16x16x32_bf16 v[108:111], v[128:131], v[204:207], v[108:111]
	v_mfma_f32_16x16x32_bf16 v[104:107], v[136:139], v[204:207], v[104:107]
	v_mfma_f32_16x16x32_bf16 v[100:103], v[128:131], v[220:223], v[100:103]
	v_mfma_f32_16x16x32_bf16 v[96:99], v[136:139], v[220:223], v[96:99]
	v_mfma_f32_16x16x32_bf16 v[124:127], v[132:135], v[166:169], v[124:127]
	v_mfma_f32_16x16x32_bf16 v[120:123], v[140:143], v[166:169], v[120:123]
	v_mfma_f32_16x16x32_bf16 v[116:119], v[132:135], v[200:203], v[116:119]
	v_mfma_f32_16x16x32_bf16 v[112:115], v[140:143], v[200:203], v[112:115]
	v_mfma_f32_16x16x32_bf16 v[108:111], v[132:135], v[216:219], v[108:111]
	v_mfma_f32_16x16x32_bf16 v[104:107], v[140:143], v[216:219], v[104:107]
	v_mfma_f32_16x16x32_bf16 v[100:103], v[132:135], v[228:231], v[100:103]
	v_mfma_f32_16x16x32_bf16 v[96:99], v[140:143], v[228:231], v[96:99]
	s_barrier
	s_add_i32 s37, 0, 0x1c000
	s_add_i32 s27, s27, s76
	v_add_u32_e32 v161, s37, v192
	s_add_u32 s56, s50, s18
	s_addc_u32 s57, s51, s19
	s_mov_b32 m0, s27
	ds_read_b128 v[232:235], v161
	ds_read_b128 v[236:239], v161 offset:1024
	ds_read_b128 v[240:243], v161 offset:2048
	ds_read_b128 v[244:247], v161 offset:3072
	global_load_lds_dwordx4 v148, s[56:57]
	s_add_u32 s56, s50, s18
	s_addc_u32 s57, s51, s19
	s_add_i32 m0, s27, 0x2000
	s_nop 0
	global_load_lds_dwordx4 v152, s[56:57]
	s_barrier
	s_waitcnt lgkmcnt(0)
	v_mfma_f32_16x16x32_bf16 v[92:95], v[232:235], v[162:165], v[92:95]
	v_mfma_f32_16x16x32_bf16 v[88:91], v[240:243], v[162:165], v[88:91]
	v_mfma_f32_16x16x32_bf16 v[84:87], v[232:235], v[196:199], v[84:87]
	v_mfma_f32_16x16x32_bf16 v[80:83], v[240:243], v[196:199], v[80:83]
	v_mfma_f32_16x16x32_bf16 v[76:79], v[232:235], v[204:207], v[76:79]
	v_mfma_f32_16x16x32_bf16 v[72:75], v[240:243], v[204:207], v[72:75]
	v_mfma_f32_16x16x32_bf16 v[68:71], v[232:235], v[220:223], v[68:71]
	v_mfma_f32_16x16x32_bf16 v[64:67], v[240:243], v[220:223], v[64:67]
	v_mfma_f32_16x16x32_bf16 v[92:95], v[236:239], v[166:169], v[92:95]
	v_mfma_f32_16x16x32_bf16 v[88:91], v[244:247], v[166:169], v[88:91]
	v_mfma_f32_16x16x32_bf16 v[84:87], v[236:239], v[200:203], v[84:87]
	v_mfma_f32_16x16x32_bf16 v[80:83], v[244:247], v[200:203], v[80:83]
	v_mfma_f32_16x16x32_bf16 v[76:79], v[236:239], v[216:219], v[76:79]
	v_mfma_f32_16x16x32_bf16 v[72:75], v[244:247], v[216:219], v[72:75]
	v_mfma_f32_16x16x32_bf16 v[68:71], v[236:239], v[228:231], v[68:71]
	v_mfma_f32_16x16x32_bf16 v[64:67], v[244:247], v[228:231], v[64:67]
	s_barrier
	s_mov_b32 m0, s80
	v_lshl_add_u64 v[176:177], v[224:225], 0, s[18:19]
	ds_read_b128 v[162:165], v194 offset:49152
	ds_read_b128 v[166:169], v194 offset:50176
	ds_read_b128 v[196:199], v194 offset:51200
	ds_read_b128 v[200:203], v194 offset:52224
	ds_read_b128 v[204:207], v194 offset:53248
	ds_read_b128 v[216:219], v194 offset:54272
	ds_read_b128 v[220:223], v194 offset:55296
	ds_read_b128 v[228:231], v194 offset:56320
	global_load_lds_dwordx4 v[176:177], off
	v_lshl_add_u64 v[176:177], v[248:249], 0, s[18:19]
	s_mov_b32 m0, s83
	s_nop 0
	global_load_lds_dwordx4 v[176:177], off
	s_barrier
	s_waitcnt lgkmcnt(0)
	v_mfma_f32_16x16x32_bf16 v[60:63], v[128:131], v[162:165], v[60:63]
	v_mfma_f32_16x16x32_bf16 v[56:59], v[136:139], v[162:165], v[56:59]
	v_mfma_f32_16x16x32_bf16 v[52:55], v[128:131], v[196:199], v[52:55]
	v_mfma_f32_16x16x32_bf16 v[48:51], v[136:139], v[196:199], v[48:51]
	v_mfma_f32_16x16x32_bf16 v[44:47], v[128:131], v[204:207], v[44:47]
	v_mfma_f32_16x16x32_bf16 v[40:43], v[136:139], v[204:207], v[40:43]
	v_mfma_f32_16x16x32_bf16 v[36:39], v[128:131], v[220:223], v[36:39]
	v_mfma_f32_16x16x32_bf16 v[32:35], v[136:139], v[220:223], v[32:35]
	v_mfma_f32_16x16x32_bf16 v[60:63], v[132:135], v[166:169], v[60:63]
	v_mfma_f32_16x16x32_bf16 v[56:59], v[140:143], v[166:169], v[56:59]
	v_mfma_f32_16x16x32_bf16 v[52:55], v[132:135], v[200:203], v[52:55]
	v_mfma_f32_16x16x32_bf16 v[48:51], v[140:143], v[200:203], v[48:51]
	v_mfma_f32_16x16x32_bf16 v[44:47], v[132:135], v[216:219], v[44:47]
	v_mfma_f32_16x16x32_bf16 v[40:43], v[140:143], v[216:219], v[40:43]
	v_mfma_f32_16x16x32_bf16 v[36:39], v[132:135], v[228:231], v[36:39]
	v_mfma_f32_16x16x32_bf16 v[32:35], v[140:143], v[228:231], v[32:35]
	s_barrier
	s_add_u32 s50, s50, 0x40080
	s_addc_u32 s51, s51, 0
	s_add_i32 s27, s37, s76
	s_mov_b32 m0, s27
	s_nop 0
	global_load_lds_dwordx4 v148, s[50:51]
	s_add_i32 m0, s27, 0x2000
	s_nop 0
	global_load_lds_dwordx4 v152, s[50:51]
	s_waitcnt vmcnt(6)
	s_barrier
	v_mfma_f32_16x16x32_bf16 v[28:31], v[232:235], v[162:165], v[28:31]
	v_mfma_f32_16x16x32_bf16 v[24:27], v[240:243], v[162:165], v[24:27]
	v_mfma_f32_16x16x32_bf16 v[20:23], v[232:235], v[196:199], v[20:23]
	v_mfma_f32_16x16x32_bf16 v[16:19], v[240:243], v[196:199], v[16:19]
	v_mfma_f32_16x16x32_bf16 v[12:15], v[232:235], v[204:207], v[12:15]
	v_mfma_f32_16x16x32_bf16 v[8:11], v[240:243], v[204:207], v[8:11]
	v_mfma_f32_16x16x32_bf16 v[4:7], v[232:235], v[220:223], v[4:7]
	v_mfma_f32_16x16x32_bf16 v[0:3], v[240:243], v[220:223], v[0:3]
	v_mfma_f32_16x16x32_bf16 v[28:31], v[236:239], v[166:169], v[28:31]
	v_mfma_f32_16x16x32_bf16 v[24:27], v[244:247], v[166:169], v[24:27]
	v_mfma_f32_16x16x32_bf16 v[20:23], v[236:239], v[200:203], v[20:23]
	v_mfma_f32_16x16x32_bf16 v[16:19], v[244:247], v[200:203], v[16:19]
	v_mfma_f32_16x16x32_bf16 v[12:15], v[236:239], v[216:219], v[12:15]
	v_mfma_f32_16x16x32_bf16 v[8:11], v[244:247], v[216:219], v[8:11]
	v_mfma_f32_16x16x32_bf16 v[4:7], v[236:239], v[228:231], v[4:7]
	v_mfma_f32_16x16x32_bf16 v[0:3], v[244:247], v[228:231], v[0:3]
	s_barrier
	s_add_i32 s36, s36, 2
	s_add_u32 s0, s0, 0x100
	s_addc_u32 s1, s1, 0
	s_add_u32 s34, s34, 0x100
	s_addc_u32 s35, s35, 0
	s_cmp_gt_u32 s36, 13
	s_cbranch_scc0 .LBB0_351
	s_lshl_b32 s0, s11, 8
	s_or_b32 s50, s0, s79
	s_ashr_i32 s51, s50, 31
	v_lshl_add_u64 v[140:141], s[50:51], 3, v[154:155]
	global_load_dwordx4 v[128:131], v[140:141], off offset:48
	global_load_dwordx4 v[132:135], v[140:141], off offset:32
	global_load_dwordx4 v[136:139], v[140:141], off offset:16
	global_load_dwordx4 v[162:165], v[140:141], off
	s_mov_b32 s34, 0x35800000
	s_mov_b32 s0, 0x358637bd
	v_mov_b64_e32 v[168:169], s[0:1]
	s_mov_b32 s30, 0x45800000
	s_cmp_lt_u32 s10, 2
	s_waitcnt vmcnt(0)
	v_ffbh_u32_e32 v142, v165
	v_min_u32_e32 v161, 32, v142
	v_lshlrev_b64 v[142:143], v161, v[164:165]
	v_min_u32_e32 v142, 1, v142
	v_or_b32_e32 v142, v143, v142
	v_cvt_f32_u32_e32 v142, v142
	v_sub_u32_e32 v143, 32, v161
	v_ldexp_f32 v143, v142, v143
	v_ffbh_u32_e32 v142, v163
	v_min_u32_e32 v142, 32, v142
	v_lshlrev_b64 v[162:163], v142, v[162:163]
	v_min_u32_e32 v161, 1, v162
	v_or_b32_e32 v161, v163, v161
	v_cvt_f32_u32_e32 v161, v161
	v_sub_u32_e32 v142, 32, v142
	v_ldexp_f32 v142, v161, v142
	v_pk_mul_f32 v[142:143], v[142:143], s[34:35] op_sel_hi:[1,0]
	s_nop 0
	v_pk_fma_f32 v[142:143], v[142:143], s[2:3], v[168:169] op_sel_hi:[1,0,0]
	s_nop 0
	v_mul_f32_e32 v161, 0x4b800000, v142
	v_cmp_gt_f32_e64 s[0:1], s89, v142
	v_cmp_gt_f32_e32 vcc, s89, v143
	s_nop 0
	v_cndmask_b32_e64 v142, v142, v161, s[0:1]
	v_mul_f32_e32 v161, 0x4b800000, v143
	v_cndmask_b32_e32 v143, v143, v161, vcc
	v_rsq_f32_e32 v142, v142
	v_rsq_f32_e32 v143, v143
	s_nop 0
	v_pk_mul_f32 v[162:163], v[142:143], s[30:31] op_sel_hi:[1,0]
	s_nop 0
	v_cndmask_b32_e64 v166, v142, v162, s[0:1]
	v_ffbh_u32_e32 v142, v139
	v_min_u32_e32 v142, 32, v142
	v_lshlrev_b64 v[138:139], v142, v[138:139]
	v_min_u32_e32 v138, 1, v138
	v_or_b32_e32 v138, v139, v138
	v_cvt_f32_u32_e32 v138, v138
	v_sub_u32_e32 v139, 32, v142
	v_cndmask_b32_e32 v167, v143, v163, vcc
	v_pk_mul_f32 v[60:61], v[60:61], v[166:167]
	v_ldexp_f32 v139, v138, v139
	v_ffbh_u32_e32 v138, v137
	v_min_u32_e32 v138, 32, v138
	v_lshlrev_b64 v[136:137], v138, v[136:137]
	v_min_u32_e32 v136, 1, v136
	v_or_b32_e32 v136, v137, v136
	v_cvt_f32_u32_e32 v136, v136
	v_sub_u32_e32 v137, 32, v138
	v_pk_mul_f32 v[52:53], v[52:53], v[166:167]
	v_pk_mul_f32 v[44:45], v[44:45], v[166:167]
	v_ldexp_f32 v138, v136, v137
	v_pk_mul_f32 v[136:137], v[138:139], s[34:35] op_sel_hi:[1,0]
	v_pk_mul_f32 v[36:37], v[36:37], v[166:167]
	v_pk_fma_f32 v[136:137], v[136:137], s[2:3], v[168:169] op_sel_hi:[1,0,0]
	s_nop 0
	v_mul_f32_e32 v138, 0x4b800000, v136
	v_cmp_gt_f32_e64 s[0:1], s89, v136
	v_cmp_gt_f32_e32 vcc, s89, v137
	s_nop 0
	v_cndmask_b32_e64 v136, v136, v138, s[0:1]
	v_mul_f32_e32 v138, 0x4b800000, v137
	v_cndmask_b32_e32 v137, v137, v138, vcc
	v_rsq_f32_e32 v136, v136
	v_rsq_f32_e32 v137, v137
	s_nop 0
	v_pk_mul_f32 v[138:139], v[136:137], s[30:31] op_sel_hi:[1,0]
	s_nop 0
	v_cndmask_b32_e64 v162, v136, v138, s[0:1]
	v_ffbh_u32_e32 v136, v135
	v_min_u32_e32 v136, 32, v136
	v_lshlrev_b64 v[134:135], v136, v[134:135]
	v_min_u32_e32 v134, 1, v134
	v_or_b32_e32 v134, v135, v134
	v_cvt_f32_u32_e32 v134, v134
	v_sub_u32_e32 v135, 32, v136
	v_cndmask_b32_e32 v163, v137, v139, vcc
	v_ldexp_f32 v135, v134, v135
	v_ffbh_u32_e32 v134, v133
	v_min_u32_e32 v134, 32, v134
	v_lshlrev_b64 v[132:133], v134, v[132:133]
	v_min_u32_e32 v132, 1, v132
	v_or_b32_e32 v132, v133, v132
	v_cvt_f32_u32_e32 v132, v132
	v_sub_u32_e32 v133, 32, v134
	v_ldexp_f32 v134, v132, v133
	v_pk_mul_f32 v[132:133], v[134:135], s[34:35] op_sel_hi:[1,0]
	s_nop 0
	v_pk_fma_f32 v[132:133], v[132:133], s[2:3], v[168:169] op_sel_hi:[1,0,0]
	s_nop 0
	v_mul_f32_e32 v134, 0x4b800000, v132
	v_cmp_gt_f32_e64 s[0:1], s89, v132
	v_cmp_gt_f32_e32 vcc, s89, v133
	s_nop 0
	v_cndmask_b32_e64 v132, v132, v134, s[0:1]
	v_mul_f32_e32 v134, 0x4b800000, v133
	v_cndmask_b32_e32 v133, v133, v134, vcc
	v_rsq_f32_e32 v132, v132
	v_rsq_f32_e32 v133, v133
	s_nop 0
	v_pk_mul_f32 v[134:135], v[132:133], s[30:31] op_sel_hi:[1,0]
	s_nop 0
	v_cndmask_b32_e64 v188, v132, v134, s[0:1]
	v_ffbh_u32_e32 v132, v131
	v_min_u32_e32 v132, 32, v132
	v_lshlrev_b64 v[130:131], v132, v[130:131]
	v_min_u32_e32 v130, 1, v130
	v_or_b32_e32 v130, v131, v130
	v_cvt_f32_u32_e32 v130, v130
	v_sub_u32_e32 v131, 32, v132
	v_cndmask_b32_e32 v189, v133, v135, vcc
	v_pk_mul_f32 v[56:57], v[56:57], v[188:189]
	v_ldexp_f32 v131, v130, v131
	v_ffbh_u32_e32 v130, v129
	v_min_u32_e32 v130, 32, v130
	v_lshlrev_b64 v[128:129], v130, v[128:129]
	v_min_u32_e32 v128, 1, v128
	v_or_b32_e32 v128, v129, v128
	v_cvt_f32_u32_e32 v128, v128
	v_sub_u32_e32 v129, 32, v130
	v_pk_mul_f32 v[48:49], v[48:49], v[188:189]
	v_pk_mul_f32 v[40:41], v[40:41], v[188:189]
	v_ldexp_f32 v130, v128, v129
	v_pk_mul_f32 v[128:129], v[130:131], s[34:35] op_sel_hi:[1,0]
	v_pk_mul_f32 v[32:33], v[32:33], v[188:189]
	v_pk_fma_f32 v[128:129], v[128:129], s[2:3], v[168:169] op_sel_hi:[1,0,0]
	s_nop 0
	v_mul_f32_e32 v130, 0x4b800000, v128
	v_cmp_gt_f32_e64 s[0:1], s89, v128
	v_cmp_gt_f32_e32 vcc, s89, v129
	s_nop 0
	v_cndmask_b32_e64 v128, v128, v130, s[0:1]
	v_mul_f32_e32 v130, 0x4b800000, v129
	v_cndmask_b32_e32 v129, v129, v130, vcc
	v_rsq_f32_e32 v128, v128
	v_rsq_f32_e32 v129, v129
	s_nop 0
	v_pk_mul_f32 v[130:131], v[128:129], s[30:31] op_sel_hi:[1,0]
	s_nop 0
	v_cndmask_b32_e32 v165, v129, v131, vcc
	v_cndmask_b32_e64 v164, v128, v130, s[0:1]
	global_load_dwordx4 v[128:131], v[140:141], off offset:1072
	global_load_dwordx4 v[132:135], v[140:141], off offset:1056
	global_load_dwordx4 v[136:139], v[140:141], off offset:1040
	s_nop 0
	global_load_dwordx4 v[140:143], v[140:141], off offset:1024
	s_waitcnt vmcnt(0)
	v_ffbh_u32_e32 v161, v143
	v_min_u32_e32 v161, 32, v161
	v_lshlrev_b64 v[142:143], v161, v[142:143]
	v_min_u32_e32 v142, 1, v142
	v_or_b32_e32 v142, v143, v142
	v_cvt_f32_u32_e32 v142, v142
	v_sub_u32_e32 v143, 32, v161
	v_ldexp_f32 v143, v142, v143
	v_ffbh_u32_e32 v142, v141
	v_min_u32_e32 v142, 32, v142
	v_lshlrev_b64 v[140:141], v142, v[140:141]
	v_min_u32_e32 v140, 1, v140
	v_or_b32_e32 v140, v141, v140
	v_cvt_f32_u32_e32 v140, v140
	v_sub_u32_e32 v141, 32, v142
	v_ldexp_f32 v142, v140, v141
	v_pk_mul_f32 v[140:141], v[142:143], s[34:35] op_sel_hi:[1,0]
	s_nop 0
	v_pk_fma_f32 v[140:141], v[140:141], s[2:3], v[168:169] op_sel_hi:[1,0,0]
	s_nop 0
	v_mul_f32_e32 v142, 0x4b800000, v140
	v_cmp_gt_f32_e64 s[0:1], s89, v140
	v_cmp_gt_f32_e32 vcc, s89, v141
	s_nop 0
	v_cndmask_b32_e64 v140, v140, v142, s[0:1]
	v_mul_f32_e32 v142, 0x4b800000, v141
	v_cndmask_b32_e32 v141, v141, v142, vcc
	v_rsq_f32_e32 v140, v140
	v_rsq_f32_e32 v141, v141
	s_nop 0
	v_pk_mul_f32 v[142:143], v[140:141], s[30:31] op_sel_hi:[1,0]
	s_nop 0
	v_cndmask_b32_e64 v142, v140, v142, s[0:1]
	v_ffbh_u32_e32 v140, v139
	v_min_u32_e32 v140, 32, v140
	v_lshlrev_b64 v[138:139], v140, v[138:139]
	v_min_u32_e32 v138, 1, v138
	v_or_b32_e32 v138, v139, v138
	v_cvt_f32_u32_e32 v138, v138
	v_sub_u32_e32 v139, 32, v140
	v_cndmask_b32_e32 v143, v141, v143, vcc
	v_pk_mul_f32 v[140:141], v[124:125], v[166:167]
	v_ldexp_f32 v139, v138, v139
	v_ffbh_u32_e32 v138, v137
	v_min_u32_e32 v138, 32, v138
	v_lshlrev_b64 v[136:137], v138, v[136:137]
	v_min_u32_e32 v136, 1, v136
	v_or_b32_e32 v136, v137, v136
	v_cvt_f32_u32_e32 v136, v136
	v_sub_u32_e32 v137, 32, v138
	v_pk_mul_f32 v[28:29], v[28:29], v[142:143]
	v_pk_mul_f32 v[20:21], v[20:21], v[142:143]
	v_ldexp_f32 v138, v136, v137
	v_pk_mul_f32 v[136:137], v[138:139], s[34:35] op_sel_hi:[1,0]
	v_pk_mul_f32 v[12:13], v[12:13], v[142:143]
	v_pk_fma_f32 v[136:137], v[136:137], s[2:3], v[168:169] op_sel_hi:[1,0,0]
	v_pk_mul_f32 v[4:5], v[4:5], v[142:143]
	v_mul_f32_e32 v138, 0x4b800000, v136
	v_cmp_gt_f32_e64 s[0:1], s89, v136
	v_cmp_gt_f32_e32 vcc, s89, v137
	s_nop 0
	v_cndmask_b32_e64 v136, v136, v138, s[0:1]
	v_mul_f32_e32 v138, 0x4b800000, v137
	v_cndmask_b32_e32 v137, v137, v138, vcc
	v_rsq_f32_e32 v136, v136
	v_rsq_f32_e32 v137, v137
	s_nop 0
	v_pk_mul_f32 v[138:139], v[136:137], s[30:31] op_sel_hi:[1,0]
	s_nop 0
	v_cndmask_b32_e64 v136, v136, v138, s[0:1]
	v_ffbh_u32_e32 v138, v135
	v_min_u32_e32 v138, 32, v138
	v_lshlrev_b64 v[134:135], v138, v[134:135]
	v_min_u32_e32 v134, 1, v134
	v_or_b32_e32 v134, v135, v134
	v_cvt_f32_u32_e32 v134, v134
	v_sub_u32_e32 v135, 32, v138
	v_cndmask_b32_e32 v137, v137, v139, vcc
	v_pk_mul_f32 v[138:139], v[120:121], v[188:189]
	v_ldexp_f32 v135, v134, v135
	v_ffbh_u32_e32 v134, v133
	v_min_u32_e32 v134, 32, v134
	v_lshlrev_b64 v[132:133], v134, v[132:133]
	v_min_u32_e32 v132, 1, v132
	v_or_b32_e32 v132, v133, v132
	v_cvt_f32_u32_e32 v132, v132
	v_sub_u32_e32 v133, 32, v134
	v_pk_mul_f32 v[120:121], v[84:85], v[142:143]
	v_ldexp_f32 v134, v132, v133
	v_pk_mul_f32 v[132:133], v[134:135], s[34:35] op_sel_hi:[1,0]
	s_nop 0
	v_pk_fma_f32 v[132:133], v[132:133], s[2:3], v[168:169] op_sel_hi:[1,0,0]
	s_nop 0
	v_mul_f32_e32 v134, 0x4b800000, v132
	v_cmp_gt_f32_e64 s[0:1], s89, v132
	v_cmp_gt_f32_e32 vcc, s89, v133
	s_nop 0
	v_cndmask_b32_e64 v132, v132, v134, s[0:1]
	v_mul_f32_e32 v134, 0x4b800000, v133
	v_cndmask_b32_e32 v133, v133, v134, vcc
	v_rsq_f32_e32 v132, v132
	v_rsq_f32_e32 v133, v133
	s_nop 0
	v_pk_mul_f32 v[134:135], v[132:133], s[30:31] op_sel_hi:[1,0]
	s_nop 0
	v_cndmask_b32_e64 v176, v132, v134, s[0:1]
	v_ffbh_u32_e32 v132, v131
	v_min_u32_e32 v132, 32, v132
	v_lshlrev_b64 v[130:131], v132, v[130:131]
	v_min_u32_e32 v130, 1, v130
	v_or_b32_e32 v130, v131, v130
	v_cvt_f32_u32_e32 v130, v130
	v_sub_u32_e32 v131, 32, v132
	v_cndmask_b32_e32 v177, v133, v135, vcc
	v_pk_mul_f32 v[124:125], v[88:89], v[176:177]
	v_ldexp_f32 v131, v130, v131
	v_ffbh_u32_e32 v130, v129
	v_min_u32_e32 v130, 32, v130
	v_lshlrev_b64 v[128:129], v130, v[128:129]
	v_min_u32_e32 v128, 1, v128
	v_or_b32_e32 v128, v129, v128
	v_cvt_f32_u32_e32 v128, v128
	v_sub_u32_e32 v129, 32, v130
	v_pk_mul_f32 v[134:135], v[116:117], v[166:167]
	v_pk_mul_f32 v[132:133], v[112:113], v[188:189]
	v_ldexp_f32 v130, v128, v129
	v_pk_mul_f32 v[128:129], v[130:131], s[34:35] op_sel_hi:[1,0]
	v_pk_mul_f32 v[116:117], v[80:81], v[176:177]
	v_pk_fma_f32 v[128:129], v[128:129], s[2:3], v[168:169] op_sel_hi:[1,0,0]
	v_pk_mul_f32 v[88:89], v[104:105], v[188:189]
	v_mul_f32_e32 v130, 0x4b800000, v128
	v_cmp_gt_f32_e64 s[0:1], s89, v128
	v_cmp_gt_f32_e32 vcc, s89, v129
	v_pk_mul_f32 v[112:113], v[76:77], v[142:143]
	v_cndmask_b32_e64 v128, v128, v130, s[0:1]
	v_mul_f32_e32 v130, 0x4b800000, v129
	v_cndmask_b32_e32 v129, v129, v130, vcc
	v_rsq_f32_e32 v128, v128
	v_rsq_f32_e32 v129, v129
	v_pk_mul_f32 v[76:77], v[100:101], v[166:167]
	v_pk_mul_f32 v[104:105], v[68:69], v[142:143]
	v_pk_mul_f32 v[24:25], v[24:25], v[176:177]
	v_pk_mul_f32 v[130:131], v[128:129], s[30:31] op_sel_hi:[1,0]
	v_pk_mul_f32 v[16:17], v[16:17], v[176:177]
	v_cndmask_b32_e32 v129, v129, v131, vcc
	v_cndmask_b32_e64 v128, v128, v130, s[0:1]
	s_mov_b64 s[0:1], -1
	v_pk_mul_f32 v[130:131], v[92:93], v[142:143]
	v_pk_mul_f32 v[92:93], v[108:109], v[166:167]
	v_pk_mul_f32 v[108:109], v[72:73], v[176:177]
	v_pk_mul_f32 v[72:73], v[96:97], v[188:189]
	v_pk_mul_f32 v[96:97], v[64:65], v[176:177]
	v_pk_mul_f32 v[8:9], v[8:9], v[176:177]
	v_pk_mul_f32 v[0:1], v[0:1], v[176:177]
	s_cbranch_scc1 .LBB0_354
	v_lshl_add_u32 v68, s10, 8, v193
	v_ashrrev_i32_e32 v69, 31, v68
	v_pk_mul_f32 v[64:65], v[126:127], v[162:163]
	v_cvt_pk_bf16_f32 v80, v140, v141
	s_lshl_b64 s[0:1], s[50:51], 1
	v_cvt_pk_bf16_f32 v81, v64, v65
	v_lshlrev_b64 v[64:65], 13, v[68:69]
	v_lshl_add_u64 v[64:65], s[44:45], 0, v[64:65]
	v_lshl_add_u64 v[64:65], v[64:65], 0, s[0:1]
	v_lshl_add_u64 v[64:65], v[64:65], 0, v[144:145]
	v_mov_b32_e32 v161, v145
	v_lshl_add_u64 v[64:65], v[64:65], 0, v[160:161]
	global_store_dwordx2 v[64:65], v[80:81], off
	v_pk_mul_f32 v[80:81], v[122:123], v[164:165]
	v_cvt_pk_bf16_f32 v84, v138, v139
	s_nop 0
	v_cvt_pk_bf16_f32 v85, v80, v81
	v_pk_mul_f32 v[80:81], v[94:95], v[136:137]
	global_store_dwordx2 v[64:65], v[84:85], off offset:16
	v_cvt_pk_bf16_f32 v84, v130, v131
	v_cvt_pk_bf16_f32 v85, v80, v81
	v_pk_mul_f32 v[80:81], v[90:91], v[128:129]
	global_store_dwordx2 v[64:65], v[84:85], off offset:256
	v_cvt_pk_bf16_f32 v84, v124, v125
	v_cvt_pk_bf16_f32 v85, v80, v81
	v_or_b32_e32 v80, 16, v68
	v_ashrrev_i32_e32 v81, 31, v80
	v_lshlrev_b64 v[80:81], 13, v[80:81]
	v_lshl_add_u64 v[80:81], s[44:45], 0, v[80:81]
	v_lshl_add_u64 v[80:81], v[80:81], 0, s[0:1]
	v_lshl_add_u64 v[80:81], v[80:81], 0, v[144:145]
	global_store_dwordx2 v[64:65], v[84:85], off offset:272
	v_pk_mul_f32 v[84:85], v[118:119], v[162:163]
	v_cvt_pk_bf16_f32 v100, v134, v135
	v_lshl_add_u64 v[80:81], v[80:81], 0, v[160:161]
	v_cvt_pk_bf16_f32 v101, v84, v85
	global_store_dwordx2 v[80:81], v[100:101], off
	v_pk_mul_f32 v[84:85], v[114:115], v[164:165]
	v_cvt_pk_bf16_f32 v100, v132, v133
	s_nop 0
	v_cvt_pk_bf16_f32 v101, v84, v85
	global_store_dwordx2 v[80:81], v[100:101], off offset:16
	v_pk_mul_f32 v[84:85], v[86:87], v[136:137]
	v_cvt_pk_bf16_f32 v100, v120, v121
	s_nop 0
	v_cvt_pk_bf16_f32 v101, v84, v85
	global_store_dwordx2 v[80:81], v[100:101], off offset:256
	v_pk_mul_f32 v[84:85], v[82:83], v[128:129]
	v_cvt_pk_bf16_f32 v100, v116, v117
	s_nop 0
	v_cvt_pk_bf16_f32 v101, v84, v85
	global_store_dwordx2 v[80:81], v[100:101], off offset:272
	v_or_b32_e32 v80, 32, v68
	v_ashrrev_i32_e32 v81, 31, v80
	v_lshlrev_b64 v[80:81], 13, v[80:81]
	v_lshl_add_u64 v[80:81], s[44:45], 0, v[80:81]
	v_or_b32_e32 v68, 48, v68
	v_lshl_add_u64 v[80:81], v[80:81], 0, s[0:1]
	v_ashrrev_i32_e32 v69, 31, v68
	v_pk_mul_f32 v[84:85], v[110:111], v[162:163]
	v_lshl_add_u64 v[80:81], v[80:81], 0, v[144:145]
	v_lshlrev_b64 v[68:69], 13, v[68:69]
	v_cvt_pk_bf16_f32 v100, v92, v93
	v_cvt_pk_bf16_f32 v101, v84, v85
	v_lshl_add_u64 v[80:81], v[80:81], 0, v[160:161]
	v_pk_mul_f32 v[84:85], v[106:107], v[164:165]
	v_lshl_add_u64 v[68:69], s[44:45], 0, v[68:69]
	global_store_dwordx2 v[80:81], v[100:101], off
	v_cvt_pk_bf16_f32 v100, v88, v89
	v_cvt_pk_bf16_f32 v101, v84, v85
	v_pk_mul_f32 v[84:85], v[78:79], v[136:137]
	v_lshl_add_u64 v[68:69], v[68:69], 0, s[0:1]
	global_store_dwordx2 v[80:81], v[100:101], off offset:16
	v_cvt_pk_bf16_f32 v100, v112, v113
	v_cvt_pk_bf16_f32 v101, v84, v85
	v_pk_mul_f32 v[84:85], v[74:75], v[128:129]
	v_lshl_add_u64 v[68:69], v[68:69], 0, v[144:145]
	global_store_dwordx2 v[80:81], v[100:101], off offset:256
	v_cvt_pk_bf16_f32 v100, v108, v109
	v_cvt_pk_bf16_f32 v101, v84, v85
	global_store_dwordx2 v[80:81], v[100:101], off offset:272
	v_cvt_pk_bf16_f32 v84, v76, v77
	v_lshl_add_u64 v[68:69], v[68:69], 0, v[160:161]
	v_pk_mul_f32 v[80:81], v[102:103], v[162:163]
	s_mov_b64 s[0:1], 0x100000
	v_cvt_pk_bf16_f32 v85, v80, v81
	global_store_dwordx2 v[68:69], v[84:85], off
	v_cvt_pk_bf16_f32 v84, v72, v73
	v_pk_mul_f32 v[80:81], v[98:99], v[164:165]
	s_nop 0
	v_cvt_pk_bf16_f32 v85, v80, v81
	global_store_dwordx2 v[68:69], v[84:85], off offset:16
	v_cvt_pk_bf16_f32 v84, v104, v105
	v_pk_mul_f32 v[80:81], v[70:71], v[136:137]
	s_nop 0
	v_cvt_pk_bf16_f32 v85, v80, v81
	global_store_dwordx2 v[68:69], v[84:85], off offset:256
	v_cvt_pk_bf16_f32 v84, v96, v97
	v_pk_mul_f32 v[80:81], v[66:67], v[128:129]
	s_nop 0
	v_cvt_pk_bf16_f32 v85, v80, v81
	global_store_dwordx2 v[68:69], v[84:85], off offset:272
	v_add_co_u32_e32 v84, vcc, s29, v64
	v_pk_mul_f32 v[68:69], v[62:63], v[162:163]
	s_nop 0
	v_addc_co_u32_e32 v85, vcc, 0, v65, vcc
	v_cvt_pk_bf16_f32 v80, v60, v61
	v_cvt_pk_bf16_f32 v81, v68, v69
	v_lshl_add_u64 v[68:69], v[64:65], 0, s[0:1]
	global_store_dwordx2 v[84:85], v[80:81], off
	v_cvt_pk_bf16_f32 v84, v56, v57
	v_pk_mul_f32 v[80:81], v[58:59], v[164:165]
	s_mov_b64 s[0:1], 0x120000
	v_cvt_pk_bf16_f32 v85, v80, v81
	global_store_dwordx2 v[68:69], v[84:85], off offset:16
	v_cvt_pk_bf16_f32 v84, v28, v29
	v_pk_mul_f32 v[80:81], v[30:31], v[136:137]
	s_nop 0
	v_cvt_pk_bf16_f32 v85, v80, v81
	global_store_dwordx2 v[68:69], v[84:85], off offset:256
	v_cvt_pk_bf16_f32 v84, v24, v25
	v_pk_mul_f32 v[80:81], v[26:27], v[128:129]
	s_nop 0
	v_cvt_pk_bf16_f32 v85, v80, v81
	global_store_dwordx2 v[68:69], v[84:85], off offset:272
	v_add_co_u32_e32 v84, vcc, s49, v64
	v_pk_mul_f32 v[68:69], v[54:55], v[162:163]
	v_cvt_pk_bf16_f32 v80, v52, v53
	s_nop 0
	v_addc_co_u32_e32 v85, vcc, 0, v65, vcc
	v_cvt_pk_bf16_f32 v81, v68, v69
	v_lshl_add_u64 v[68:69], v[64:65], 0, s[0:1]
	global_store_dwordx2 v[84:85], v[80:81], off
	v_pk_mul_f32 v[80:81], v[50:51], v[164:165]
	v_cvt_pk_bf16_f32 v84, v48, v49
	s_mov_b64 s[0:1], 0x140000
	v_cvt_pk_bf16_f32 v85, v80, v81
	global_store_dwordx2 v[68:69], v[84:85], off offset:16
	v_pk_mul_f32 v[80:81], v[22:23], v[136:137]
	v_cvt_pk_bf16_f32 v84, v20, v21
	s_nop 0
	v_cvt_pk_bf16_f32 v85, v80, v81
	global_store_dwordx2 v[68:69], v[84:85], off offset:256
	v_pk_mul_f32 v[80:81], v[18:19], v[128:129]
	v_cvt_pk_bf16_f32 v84, v16, v17
	s_nop 0
	v_cvt_pk_bf16_f32 v85, v80, v81
	global_store_dwordx2 v[68:69], v[84:85], off offset:272
	v_pk_mul_f32 v[68:69], v[46:47], v[162:163]
	v_cvt_pk_bf16_f32 v80, v44, v45
	s_nop 0
	v_cvt_pk_bf16_f32 v81, v68, v69
	v_lshl_add_u64 v[68:69], v[64:65], 0, s[0:1]
	s_mov_b32 s0, 0x140000
	v_add_co_u32_e32 v84, vcc, s0, v64
	s_mov_b64 s[0:1], 0x160000
	s_nop 0
	v_addc_co_u32_e32 v85, vcc, 0, v65, vcc
	global_store_dwordx2 v[84:85], v[80:81], off
	v_pk_mul_f32 v[80:81], v[42:43], v[164:165]
	v_cvt_pk_bf16_f32 v84, v40, v41
	s_nop 0
	v_cvt_pk_bf16_f32 v85, v80, v81
	global_store_dwordx2 v[68:69], v[84:85], off offset:16
	v_pk_mul_f32 v[80:81], v[14:15], v[136:137]
	v_cvt_pk_bf16_f32 v84, v12, v13
	s_nop 0
	v_cvt_pk_bf16_f32 v85, v80, v81
	global_store_dwordx2 v[68:69], v[84:85], off offset:256
	v_pk_mul_f32 v[80:81], v[10:11], v[128:129]
	v_cvt_pk_bf16_f32 v84, v8, v9
	s_nop 0
	v_cvt_pk_bf16_f32 v85, v80, v81
	global_store_dwordx2 v[68:69], v[84:85], off offset:272
	v_pk_mul_f32 v[68:69], v[38:39], v[162:163]
	v_cvt_pk_bf16_f32 v80, v36, v37
	s_nop 0
	v_cvt_pk_bf16_f32 v81, v68, v69
	v_lshl_add_u64 v[68:69], v[64:65], 0, s[0:1]
	s_mov_b32 s0, 0x160000
	v_add_co_u32_e32 v64, vcc, s0, v64
	s_mov_b64 s[0:1], 0
	s_nop 0
	v_addc_co_u32_e32 v65, vcc, 0, v65, vcc
	global_store_dwordx2 v[64:65], v[80:81], off
	v_pk_mul_f32 v[64:65], v[34:35], v[164:165]
	v_cvt_pk_bf16_f32 v80, v32, v33
	s_nop 0
	v_cvt_pk_bf16_f32 v81, v64, v65
	global_store_dwordx2 v[68:69], v[80:81], off offset:16
	v_pk_mul_f32 v[64:65], v[6:7], v[136:137]
	v_cvt_pk_bf16_f32 v80, v4, v5
	s_nop 0
	v_cvt_pk_bf16_f32 v81, v64, v65
	global_store_dwordx2 v[68:69], v[80:81], off offset:256
	v_pk_mul_f32 v[64:65], v[2:3], v[128:129]
	v_cvt_pk_bf16_f32 v80, v0, v1
	s_nop 0
	v_cvt_pk_bf16_f32 v81, v64, v65
	s_nop 1
	global_store_dwordx2 v[68:69], v[80:81], off offset:272
